# row-statistic butterflies in 8 GEMM epilogues: ds_bpermute + lgkmcnt wait replaced by copy + v_permlane16/32_swap (no LDS round trip)
# speedup vs baseline: 1.0114x; 1.0079x over previous
; #define EPI_IT_ROW(it) EPI_ROW((it) >> 2, (it) & 3)
; #define EPI_PACK8(v0, v1) (u32x4){pk2((v0)[0], (v0)[1]), pk2((v0)[2], (v0)[3]), pk2((v1)[0], (v1)[1]), pk2((v1)[2], (v1)[3])}
;     __device__ __forceinline__ void operator()(AccRef acc, const Unit& u, int wr, int wc, int fr, int fq) const {
;         asm volatile("" : "+v"(fr), "+v"(fq));
;         f32x4 xc[2][2], xn[2][2];
; #pragma unroll
;         for (int bj = 0; bj < 2; ++bj) { const size_t p = (size_t)EPI_IT_ROW(0) * DM + EPI_COL(bj); xc[bj][0] = *(const f32x4*)(xin + p); xc[bj][1] = *(const f32x4*)(xin + p + 4); }
; #pragma unroll
;         for (int it = 0; it < 8; ++it) { const int ai = it >> 2, m = it & 3, row = EPI_IT_ROW(it);
;             if (it + 1 < 8) {
; #pragma unroll
;                 for (int bj = 0; bj < 2; ++bj) { const size_t p = (size_t)EPI_IT_ROW(it + 1) * DM + EPI_COL(bj); xn[bj][0] = *(const f32x4*)(xin + p); xn[bj][1] = *(const f32x4*)(xin + p + 4); } }
;             float q = 0.f;
; #pragma unroll
;             for (int bj = 0; bj < 2; ++bj) { const size_t p = (size_t)row * DM + EPI_COL(bj);
;                 const f32x4 x0 = xc[bj][0] + acc[ai][bj][m][0], x1 = xc[bj][1] + acc[ai][bj][m][1];
;                 __builtin_nontemporal_store(x0, (f32x4*)(xout + p)); __builtin_nontemporal_store(x1, (f32x4*)(xout + p + 4));
;                 *(u32x4*)(xb + p) = EPI_PACK8(x0, x1);
;                 q += EPI_SQ8(x0, x1); }
;             q += __shfl_xor(q, 16); q += __shfl_xor(q, 32);
;             if (fq == 0) atomicAdd(ssout + row, q);
; #pragma unroll
;             for (int bj = 0; bj < 2; ++bj) { xc[bj][0] = xn[bj][0]; xc[bj][1] = xn[bj][1]; } }
;     }
.LBB0_460:
	s_lshl_b32 s1, s34, 8
	v_mov_b32_e32 v128, v171
	v_mov_b32_e32 v168, v170
	s_add_i32 s1, s1, s63
	s_lshl_b32 s0, s0, 8
	s_or_b32 s0, s0, s64
	v_add_u32_e32 v164, s1, v128
	v_ashrrev_i32_e32 v165, 31, v164
	v_lshl_add_u32 v162, v168, 3, s0
	v_lshlrev_b64 v[128:129], 12, v[164:165]
	v_ashrrev_i32_e32 v163, 31, v162
	v_lshl_add_u64 v[128:129], s[16:17], 0, v[128:129]
	v_lshlrev_b64 v[130:131], 2, v[162:163]
	v_add_u32_e32 v160, 0x80, v162
	v_lshl_add_u64 v[132:133], v[128:129], 0, v[130:131]
	v_ashrrev_i32_e32 v161, 31, v160
	global_load_dwordx4 v[180:183], v[132:133], off offset:16
	global_load_dwordx4 v[184:187], v[132:133], off
	v_lshlrev_b64 v[132:133], 2, v[160:161]
	v_lshl_add_u64 v[128:129], v[128:129], 0, v[132:133]
	global_load_dwordx4 v[188:191], v[128:129], off
	global_load_dwordx4 v[192:195], v[128:129], off offset:16
	v_add_u32_e32 v166, 16, v164
	v_ashrrev_i32_e32 v167, 31, v166
	v_lshlrev_b64 v[128:129], 12, v[166:167]
	v_lshl_add_u64 v[128:129], s[16:17], 0, v[128:129]
	v_lshl_add_u64 v[130:131], v[128:129], 0, v[130:131]
	v_lshl_add_u64 v[132:133], v[128:129], 0, v[132:133]
	global_load_dwordx4 v[136:139], v[130:131], off offset:16
	global_load_dwordx4 v[140:143], v[130:131], off
	s_nop 0
	global_load_dwordx4 v[128:131], v[132:133], off offset:16
	s_nop 0
	global_load_dwordx4 v[132:135], v[132:133], off
	v_and_b32_e32 v178, 64, v177
	v_xor_b32_e32 v169, 16, v177
	v_add_u32_e32 v178, 64, v178
	v_cmp_lt_i32_e64 s[0:1], v169, v178
	v_xor_b32_e32 v179, 32, v177
	v_cmp_eq_u32_e32 vcc, 0, v168
	v_cndmask_b32_e64 v168, v177, v169, s[0:1]
	v_cmp_lt_i32_e64 s[0:1], v179, v178
	v_lshlrev_b32_e32 v178, 2, v168
	v_lshlrev_b64 v[168:169], 10, v[164:165]
	v_lshl_add_u64 v[196:197], v[168:169], 0, v[162:163]
	v_lshl_add_u64 v[198:199], v[196:197], 2, s[48:49]
	v_cndmask_b32_e64 v179, v177, v179, s[0:1]
	v_lshl_add_u64 v[168:169], v[168:169], 0, v[160:161]
	v_lshl_add_u64 v[196:197], v[196:197], 1, s[24:25]
	v_lshl_add_u64 v[200:201], v[168:169], 2, s[48:49]
	v_lshlrev_b32_e32 v179, 2, v179
	s_waitcnt vmcnt(0)
	v_pk_add_f32 v[122:123], v[122:123], v[182:183]
	v_pk_add_f32 v[126:127], v[126:127], v[186:187]
	v_pk_add_f32 v[124:125], v[124:125], v[184:185]
	v_pk_add_f32 v[118:119], v[118:119], v[190:191]
	v_pk_add_f32 v[116:117], v[116:117], v[188:189]
	v_pk_add_f32 v[120:121], v[120:121], v[180:181]
	v_pk_add_f32 v[180:181], v[112:113], v[192:193]
	global_store_dwordx4 v[198:199], v[124:127], off nt
	global_store_dwordx4 v[198:199], v[120:123], off offset:16 nt
	v_cvt_pk_bf16_f32 v112, v124, v125
	v_cvt_pk_bf16_f32 v113, v126, v127
	v_mul_f32_e32 v185, v117, v117
	v_mul_f32_e32 v125, v125, v125
	v_mul_f32_e32 v127, v127, v127
	v_mul_f32_e32 v186, v119, v119
	v_pk_add_f32 v[182:183], v[114:115], v[194:195]
	v_cvt_pk_bf16_f32 v114, v120, v121
	v_cvt_pk_bf16_f32 v115, v122, v123
	v_mul_f32_e32 v121, v121, v121
	v_mul_f32_e32 v123, v123, v123
	v_mul_f32_e32 v187, v181, v181
	v_fmac_f32_e32 v125, v124, v124
	v_fmac_f32_e32 v127, v126, v126
	v_fmac_f32_e32 v185, v116, v116
	v_fmac_f32_e32 v186, v118, v118
	v_mul_f32_e32 v188, v183, v183
	v_fmac_f32_e32 v121, v120, v120
	v_fmac_f32_e32 v123, v122, v122
	v_fmac_f32_e32 v187, v180, v180
	v_add_f32_e32 v120, v125, v127
	v_add_f32_e32 v122, v185, v186
	v_fmac_f32_e32 v188, v182, v182
	v_add_f32_e32 v120, v120, v121
	v_add_f32_e32 v121, v122, v187
	v_add_f32_e32 v120, v123, v120
	v_add_f32_e32 v121, v188, v121
	v_add_f32_e32 v120, v120, v121
	v_mov_b32_e32 v121, v120
	s_nop 1
	v_permlane16_swap_b32_e32 v121, v120
	global_store_dwordx4 v[196:197], v[112:115], off
	global_store_dwordx4 v[200:201], v[116:119], off nt
	global_store_dwordx4 v[200:201], v[180:183], off offset:16 nt
	v_lshl_add_u64 v[114:115], v[168:169], 1, s[24:25]
	v_cvt_pk_bf16_f32 v184, v116, v117
	v_cvt_pk_bf16_f32 v185, v118, v119
	s_waitcnt lgkmcnt(0)
	v_add_f32_e32 v112, v120, v121
	v_mov_b32_e32 v113, v112
	s_nop 1
	v_permlane32_swap_b32_e32 v113, v112
	v_cvt_pk_bf16_f32 v186, v180, v181
	v_cvt_pk_bf16_f32 v187, v182, v183
	global_store_dwordx4 v[114:115], v[184:187], off
	s_and_saveexec_b64 s[0:1], vcc
	s_cbranch_execz .LBB0_462
	v_lshl_add_u64 v[114:115], v[164:165], 2, s[10:11]
	s_waitcnt lgkmcnt(0)
	v_add_f32_e32 v112, v112, v113
	global_atomic_add_f32 v[114:115], v112, off
; #define EPI_IT_ROW(it) EPI_ROW((it) >> 2, (it) & 3)
; #define EPI_PACK8(v0, v1) (u32x4){pk2((v0)[0], (v0)[1]), pk2((v0)[2], (v0)[3]), pk2((v1)[0], (v1)[1]), pk2((v1)[2], (v1)[3])}
;     __device__ __forceinline__ void operator()(AccRef acc, const Unit& u, int wr, int wc, int fr, int fq) const {
;         asm volatile("" : "+v"(fr), "+v"(fq));
;         f32x4 xc[2][2], xn[2][2];
; #pragma unroll
;         for (int bj = 0; bj < 2; ++bj) { const size_t p = (size_t)EPI_IT_ROW(0) * DM + EPI_COL(bj); xc[bj][0] = *(const f32x4*)(xin + p); xc[bj][1] = *(const f32x4*)(xin + p + 4); }
; #pragma unroll
;         for (int it = 0; it < 8; ++it) { const int ai = it >> 2, m = it & 3, row = EPI_IT_ROW(it);
;             if (it + 1 < 8) {
; #pragma unroll
;                 for (int bj = 0; bj < 2; ++bj) { const size_t p = (size_t)EPI_IT_ROW(it + 1) * DM + EPI_COL(bj); xn[bj][0] = *(const f32x4*)(xin + p); xn[bj][1] = *(const f32x4*)(xin + p + 4); } }
;             float q = 0.f;
; #pragma unroll
;             for (int bj = 0; bj < 2; ++bj) { const size_t p = (size_t)row * DM + EPI_COL(bj);
;                 const f32x4 x0 = xc[bj][0] + acc[ai][bj][m][0], x1 = xc[bj][1] + acc[ai][bj][m][1];
;                 __builtin_nontemporal_store(x0, (f32x4*)(xout + p)); __builtin_nontemporal_store(x1, (f32x4*)(xout + p + 4));
;                 *(u32x4*)(xb + p) = EPI_PACK8(x0, x1);
;                 q += EPI_SQ8(x0, x1); }
;             q += __shfl_xor(q, 16); q += __shfl_xor(q, 32);
;             if (fq == 0) atomicAdd(ssout + row, q);
; #pragma unroll
;             for (int bj = 0; bj < 2; ++bj) { xc[bj][0] = xn[bj][0]; xc[bj][1] = xn[bj][1]; } }
;     }
.LBB0_462:
	s_or_b64 exec, exec, s[0:1]
	v_add_u32_e32 v168, 32, v164
	v_ashrrev_i32_e32 v169, 31, v168
	s_waitcnt lgkmcnt(0)
	v_lshlrev_b64 v[112:113], 12, v[168:169]
	v_lshl_add_u64 v[112:113], s[16:17], 0, v[112:113]
	v_lshl_add_u64 v[114:115], v[162:163], 2, v[112:113]
	v_lshl_add_u64 v[116:117], v[160:161], 2, v[112:113]
	global_load_dwordx4 v[120:123], v[114:115], off offset:16
	global_load_dwordx4 v[124:127], v[114:115], off
	s_nop 0
	global_load_dwordx4 v[112:115], v[116:117], off offset:16
	s_nop 0
	global_load_dwordx4 v[116:119], v[116:117], off
	v_lshlrev_b64 v[180:181], 10, v[166:167]
	v_lshl_add_u64 v[182:183], v[180:181], 0, v[162:163]
	v_pk_add_f32 v[110:111], v[110:111], v[142:143]
	v_pk_add_f32 v[108:109], v[108:109], v[140:141]
	v_pk_add_f32 v[104:105], v[104:105], v[136:137]
	v_lshl_add_u64 v[136:137], v[182:183], 2, s[48:49]
	v_pk_add_f32 v[106:107], v[106:107], v[138:139]
	global_store_dwordx4 v[136:137], v[108:111], off nt
	global_store_dwordx4 v[136:137], v[104:107], off offset:16 nt
	v_cvt_pk_bf16_f32 v136, v108, v109
	v_cvt_pk_bf16_f32 v138, v104, v105
	v_pk_add_f32 v[102:103], v[102:103], v[134:135]
	v_mul_f32_e32 v109, v109, v109
	v_fmac_f32_e32 v109, v108, v108
	v_mul_f32_e32 v108, v111, v111
	v_fmac_f32_e32 v108, v110, v110
	v_mul_f32_e32 v105, v105, v105
	v_add_f32_e32 v108, v109, v108
	v_fmac_f32_e32 v105, v104, v104
	v_add_f32_e32 v104, v108, v105
	v_mul_f32_e32 v105, v107, v107
	v_pk_add_f32 v[100:101], v[100:101], v[132:133]
	v_cvt_pk_bf16_f32 v139, v106, v107
	v_fmac_f32_e32 v105, v106, v106
	v_pk_add_f32 v[106:107], v[98:99], v[130:131]
	v_mul_f32_e32 v98, v101, v101
	v_mul_f32_e32 v99, v103, v103
	v_cvt_pk_bf16_f32 v137, v110, v111
	v_add_f32_e32 v110, v105, v104
	v_pk_add_f32 v[104:105], v[96:97], v[128:129]
	v_fmac_f32_e32 v98, v100, v100
	v_fmac_f32_e32 v99, v102, v102
	v_add_f32_e32 v98, v98, v99
	v_mul_f32_e32 v99, v105, v105
	v_fmac_f32_e32 v99, v104, v104
	v_add_f32_e32 v98, v98, v99
	v_mul_f32_e32 v99, v107, v107
	v_fmac_f32_e32 v99, v106, v106
	v_add_f32_e32 v98, v99, v98
	v_add_f32_e32 v110, v110, v98
	v_mov_b32_e32 v111, v110
	s_nop 1
	v_permlane16_swap_b32_e32 v111, v110
	v_lshl_add_u64 v[108:109], v[180:181], 0, v[160:161]
	v_lshl_add_u64 v[140:141], v[182:183], 1, s[24:25]
	v_lshl_add_u64 v[96:97], v[108:109], 2, s[48:49]
	global_store_dwordx4 v[140:141], v[136:139], off
	global_store_dwordx4 v[96:97], v[100:103], off nt
	global_store_dwordx4 v[96:97], v[104:107], off offset:16 nt
	s_waitcnt lgkmcnt(0)
	v_add_f32_e32 v96, v110, v111
	v_mov_b32_e32 v97, v96
	s_nop 1
	v_permlane32_swap_b32_e32 v97, v96
	v_cvt_pk_bf16_f32 v99, v102, v103
	v_lshl_add_u64 v[102:103], v[108:109], 1, s[24:25]
	v_cvt_pk_bf16_f32 v98, v100, v101
	v_cvt_pk_bf16_f32 v100, v104, v105
	v_cvt_pk_bf16_f32 v101, v106, v107
	global_store_dwordx4 v[102:103], v[98:101], off
	s_and_saveexec_b64 s[0:1], vcc
	s_cbranch_execz .LBB0_464
	v_lshl_add_u64 v[98:99], v[166:167], 2, s[10:11]
	s_waitcnt lgkmcnt(0)
	v_add_f32_e32 v96, v96, v97
	global_atomic_add_f32 v[98:99], v96, off
.LBB0_464:
	s_or_b64 exec, exec, s[0:1]
	v_add_u32_e32 v128, 48, v164
	v_ashrrev_i32_e32 v129, 31, v128
	s_waitcnt lgkmcnt(0)
	v_lshlrev_b64 v[96:97], 12, v[128:129]
	v_lshl_add_u64 v[96:97], s[16:17], 0, v[96:97]
	v_lshl_add_u64 v[98:99], v[162:163], 2, v[96:97]
	v_lshl_add_u64 v[100:101], v[160:161], 2, v[96:97]
	global_load_dwordx4 v[104:107], v[98:99], off offset:16
	global_load_dwordx4 v[108:111], v[98:99], off
	s_nop 0
	global_load_dwordx4 v[96:99], v[100:101], off offset:16
	s_nop 0
	global_load_dwordx4 v[100:103], v[100:101], off
	v_lshlrev_b64 v[130:131], 10, v[168:169]
	v_lshl_add_u64 v[132:133], v[130:131], 0, v[162:163]
	s_waitcnt vmcnt(12)
	v_pk_add_f32 v[94:95], v[94:95], v[126:127]
	v_pk_add_f32 v[92:93], v[92:93], v[124:125]
	v_pk_add_f32 v[88:89], v[88:89], v[120:121]
	v_lshl_add_u64 v[120:121], v[132:133], 2, s[48:49]
	v_pk_add_f32 v[90:91], v[90:91], v[122:123]
	global_store_dwordx4 v[120:121], v[92:95], off nt
	global_store_dwordx4 v[120:121], v[88:91], off offset:16 nt
	v_cvt_pk_bf16_f32 v120, v92, v93
	v_cvt_pk_bf16_f32 v122, v88, v89
	s_waitcnt vmcnt(12)
	v_pk_add_f32 v[86:87], v[86:87], v[118:119]
	v_mul_f32_e32 v93, v93, v93
	v_fmac_f32_e32 v93, v92, v92
	v_mul_f32_e32 v92, v95, v95
	v_fmac_f32_e32 v92, v94, v94
	v_mul_f32_e32 v89, v89, v89
	v_add_f32_e32 v92, v93, v92
	v_fmac_f32_e32 v89, v88, v88
	v_add_f32_e32 v88, v92, v89
	v_mul_f32_e32 v89, v91, v91
	v_pk_add_f32 v[84:85], v[84:85], v[116:117]
	v_cvt_pk_bf16_f32 v123, v90, v91
	v_fmac_f32_e32 v89, v90, v90
	v_pk_add_f32 v[90:91], v[82:83], v[114:115]
	v_mul_f32_e32 v82, v85, v85
	v_mul_f32_e32 v83, v87, v87
	v_cvt_pk_bf16_f32 v121, v94, v95
	v_add_f32_e32 v94, v89, v88
	v_pk_add_f32 v[88:89], v[80:81], v[112:113]
	v_fmac_f32_e32 v82, v84, v84
	v_fmac_f32_e32 v83, v86, v86
	v_add_f32_e32 v82, v82, v83
	v_mul_f32_e32 v83, v89, v89
	v_fmac_f32_e32 v83, v88, v88
	v_add_f32_e32 v82, v82, v83
	v_mul_f32_e32 v83, v91, v91
	v_fmac_f32_e32 v83, v90, v90
	v_add_f32_e32 v82, v83, v82
	v_add_f32_e32 v94, v94, v82
	v_mov_b32_e32 v95, v94
	s_nop 1
	v_permlane16_swap_b32_e32 v95, v94
	v_lshl_add_u64 v[92:93], v[130:131], 0, v[160:161]
	v_lshl_add_u64 v[124:125], v[132:133], 1, s[24:25]
	v_lshl_add_u64 v[80:81], v[92:93], 2, s[48:49]
	global_store_dwordx4 v[124:125], v[120:123], off
	global_store_dwordx4 v[80:81], v[84:87], off nt
	global_store_dwordx4 v[80:81], v[88:91], off offset:16 nt
	s_waitcnt lgkmcnt(0)
	v_add_f32_e32 v80, v94, v95
	v_mov_b32_e32 v81, v80
	s_nop 1
	v_permlane32_swap_b32_e32 v81, v80
	v_cvt_pk_bf16_f32 v83, v86, v87
	v_lshl_add_u64 v[86:87], v[92:93], 1, s[24:25]
	v_cvt_pk_bf16_f32 v82, v84, v85
	v_cvt_pk_bf16_f32 v84, v88, v89
	v_cvt_pk_bf16_f32 v85, v90, v91
	global_store_dwordx4 v[86:87], v[82:85], off
	s_and_saveexec_b64 s[0:1], vcc
	s_cbranch_execz .LBB0_466
	v_lshl_add_u64 v[82:83], v[168:169], 2, s[10:11]
	s_waitcnt lgkmcnt(0)
	v_add_f32_e32 v80, v80, v81
	global_atomic_add_f32 v[82:83], v80, off
; #define EPI_IT_ROW(it) EPI_ROW((it) >> 2, (it) & 3)
; #define EPI_PACK8(v0, v1) (u32x4){pk2((v0)[0], (v0)[1]), pk2((v0)[2], (v0)[3]), pk2((v1)[0], (v1)[1]), pk2((v1)[2], (v1)[3])}
;     __device__ __forceinline__ void operator()(AccRef acc, const Unit& u, int wr, int wc, int fr, int fq) const {
;         asm volatile("" : "+v"(fr), "+v"(fq));
;         f32x4 xc[2][2], xn[2][2];
; #pragma unroll
;         for (int bj = 0; bj < 2; ++bj) { const size_t p = (size_t)EPI_IT_ROW(0) * DM + EPI_COL(bj); xc[bj][0] = *(const f32x4*)(xin + p); xc[bj][1] = *(const f32x4*)(xin + p + 4); }
; #pragma unroll
;         for (int it = 0; it < 8; ++it) { const int ai = it >> 2, m = it & 3, row = EPI_IT_ROW(it);
;             if (it + 1 < 8) {
; #pragma unroll
;                 for (int bj = 0; bj < 2; ++bj) { const size_t p = (size_t)EPI_IT_ROW(it + 1) * DM + EPI_COL(bj); xn[bj][0] = *(const f32x4*)(xin + p); xn[bj][1] = *(const f32x4*)(xin + p + 4); } }
;             float q = 0.f;
; #pragma unroll
;             for (int bj = 0; bj < 2; ++bj) { const size_t p = (size_t)row * DM + EPI_COL(bj);
;                 const f32x4 x0 = xc[bj][0] + acc[ai][bj][m][0], x1 = xc[bj][1] + acc[ai][bj][m][1];
;                 __builtin_nontemporal_store(x0, (f32x4*)(xout + p)); __builtin_nontemporal_store(x1, (f32x4*)(xout + p + 4));
;                 *(u32x4*)(xb + p) = EPI_PACK8(x0, x1);
;                 q += EPI_SQ8(x0, x1); }
;             q += __shfl_xor(q, 16); q += __shfl_xor(q, 32);
;             if (fq == 0) atomicAdd(ssout + row, q);
; #pragma unroll
;             for (int bj = 0; bj < 2; ++bj) { xc[bj][0] = xn[bj][0]; xc[bj][1] = xn[bj][1]; } }
;     }
.LBB0_466:
	s_or_b64 exec, exec, s[0:1]
	v_add_u32_e32 v112, 0x80, v164
	v_ashrrev_i32_e32 v113, 31, v112
	s_waitcnt lgkmcnt(0)
	v_lshlrev_b64 v[80:81], 12, v[112:113]
	v_lshl_add_u64 v[80:81], s[16:17], 0, v[80:81]
	v_lshl_add_u64 v[82:83], v[162:163], 2, v[80:81]
	v_lshl_add_u64 v[84:85], v[160:161], 2, v[80:81]
	global_load_dwordx4 v[88:91], v[82:83], off offset:16
	global_load_dwordx4 v[92:95], v[82:83], off
	s_nop 0
	global_load_dwordx4 v[80:83], v[84:85], off offset:16
	s_nop 0
	global_load_dwordx4 v[84:87], v[84:85], off
	v_lshlrev_b64 v[114:115], 10, v[128:129]
	v_lshl_add_u64 v[116:117], v[114:115], 0, v[162:163]
	s_waitcnt vmcnt(12)
	v_pk_add_f32 v[78:79], v[78:79], v[110:111]
	v_pk_add_f32 v[76:77], v[76:77], v[108:109]
	v_pk_add_f32 v[72:73], v[72:73], v[104:105]
	v_lshl_add_u64 v[104:105], v[116:117], 2, s[48:49]
	v_pk_add_f32 v[74:75], v[74:75], v[106:107]
	global_store_dwordx4 v[104:105], v[76:79], off nt
	global_store_dwordx4 v[104:105], v[72:75], off offset:16 nt
	v_cvt_pk_bf16_f32 v104, v76, v77
	v_cvt_pk_bf16_f32 v106, v72, v73
	s_waitcnt vmcnt(12)
	v_pk_add_f32 v[70:71], v[70:71], v[102:103]
	v_mul_f32_e32 v77, v77, v77
	v_fmac_f32_e32 v77, v76, v76
	v_mul_f32_e32 v76, v79, v79
	v_fmac_f32_e32 v76, v78, v78
	v_mul_f32_e32 v73, v73, v73
	v_add_f32_e32 v76, v77, v76
	v_fmac_f32_e32 v73, v72, v72
	v_add_f32_e32 v72, v76, v73
	v_mul_f32_e32 v73, v75, v75
	v_pk_add_f32 v[68:69], v[68:69], v[100:101]
	v_cvt_pk_bf16_f32 v107, v74, v75
	v_fmac_f32_e32 v73, v74, v74
	v_pk_add_f32 v[74:75], v[66:67], v[98:99]
	v_mul_f32_e32 v66, v69, v69
	v_mul_f32_e32 v67, v71, v71
	v_cvt_pk_bf16_f32 v105, v78, v79
	v_add_f32_e32 v78, v73, v72
	v_pk_add_f32 v[72:73], v[64:65], v[96:97]
	v_fmac_f32_e32 v66, v68, v68
	v_fmac_f32_e32 v67, v70, v70
	v_add_f32_e32 v66, v66, v67
	v_mul_f32_e32 v67, v73, v73
	v_fmac_f32_e32 v67, v72, v72
	v_add_f32_e32 v66, v66, v67
	v_mul_f32_e32 v67, v75, v75
	v_fmac_f32_e32 v67, v74, v74
	v_add_f32_e32 v66, v67, v66
	v_add_f32_e32 v78, v78, v66
	v_mov_b32_e32 v79, v78
	s_nop 1
	v_permlane16_swap_b32_e32 v79, v78
	v_lshl_add_u64 v[76:77], v[114:115], 0, v[160:161]
	v_lshl_add_u64 v[108:109], v[116:117], 1, s[24:25]
	v_lshl_add_u64 v[64:65], v[76:77], 2, s[48:49]
	global_store_dwordx4 v[108:109], v[104:107], off
	global_store_dwordx4 v[64:65], v[68:71], off nt
	global_store_dwordx4 v[64:65], v[72:75], off offset:16 nt
	s_waitcnt lgkmcnt(0)
	v_add_f32_e32 v64, v78, v79
	v_mov_b32_e32 v65, v64
	s_nop 1
	v_permlane32_swap_b32_e32 v65, v64
	v_cvt_pk_bf16_f32 v67, v70, v71
	v_lshl_add_u64 v[70:71], v[76:77], 1, s[24:25]
	v_cvt_pk_bf16_f32 v66, v68, v69
	v_cvt_pk_bf16_f32 v68, v72, v73
	v_cvt_pk_bf16_f32 v69, v74, v75
	global_store_dwordx4 v[70:71], v[66:69], off
	s_and_saveexec_b64 s[0:1], vcc
	s_cbranch_execz .LBB0_468
	v_lshl_add_u64 v[66:67], v[128:129], 2, s[10:11]
	s_waitcnt lgkmcnt(0)
	v_add_f32_e32 v64, v64, v65
	global_atomic_add_f32 v[66:67], v64, off
.LBB0_468:
	s_or_b64 exec, exec, s[0:1]
	v_add_u32_e32 v96, 0x90, v164
	v_ashrrev_i32_e32 v97, 31, v96
	s_waitcnt lgkmcnt(0)
	v_lshlrev_b64 v[64:65], 12, v[96:97]
	v_lshl_add_u64 v[64:65], s[16:17], 0, v[64:65]
	v_lshl_add_u64 v[66:67], v[162:163], 2, v[64:65]
	v_lshl_add_u64 v[68:69], v[160:161], 2, v[64:65]
	global_load_dwordx4 v[72:75], v[66:67], off offset:16
	global_load_dwordx4 v[76:79], v[66:67], off
	s_nop 0
	global_load_dwordx4 v[64:67], v[68:69], off offset:16
	s_nop 0
	global_load_dwordx4 v[68:71], v[68:69], off
	v_lshlrev_b64 v[98:99], 10, v[112:113]
	v_lshl_add_u64 v[100:101], v[98:99], 0, v[162:163]
	s_waitcnt vmcnt(12)
	v_pk_add_f32 v[62:63], v[62:63], v[94:95]
	v_pk_add_f32 v[60:61], v[60:61], v[92:93]
	v_pk_add_f32 v[56:57], v[56:57], v[88:89]
	v_lshl_add_u64 v[88:89], v[100:101], 2, s[48:49]
	v_pk_add_f32 v[58:59], v[58:59], v[90:91]
	global_store_dwordx4 v[88:89], v[60:63], off nt
	global_store_dwordx4 v[88:89], v[56:59], off offset:16 nt
	v_cvt_pk_bf16_f32 v88, v60, v61
	v_cvt_pk_bf16_f32 v90, v56, v57
	s_waitcnt vmcnt(12)
	v_pk_add_f32 v[54:55], v[54:55], v[86:87]
	v_mul_f32_e32 v61, v61, v61
	v_fmac_f32_e32 v61, v60, v60
	v_mul_f32_e32 v60, v63, v63
	v_fmac_f32_e32 v60, v62, v62
	v_mul_f32_e32 v57, v57, v57
	v_add_f32_e32 v60, v61, v60
	v_fmac_f32_e32 v57, v56, v56
	v_add_f32_e32 v56, v60, v57
	v_mul_f32_e32 v57, v59, v59
	v_pk_add_f32 v[52:53], v[52:53], v[84:85]
	v_cvt_pk_bf16_f32 v91, v58, v59
	v_fmac_f32_e32 v57, v58, v58
	v_pk_add_f32 v[58:59], v[50:51], v[82:83]
	v_mul_f32_e32 v50, v53, v53
	v_mul_f32_e32 v51, v55, v55
	v_cvt_pk_bf16_f32 v89, v62, v63
	v_add_f32_e32 v62, v57, v56
	v_pk_add_f32 v[56:57], v[48:49], v[80:81]
	v_fmac_f32_e32 v50, v52, v52
	v_fmac_f32_e32 v51, v54, v54
	v_add_f32_e32 v50, v50, v51
	v_mul_f32_e32 v51, v57, v57
	v_fmac_f32_e32 v51, v56, v56
	v_add_f32_e32 v50, v50, v51
	v_mul_f32_e32 v51, v59, v59
	v_fmac_f32_e32 v51, v58, v58
	v_add_f32_e32 v50, v51, v50
	v_add_f32_e32 v62, v62, v50
	v_mov_b32_e32 v63, v62
	s_nop 1
	v_permlane16_swap_b32_e32 v63, v62
	v_lshl_add_u64 v[60:61], v[98:99], 0, v[160:161]
	v_lshl_add_u64 v[92:93], v[100:101], 1, s[24:25]
	v_lshl_add_u64 v[48:49], v[60:61], 2, s[48:49]
	global_store_dwordx4 v[92:93], v[88:91], off
	global_store_dwordx4 v[48:49], v[52:55], off nt
	global_store_dwordx4 v[48:49], v[56:59], off offset:16 nt
	s_waitcnt lgkmcnt(0)
	v_add_f32_e32 v48, v62, v63
	v_mov_b32_e32 v49, v48
	s_nop 1
	v_permlane32_swap_b32_e32 v49, v48
	v_cvt_pk_bf16_f32 v51, v54, v55
	v_lshl_add_u64 v[54:55], v[60:61], 1, s[24:25]
	v_cvt_pk_bf16_f32 v50, v52, v53
	v_cvt_pk_bf16_f32 v52, v56, v57
	v_cvt_pk_bf16_f32 v53, v58, v59
	global_store_dwordx4 v[54:55], v[50:53], off
	s_and_saveexec_b64 s[0:1], vcc
	s_cbranch_execz .LBB0_470
	v_lshl_add_u64 v[50:51], v[112:113], 2, s[10:11]
	s_waitcnt lgkmcnt(0)
	v_add_f32_e32 v48, v48, v49
	global_atomic_add_f32 v[50:51], v48, off
; #define EPI_IT_ROW(it) EPI_ROW((it) >> 2, (it) & 3)
; #define EPI_PACK8(v0, v1) (u32x4){pk2((v0)[0], (v0)[1]), pk2((v0)[2], (v0)[3]), pk2((v1)[0], (v1)[1]), pk2((v1)[2], (v1)[3])}
;     __device__ __forceinline__ void operator()(AccRef acc, const Unit& u, int wr, int wc, int fr, int fq) const {
;         asm volatile("" : "+v"(fr), "+v"(fq));
;         f32x4 xc[2][2], xn[2][2];
; #pragma unroll
;         for (int bj = 0; bj < 2; ++bj) { const size_t p = (size_t)EPI_IT_ROW(0) * DM + EPI_COL(bj); xc[bj][0] = *(const f32x4*)(xin + p); xc[bj][1] = *(const f32x4*)(xin + p + 4); }
; #pragma unroll
;         for (int it = 0; it < 8; ++it) { const int ai = it >> 2, m = it & 3, row = EPI_IT_ROW(it);
;             if (it + 1 < 8) {
; #pragma unroll
;                 for (int bj = 0; bj < 2; ++bj) { const size_t p = (size_t)EPI_IT_ROW(it + 1) * DM + EPI_COL(bj); xn[bj][0] = *(const f32x4*)(xin + p); xn[bj][1] = *(const f32x4*)(xin + p + 4); } }
;             float q = 0.f;
; #pragma unroll
;             for (int bj = 0; bj < 2; ++bj) { const size_t p = (size_t)row * DM + EPI_COL(bj);
;                 const f32x4 x0 = xc[bj][0] + acc[ai][bj][m][0], x1 = xc[bj][1] + acc[ai][bj][m][1];
;                 __builtin_nontemporal_store(x0, (f32x4*)(xout + p)); __builtin_nontemporal_store(x1, (f32x4*)(xout + p + 4));
;                 *(u32x4*)(xb + p) = EPI_PACK8(x0, x1);
;                 q += EPI_SQ8(x0, x1); }
;             q += __shfl_xor(q, 16); q += __shfl_xor(q, 32);
;             if (fq == 0) atomicAdd(ssout + row, q);
; #pragma unroll
;             for (int bj = 0; bj < 2; ++bj) { xc[bj][0] = xn[bj][0]; xc[bj][1] = xn[bj][1]; } }
;     }
.LBB0_470:
	s_or_b64 exec, exec, s[0:1]
	v_add_u32_e32 v80, 0xa0, v164
	v_ashrrev_i32_e32 v81, 31, v80
	s_waitcnt lgkmcnt(0)
	v_lshlrev_b64 v[48:49], 12, v[80:81]
	v_lshl_add_u64 v[48:49], s[16:17], 0, v[48:49]
	v_lshl_add_u64 v[50:51], v[162:163], 2, v[48:49]
	v_lshl_add_u64 v[52:53], v[160:161], 2, v[48:49]
	global_load_dwordx4 v[56:59], v[50:51], off offset:16
	global_load_dwordx4 v[60:63], v[50:51], off
	s_nop 0
	global_load_dwordx4 v[48:51], v[52:53], off offset:16
	s_nop 0
	global_load_dwordx4 v[52:55], v[52:53], off
	v_lshlrev_b64 v[82:83], 10, v[96:97]
	v_lshl_add_u64 v[84:85], v[82:83], 0, v[162:163]
	s_waitcnt vmcnt(12)
	v_pk_add_f32 v[46:47], v[46:47], v[78:79]
	v_pk_add_f32 v[44:45], v[44:45], v[76:77]
	v_pk_add_f32 v[40:41], v[40:41], v[72:73]
	v_lshl_add_u64 v[72:73], v[84:85], 2, s[48:49]
	v_pk_add_f32 v[42:43], v[42:43], v[74:75]
	global_store_dwordx4 v[72:73], v[44:47], off nt
	global_store_dwordx4 v[72:73], v[40:43], off offset:16 nt
	v_cvt_pk_bf16_f32 v72, v44, v45
	v_cvt_pk_bf16_f32 v74, v40, v41
	s_waitcnt vmcnt(12)
	v_pk_add_f32 v[38:39], v[38:39], v[70:71]
	v_mul_f32_e32 v45, v45, v45
	v_fmac_f32_e32 v45, v44, v44
	v_mul_f32_e32 v44, v47, v47
	v_fmac_f32_e32 v44, v46, v46
	v_mul_f32_e32 v41, v41, v41
	v_add_f32_e32 v44, v45, v44
	v_fmac_f32_e32 v41, v40, v40
	v_add_f32_e32 v40, v44, v41
	v_mul_f32_e32 v41, v43, v43
	v_pk_add_f32 v[36:37], v[36:37], v[68:69]
	v_cvt_pk_bf16_f32 v75, v42, v43
	v_fmac_f32_e32 v41, v42, v42
	v_pk_add_f32 v[42:43], v[34:35], v[66:67]
	v_mul_f32_e32 v34, v37, v37
	v_mul_f32_e32 v35, v39, v39
	v_cvt_pk_bf16_f32 v73, v46, v47
	v_add_f32_e32 v46, v41, v40
	v_pk_add_f32 v[40:41], v[32:33], v[64:65]
	v_fmac_f32_e32 v34, v36, v36
	v_fmac_f32_e32 v35, v38, v38
	v_add_f32_e32 v34, v34, v35
	v_mul_f32_e32 v35, v41, v41
	v_fmac_f32_e32 v35, v40, v40
	v_add_f32_e32 v34, v34, v35
	v_mul_f32_e32 v35, v43, v43
	v_fmac_f32_e32 v35, v42, v42
	v_add_f32_e32 v34, v35, v34
	v_add_f32_e32 v46, v46, v34
	v_mov_b32_e32 v47, v46
	s_nop 1
	v_permlane16_swap_b32_e32 v47, v46
	v_lshl_add_u64 v[44:45], v[82:83], 0, v[160:161]
	v_lshl_add_u64 v[76:77], v[84:85], 1, s[24:25]
	v_lshl_add_u64 v[32:33], v[44:45], 2, s[48:49]
	global_store_dwordx4 v[76:77], v[72:75], off
	global_store_dwordx4 v[32:33], v[36:39], off nt
	global_store_dwordx4 v[32:33], v[40:43], off offset:16 nt
	s_waitcnt lgkmcnt(0)
	v_add_f32_e32 v32, v46, v47
	v_mov_b32_e32 v33, v32
	s_nop 1
	v_permlane32_swap_b32_e32 v33, v32
	v_cvt_pk_bf16_f32 v35, v38, v39
	v_lshl_add_u64 v[38:39], v[44:45], 1, s[24:25]
	v_cvt_pk_bf16_f32 v34, v36, v37
	v_cvt_pk_bf16_f32 v36, v40, v41
	v_cvt_pk_bf16_f32 v37, v42, v43
	global_store_dwordx4 v[38:39], v[34:37], off
	s_and_saveexec_b64 s[0:1], vcc
	s_cbranch_execz .LBB0_472
	v_lshl_add_u64 v[34:35], v[96:97], 2, s[10:11]
	s_waitcnt lgkmcnt(0)
	v_add_f32_e32 v32, v32, v33
	global_atomic_add_f32 v[34:35], v32, off
; #define EPI_IT_ROW(it) EPI_ROW((it) >> 2, (it) & 3)
; #define EPI_PACK8(v0, v1) (u32x4){pk2((v0)[0], (v0)[1]), pk2((v0)[2], (v0)[3]), pk2((v1)[0], (v1)[1]), pk2((v1)[2], (v1)[3])}
;     __device__ __forceinline__ void operator()(AccRef acc, const Unit& u, int wr, int wc, int fr, int fq) const {
;         asm volatile("" : "+v"(fr), "+v"(fq));
;         f32x4 xc[2][2], xn[2][2];
; #pragma unroll
;         for (int bj = 0; bj < 2; ++bj) { const size_t p = (size_t)EPI_IT_ROW(0) * DM + EPI_COL(bj); xc[bj][0] = *(const f32x4*)(xin + p); xc[bj][1] = *(const f32x4*)(xin + p + 4); }
; #pragma unroll
;         for (int it = 0; it < 8; ++it) { const int ai = it >> 2, m = it & 3, row = EPI_IT_ROW(it);
;             if (it + 1 < 8) {
; #pragma unroll
;                 for (int bj = 0; bj < 2; ++bj) { const size_t p = (size_t)EPI_IT_ROW(it + 1) * DM + EPI_COL(bj); xn[bj][0] = *(const f32x4*)(xin + p); xn[bj][1] = *(const f32x4*)(xin + p + 4); } }
;             float q = 0.f;
; #pragma unroll
;             for (int bj = 0; bj < 2; ++bj) { const size_t p = (size_t)row * DM + EPI_COL(bj);
;                 const f32x4 x0 = xc[bj][0] + acc[ai][bj][m][0], x1 = xc[bj][1] + acc[ai][bj][m][1];
;                 __builtin_nontemporal_store(x0, (f32x4*)(xout + p)); __builtin_nontemporal_store(x1, (f32x4*)(xout + p + 4));
;                 *(u32x4*)(xb + p) = EPI_PACK8(x0, x1);
;                 q += EPI_SQ8(x0, x1); }
;             q += __shfl_xor(q, 16); q += __shfl_xor(q, 32);
;             if (fq == 0) atomicAdd(ssout + row, q);
; #pragma unroll
;             for (int bj = 0; bj < 2; ++bj) { xc[bj][0] = xn[bj][0]; xc[bj][1] = xn[bj][1]; } }
;     }
.LBB0_472:
	s_or_b64 exec, exec, s[0:1]
	v_add_u32_e32 v64, 0xb0, v164
	v_ashrrev_i32_e32 v65, 31, v64
	s_waitcnt lgkmcnt(0)
	v_lshlrev_b64 v[32:33], 12, v[64:65]
	v_lshl_add_u64 v[32:33], s[16:17], 0, v[32:33]
	v_lshl_add_u64 v[34:35], v[162:163], 2, v[32:33]
	v_lshl_add_u64 v[36:37], v[160:161], 2, v[32:33]
	global_load_dwordx4 v[40:43], v[34:35], off offset:16
	global_load_dwordx4 v[44:47], v[34:35], off
	s_nop 0
	global_load_dwordx4 v[32:35], v[36:37], off offset:16
	s_nop 0
	global_load_dwordx4 v[36:39], v[36:37], off
	v_lshlrev_b64 v[66:67], 10, v[80:81]
	v_lshl_add_u64 v[68:69], v[66:67], 0, v[162:163]
	s_waitcnt vmcnt(12)
	v_pk_add_f32 v[30:31], v[30:31], v[62:63]
	v_pk_add_f32 v[28:29], v[28:29], v[60:61]
	v_pk_add_f32 v[24:25], v[24:25], v[56:57]
	v_lshl_add_u64 v[56:57], v[68:69], 2, s[48:49]
	v_pk_add_f32 v[26:27], v[26:27], v[58:59]
	global_store_dwordx4 v[56:57], v[28:31], off nt
	global_store_dwordx4 v[56:57], v[24:27], off offset:16 nt
	v_cvt_pk_bf16_f32 v56, v28, v29
	v_cvt_pk_bf16_f32 v58, v24, v25
	s_waitcnt vmcnt(12)
	v_pk_add_f32 v[22:23], v[22:23], v[54:55]
	v_mul_f32_e32 v29, v29, v29
	v_fmac_f32_e32 v29, v28, v28
	v_mul_f32_e32 v28, v31, v31
	v_fmac_f32_e32 v28, v30, v30
	v_mul_f32_e32 v25, v25, v25
	v_add_f32_e32 v28, v29, v28
	v_fmac_f32_e32 v25, v24, v24
	v_add_f32_e32 v24, v28, v25
	v_mul_f32_e32 v25, v27, v27
	v_pk_add_f32 v[20:21], v[20:21], v[52:53]
	v_cvt_pk_bf16_f32 v59, v26, v27
	v_fmac_f32_e32 v25, v26, v26
	v_pk_add_f32 v[26:27], v[18:19], v[50:51]
	v_mul_f32_e32 v18, v21, v21
	v_mul_f32_e32 v19, v23, v23
	v_cvt_pk_bf16_f32 v57, v30, v31
	v_add_f32_e32 v30, v25, v24
	v_pk_add_f32 v[24:25], v[16:17], v[48:49]
	v_fmac_f32_e32 v18, v20, v20
	v_fmac_f32_e32 v19, v22, v22
	v_add_f32_e32 v18, v18, v19
	v_mul_f32_e32 v19, v25, v25
	v_fmac_f32_e32 v19, v24, v24
	v_add_f32_e32 v18, v18, v19
	v_mul_f32_e32 v19, v27, v27
	v_fmac_f32_e32 v19, v26, v26
	v_add_f32_e32 v18, v19, v18
	v_add_f32_e32 v30, v30, v18
	v_mov_b32_e32 v31, v30
	s_nop 1
	v_permlane16_swap_b32_e32 v31, v30
	v_lshl_add_u64 v[28:29], v[66:67], 0, v[160:161]
	v_lshl_add_u64 v[60:61], v[68:69], 1, s[24:25]
	v_lshl_add_u64 v[16:17], v[28:29], 2, s[48:49]
	global_store_dwordx4 v[60:61], v[56:59], off
	global_store_dwordx4 v[16:17], v[20:23], off nt
	global_store_dwordx4 v[16:17], v[24:27], off offset:16 nt
	s_waitcnt lgkmcnt(0)
	v_add_f32_e32 v16, v30, v31
	v_mov_b32_e32 v17, v16
	s_nop 1
	v_permlane32_swap_b32_e32 v17, v16
	v_cvt_pk_bf16_f32 v19, v22, v23
	v_lshl_add_u64 v[22:23], v[28:29], 1, s[24:25]
	v_cvt_pk_bf16_f32 v18, v20, v21
	v_cvt_pk_bf16_f32 v20, v24, v25
	v_cvt_pk_bf16_f32 v21, v26, v27
	global_store_dwordx4 v[22:23], v[18:21], off
	s_and_saveexec_b64 s[0:1], vcc
	s_cbranch_execz .LBB0_474
	v_lshl_add_u64 v[18:19], v[80:81], 2, s[10:11]
	s_waitcnt lgkmcnt(0)
	v_add_f32_e32 v16, v16, v17
	global_atomic_add_f32 v[18:19], v16, off
.LBB0_474:
	s_or_b64 exec, exec, s[0:1]
	v_lshlrev_b64 v[20:21], 10, v[64:65]
	v_lshl_add_u64 v[22:23], v[20:21], 0, v[162:163]
	s_waitcnt vmcnt(8)
	v_pk_add_f32 v[14:15], v[14:15], v[46:47]
	v_pk_add_f32 v[12:13], v[12:13], v[44:45]
	s_waitcnt lgkmcnt(0)
	v_lshl_add_u64 v[16:17], v[22:23], 2, s[48:49]
	v_pk_add_f32 v[10:11], v[10:11], v[42:43]
	v_pk_add_f32 v[8:9], v[8:9], v[40:41]
	global_store_dwordx4 v[16:17], v[12:15], off nt
	global_store_dwordx4 v[16:17], v[8:11], off offset:16 nt
	v_cvt_pk_bf16_f32 v16, v12, v13
	v_cvt_pk_bf16_f32 v18, v8, v9
	s_waitcnt vmcnt(8)
	v_pk_add_f32 v[6:7], v[6:7], v[38:39]
	v_mul_f32_e32 v13, v13, v13
	v_fmac_f32_e32 v13, v12, v12
	v_mul_f32_e32 v12, v15, v15
	v_fmac_f32_e32 v12, v14, v14
	v_mul_f32_e32 v9, v9, v9
	v_add_f32_e32 v12, v13, v12
	v_fmac_f32_e32 v9, v8, v8
	v_add_f32_e32 v8, v12, v9
	v_mul_f32_e32 v9, v11, v11
	v_pk_add_f32 v[4:5], v[4:5], v[36:37]
	v_cvt_pk_bf16_f32 v19, v10, v11
	v_fmac_f32_e32 v9, v10, v10
	v_pk_add_f32 v[10:11], v[2:3], v[34:35]
	v_mul_f32_e32 v2, v5, v5
	v_mul_f32_e32 v3, v7, v7
	v_cvt_pk_bf16_f32 v17, v14, v15
	v_add_f32_e32 v14, v9, v8
	v_pk_add_f32 v[8:9], v[0:1], v[32:33]
	v_fmac_f32_e32 v2, v4, v4
	v_fmac_f32_e32 v3, v6, v6
	v_add_f32_e32 v2, v2, v3
	v_mul_f32_e32 v3, v9, v9
	v_fmac_f32_e32 v3, v8, v8
	v_add_f32_e32 v2, v2, v3
	v_mul_f32_e32 v3, v11, v11
	v_fmac_f32_e32 v3, v10, v10
	v_add_f32_e32 v2, v3, v2
	v_add_f32_e32 v14, v14, v2
	v_mov_b32_e32 v15, v14
	s_nop 1
	v_permlane16_swap_b32_e32 v15, v14
	v_lshl_add_u64 v[12:13], v[20:21], 0, v[160:161]
	v_lshl_add_u64 v[22:23], v[22:23], 1, s[24:25]
	v_lshl_add_u64 v[0:1], v[12:13], 2, s[48:49]
	global_store_dwordx4 v[22:23], v[16:19], off
	global_store_dwordx4 v[0:1], v[4:7], off nt
	global_store_dwordx4 v[0:1], v[8:11], off offset:16 nt
	s_waitcnt lgkmcnt(0)
	v_add_f32_e32 v0, v14, v15
	v_mov_b32_e32 v1, v0
	s_nop 1
	v_permlane32_swap_b32_e32 v1, v0
	v_cvt_pk_bf16_f32 v3, v6, v7
	v_lshl_add_u64 v[6:7], v[12:13], 1, s[24:25]
	v_cvt_pk_bf16_f32 v2, v4, v5
	v_cvt_pk_bf16_f32 v4, v8, v9
	v_cvt_pk_bf16_f32 v5, v10, v11
	global_store_dwordx4 v[6:7], v[2:5], off
	s_and_saveexec_b64 s[0:1], vcc
	s_cbranch_execz .LBB0_476
	v_lshl_add_u64 v[2:3], v[64:65], 2, s[10:11]
	s_waitcnt lgkmcnt(0)
	v_add_f32_e32 v0, v0, v1
	global_atomic_add_f32 v[2:3], v0, off

; #define EPI_IT_ROW(it) EPI_ROW((it) >> 2, (it) & 3)
; #define EPI_PACK8(v0, v1) (u32x4){pk2((v0)[0], (v0)[1]), pk2((v0)[2], (v0)[3]), pk2((v1)[0], (v1)[1]), pk2((v1)[2], (v1)[3])}
;     __device__ __forceinline__ void operator()(AccRef acc, const Unit& u, int wr, int wc, int fr, int fq) const {
;         asm volatile("" : "+v"(fr), "+v"(fq));
; #pragma unroll
;         for (int it = 0; it < 8; ++it) { const int ai = it >> 2, m = it & 3, row = EPI_IT_ROW(it); float q = 0.f;
; #pragma unroll
;             for (int bj = 0; bj < 2; ++bj) { const f32x4 x0 = acc[ai][bj][m][0], x1 = acc[ai][bj][m][1];
;                 *(u32x4*)(O + (size_t)row * DM + EPI_COL(bj)) = EPI_PACK8(x0, x1);
;                 q += EPI_SQ8(x0, x1); }
;             q += __shfl_xor(q, 16); q += __shfl_xor(q, 32);
;             if (fq == 0) atomicAdd(ssout + row, q); }
.LBB0_615:
	v_cvt_pk_bf16_f32 v154, v124, v125
	v_mul_f32_e32 v125, v125, v125
	v_fmac_f32_e32 v125, v124, v124
	v_mul_f32_e32 v124, v127, v127
	v_cvt_pk_bf16_f32 v156, v120, v121
	v_fmac_f32_e32 v124, v126, v126
	v_mul_f32_e32 v121, v121, v121
	v_add_f32_e32 v124, v125, v124
	v_fmac_f32_e32 v121, v120, v120
	v_add_f32_e32 v120, v124, v121
	v_mul_f32_e32 v121, v123, v123
	v_fmac_f32_e32 v121, v122, v122
	v_cvt_pk_bf16_f32 v157, v122, v123
	v_add_f32_e32 v120, v121, v120
	v_mul_f32_e32 v121, v117, v117
	v_mul_f32_e32 v122, v119, v119
	v_fmac_f32_e32 v121, v116, v116
	v_fmac_f32_e32 v122, v118, v118
	v_add_f32_e32 v121, v121, v122
	v_mul_f32_e32 v122, v113, v113
	v_fmac_f32_e32 v122, v112, v112
	v_add_f32_e32 v121, v121, v122
	v_mul_f32_e32 v122, v115, v115
	v_fmac_f32_e32 v122, v114, v114
	v_mov_b32_e32 v140, v151
	v_mov_b32_e32 v141, v153
	s_lshl_b32 s1, s34, 8
	s_lshl_b32 s0, s0, 8
	v_add_f32_e32 v121, v122, v121
	v_and_b32_e32 v122, 64, v148
	s_add_i32 s1, s1, s79
	s_or_b32 s0, s0, s80
	v_add_f32_e32 v121, v120, v121
	v_xor_b32_e32 v120, 16, v148
	v_add_u32_e32 v123, 64, v122
	v_add_u32_e32 v142, s1, v140
	v_lshl_add_u32 v140, v141, 3, s0
	v_cmp_lt_i32_e64 s[0:1], v120, v123
	v_cvt_pk_bf16_f32 v122, v116, v117
	v_xor_b32_e32 v116, 32, v148
	v_ashrrev_i32_e32 v143, 31, v142
	v_cndmask_b32_e64 v120, v148, v120, s[0:1]
	v_lshlrev_b32_e32 v120, 2, v120
	v_mov_b32_e32 v124, v121
	s_nop 1
	v_permlane16_swap_b32_e32 v124, v121
	v_cmp_lt_i32_e64 s[0:1], v116, v123
	v_lshlrev_b64 v[158:159], 11, v[142:143]
	v_cmp_eq_u32_e32 vcc, 0, v141
	v_cndmask_b32_e64 v116, v148, v116, s[0:1]
	s_waitcnt lgkmcnt(0)
	v_add_f32_e32 v117, v121, v124
	v_lshlrev_b32_e32 v116, 2, v116
	v_mov_b32_e32 v121, v117
	s_nop 1
	v_permlane32_swap_b32_e32 v121, v117
	v_lshl_add_u64 v[158:159], s[40:41], 0, v[158:159]
	v_ashrrev_i32_e32 v141, 31, v140
	v_cvt_pk_bf16_f32 v155, v126, v127
	v_lshl_add_u64 v[126:127], v[140:141], 1, v[158:159]
	global_store_dwordx4 v[126:127], v[154:157], off
	v_cvt_pk_bf16_f32 v123, v118, v119
	v_cvt_pk_bf16_f32 v124, v112, v113
	v_cvt_pk_bf16_f32 v125, v114, v115
	global_store_dwordx4 v[126:127], v[122:125], off offset:256
	s_and_saveexec_b64 s[0:1], vcc
	s_cbranch_execz .LBB0_617
	s_waitcnt lgkmcnt(0)
	v_add_f32_e32 v114, v117, v121
	v_lshl_add_u64 v[112:113], v[142:143], 2, s[14:15]
	global_atomic_add_f32 v[112:113], v114, off
.LBB0_617:
	s_or_b64 exec, exec, s[0:1]
	v_cvt_pk_bf16_f32 v122, v108, v109
	v_mul_f32_e32 v109, v109, v109
	v_fmac_f32_e32 v109, v108, v108
	v_mul_f32_e32 v108, v111, v111
	v_cvt_pk_bf16_f32 v124, v104, v105
	v_fmac_f32_e32 v108, v110, v110
	v_mul_f32_e32 v105, v105, v105
	v_add_f32_e32 v108, v109, v108
	v_fmac_f32_e32 v105, v104, v104
	v_add_f32_e32 v104, v108, v105
	v_mul_f32_e32 v105, v107, v107
	v_fmac_f32_e32 v105, v106, v106
	v_cvt_pk_bf16_f32 v125, v106, v107
	v_add_f32_e32 v104, v105, v104
	v_mul_f32_e32 v105, v101, v101
	v_mul_f32_e32 v106, v103, v103
	v_fmac_f32_e32 v105, v100, v100
	v_fmac_f32_e32 v106, v102, v102
	v_add_f32_e32 v105, v105, v106
	v_mul_f32_e32 v106, v97, v97
	v_fmac_f32_e32 v106, v96, v96
	v_add_f32_e32 v105, v105, v106
	v_mul_f32_e32 v106, v99, v99
	v_fmac_f32_e32 v106, v98, v98
	v_add_f32_e32 v105, v106, v105
	v_add_f32_e32 v106, v104, v105
	v_mov_b32_e32 v107, v106
	s_nop 1
	v_permlane16_swap_b32_e32 v107, v106
	v_add_u32_e32 v112, 16, v142
	v_ashrrev_i32_e32 v113, 31, v112
	v_lshlrev_b64 v[114:115], 11, v[112:113]
	v_lshl_add_u64 v[104:105], s[40:41], 0, v[114:115]
	v_lshl_add_u64 v[108:109], v[140:141], 1, v[104:105]
	v_cvt_pk_bf16_f32 v104, v100, v101
	s_waitcnt lgkmcnt(0)
	v_add_f32_e32 v100, v106, v107
	v_mov_b32_e32 v101, v100
	s_nop 1
	v_permlane32_swap_b32_e32 v101, v100
	v_cvt_pk_bf16_f32 v123, v110, v111
	global_store_dwordx4 v[108:109], v[122:125], off
	v_cvt_pk_bf16_f32 v105, v102, v103
	v_cvt_pk_bf16_f32 v106, v96, v97
	v_cvt_pk_bf16_f32 v107, v98, v99
	global_store_dwordx4 v[108:109], v[104:107], off offset:256
	s_and_saveexec_b64 s[0:1], vcc
	s_cbranch_execz .LBB0_619
	s_waitcnt lgkmcnt(0)
	v_add_f32_e32 v98, v100, v101
	v_lshl_add_u64 v[96:97], v[112:113], 2, s[14:15]
	global_atomic_add_f32 v[96:97], v98, off
.LBB0_619:
	s_or_b64 exec, exec, s[0:1]
	v_cvt_pk_bf16_f32 v98, v92, v93
	v_mul_f32_e32 v93, v93, v93
	v_fmac_f32_e32 v93, v92, v92
	v_mul_f32_e32 v92, v95, v95
	v_cvt_pk_bf16_f32 v100, v88, v89
	v_fmac_f32_e32 v92, v94, v94
	v_mul_f32_e32 v89, v89, v89
	v_add_f32_e32 v92, v93, v92
	v_fmac_f32_e32 v89, v88, v88
	v_add_f32_e32 v88, v92, v89
	v_mul_f32_e32 v89, v91, v91
	v_fmac_f32_e32 v89, v90, v90
	s_waitcnt lgkmcnt(0)
	v_cvt_pk_bf16_f32 v101, v90, v91
	v_add_f32_e32 v88, v89, v88
	v_mul_f32_e32 v89, v85, v85
	v_mul_f32_e32 v90, v87, v87
	v_fmac_f32_e32 v89, v84, v84
	v_fmac_f32_e32 v90, v86, v86
	v_add_f32_e32 v89, v89, v90
	v_mul_f32_e32 v90, v81, v81
	v_fmac_f32_e32 v90, v80, v80
	v_add_f32_e32 v89, v89, v90
	v_mul_f32_e32 v90, v83, v83
	v_fmac_f32_e32 v90, v82, v82
	v_add_f32_e32 v89, v90, v89
	v_add_f32_e32 v90, v88, v89
	v_mov_b32_e32 v91, v90
	s_nop 1
	v_permlane16_swap_b32_e32 v91, v90
	v_add_u32_e32 v96, 32, v142
	v_ashrrev_i32_e32 v97, 31, v96
	v_lshlrev_b64 v[102:103], 11, v[96:97]
	v_lshl_add_u64 v[88:89], s[40:41], 0, v[102:103]
	v_lshl_add_u64 v[92:93], v[140:141], 1, v[88:89]
	v_cvt_pk_bf16_f32 v88, v84, v85
	s_waitcnt lgkmcnt(0)
	v_add_f32_e32 v84, v90, v91
	v_mov_b32_e32 v85, v84
	s_nop 1
	v_permlane32_swap_b32_e32 v85, v84
	v_cvt_pk_bf16_f32 v99, v94, v95
	global_store_dwordx4 v[92:93], v[98:101], off
	v_cvt_pk_bf16_f32 v89, v86, v87
	v_cvt_pk_bf16_f32 v90, v80, v81
	v_cvt_pk_bf16_f32 v91, v82, v83
	global_store_dwordx4 v[92:93], v[88:91], off offset:256
	s_and_saveexec_b64 s[0:1], vcc
	s_cbranch_execz .LBB0_621
	s_waitcnt lgkmcnt(0)
	v_add_f32_e32 v82, v84, v85
	v_lshl_add_u64 v[80:81], v[96:97], 2, s[14:15]
	global_atomic_add_f32 v[80:81], v82, off
; #define EPI_IT_ROW(it) EPI_ROW((it) >> 2, (it) & 3)
; #define EPI_PACK8(v0, v1) (u32x4){pk2((v0)[0], (v0)[1]), pk2((v0)[2], (v0)[3]), pk2((v1)[0], (v1)[1]), pk2((v1)[2], (v1)[3])}
;     __device__ __forceinline__ void operator()(AccRef acc, const Unit& u, int wr, int wc, int fr, int fq) const {
;         asm volatile("" : "+v"(fr), "+v"(fq));
; #pragma unroll
;         for (int it = 0; it < 8; ++it) { const int ai = it >> 2, m = it & 3, row = EPI_IT_ROW(it); float q = 0.f;
; #pragma unroll
;             for (int bj = 0; bj < 2; ++bj) { const f32x4 x0 = acc[ai][bj][m][0], x1 = acc[ai][bj][m][1];
;                 *(u32x4*)(O + (size_t)row * DM + EPI_COL(bj)) = EPI_PACK8(x0, x1);
;                 q += EPI_SQ8(x0, x1); }
;             q += __shfl_xor(q, 16); q += __shfl_xor(q, 32);
;             if (fq == 0) atomicAdd(ssout + row, q); }
.LBB0_621:
	s_or_b64 exec, exec, s[0:1]
	v_cvt_pk_bf16_f32 v82, v76, v77
	v_mul_f32_e32 v77, v77, v77
	v_fmac_f32_e32 v77, v76, v76
	v_mul_f32_e32 v76, v79, v79
	v_cvt_pk_bf16_f32 v84, v72, v73
	v_fmac_f32_e32 v76, v78, v78
	v_mul_f32_e32 v73, v73, v73
	v_add_f32_e32 v76, v77, v76
	v_fmac_f32_e32 v73, v72, v72
	v_add_f32_e32 v72, v76, v73
	v_mul_f32_e32 v73, v75, v75
	v_fmac_f32_e32 v73, v74, v74
	s_waitcnt lgkmcnt(0)
	v_cvt_pk_bf16_f32 v85, v74, v75
	v_add_f32_e32 v72, v73, v72
	v_mul_f32_e32 v73, v69, v69
	v_mul_f32_e32 v74, v71, v71
	v_fmac_f32_e32 v73, v68, v68
	v_fmac_f32_e32 v74, v70, v70
	v_add_f32_e32 v73, v73, v74
	v_mul_f32_e32 v74, v65, v65
	v_fmac_f32_e32 v74, v64, v64
	v_add_f32_e32 v73, v73, v74
	v_mul_f32_e32 v74, v67, v67
	v_fmac_f32_e32 v74, v66, v66
	v_add_f32_e32 v73, v74, v73
	v_add_f32_e32 v74, v72, v73
	v_mov_b32_e32 v75, v74
	s_nop 1
	v_permlane16_swap_b32_e32 v75, v74
	v_add_u32_e32 v80, 48, v142
	v_ashrrev_i32_e32 v81, 31, v80
	v_lshlrev_b64 v[86:87], 11, v[80:81]
	v_lshl_add_u64 v[72:73], s[40:41], 0, v[86:87]
	v_lshl_add_u64 v[76:77], v[140:141], 1, v[72:73]
	v_cvt_pk_bf16_f32 v72, v68, v69
	s_waitcnt lgkmcnt(0)
	v_add_f32_e32 v68, v74, v75
	v_mov_b32_e32 v69, v68
	s_nop 1
	v_permlane32_swap_b32_e32 v69, v68
	v_cvt_pk_bf16_f32 v83, v78, v79
	global_store_dwordx4 v[76:77], v[82:85], off
	v_cvt_pk_bf16_f32 v73, v70, v71
	v_cvt_pk_bf16_f32 v74, v64, v65
	v_cvt_pk_bf16_f32 v75, v66, v67
	global_store_dwordx4 v[76:77], v[72:75], off offset:256
	s_and_saveexec_b64 s[0:1], vcc
	s_cbranch_execz .LBB0_623
	s_waitcnt lgkmcnt(0)
	v_add_f32_e32 v66, v68, v69
	v_lshl_add_u64 v[64:65], v[80:81], 2, s[14:15]
	global_atomic_add_f32 v[64:65], v66, off
.LBB0_623:
	s_or_b64 exec, exec, s[0:1]
	v_cvt_pk_bf16_f32 v66, v60, v61
	v_mul_f32_e32 v61, v61, v61
	v_fmac_f32_e32 v61, v60, v60
	v_mul_f32_e32 v60, v63, v63
	v_cvt_pk_bf16_f32 v68, v56, v57
	v_fmac_f32_e32 v60, v62, v62
	v_mul_f32_e32 v57, v57, v57
	v_add_f32_e32 v60, v61, v60
	v_fmac_f32_e32 v57, v56, v56
	v_add_f32_e32 v56, v60, v57
	v_mul_f32_e32 v57, v59, v59
	v_fmac_f32_e32 v57, v58, v58
	s_waitcnt lgkmcnt(0)
	v_cvt_pk_bf16_f32 v69, v58, v59
	v_add_f32_e32 v56, v57, v56
	v_mul_f32_e32 v57, v53, v53
	v_mul_f32_e32 v58, v55, v55
	v_fmac_f32_e32 v57, v52, v52
	v_fmac_f32_e32 v58, v54, v54
	v_add_f32_e32 v57, v57, v58
	v_mul_f32_e32 v58, v49, v49
	v_fmac_f32_e32 v58, v48, v48
	v_add_f32_e32 v57, v57, v58
	v_mul_f32_e32 v58, v51, v51
	v_fmac_f32_e32 v58, v50, v50
	v_add_f32_e32 v57, v58, v57
	v_add_f32_e32 v58, v56, v57
	v_mov_b32_e32 v59, v58
	s_nop 1
	v_permlane16_swap_b32_e32 v59, v58
	v_add_u32_e32 v64, 0x80, v142
	v_ashrrev_i32_e32 v65, 31, v64
	v_lshlrev_b64 v[70:71], 11, v[64:65]
	v_lshl_add_u64 v[56:57], s[40:41], 0, v[70:71]
	v_lshl_add_u64 v[60:61], v[140:141], 1, v[56:57]
	v_cvt_pk_bf16_f32 v56, v52, v53
	s_waitcnt lgkmcnt(0)
	v_add_f32_e32 v52, v58, v59
	v_mov_b32_e32 v53, v52
	s_nop 1
	v_permlane32_swap_b32_e32 v53, v52
	v_cvt_pk_bf16_f32 v67, v62, v63
	global_store_dwordx4 v[60:61], v[66:69], off
	v_cvt_pk_bf16_f32 v57, v54, v55
	v_cvt_pk_bf16_f32 v58, v48, v49
	v_cvt_pk_bf16_f32 v59, v50, v51
	global_store_dwordx4 v[60:61], v[56:59], off offset:256
	s_and_saveexec_b64 s[0:1], vcc
	s_cbranch_execz .LBB0_625
	s_waitcnt lgkmcnt(0)
	v_add_f32_e32 v50, v52, v53
	v_lshl_add_u64 v[48:49], v[64:65], 2, s[14:15]
	global_atomic_add_f32 v[48:49], v50, off
; #define EPI_IT_ROW(it) EPI_ROW((it) >> 2, (it) & 3)
; #define EPI_PACK8(v0, v1) (u32x4){pk2((v0)[0], (v0)[1]), pk2((v0)[2], (v0)[3]), pk2((v1)[0], (v1)[1]), pk2((v1)[2], (v1)[3])}
;     __device__ __forceinline__ void operator()(AccRef acc, const Unit& u, int wr, int wc, int fr, int fq) const {
;         asm volatile("" : "+v"(fr), "+v"(fq));
; #pragma unroll
;         for (int it = 0; it < 8; ++it) { const int ai = it >> 2, m = it & 3, row = EPI_IT_ROW(it); float q = 0.f;
; #pragma unroll
;             for (int bj = 0; bj < 2; ++bj) { const f32x4 x0 = acc[ai][bj][m][0], x1 = acc[ai][bj][m][1];
;                 *(u32x4*)(O + (size_t)row * DM + EPI_COL(bj)) = EPI_PACK8(x0, x1);
;                 q += EPI_SQ8(x0, x1); }
;             q += __shfl_xor(q, 16); q += __shfl_xor(q, 32);
;             if (fq == 0) atomicAdd(ssout + row, q); }
.LBB0_625:
	s_or_b64 exec, exec, s[0:1]
	v_cvt_pk_bf16_f32 v50, v44, v45
	v_mul_f32_e32 v45, v45, v45
	v_fmac_f32_e32 v45, v44, v44
	v_mul_f32_e32 v44, v47, v47
	v_cvt_pk_bf16_f32 v52, v40, v41
	v_fmac_f32_e32 v44, v46, v46
	v_mul_f32_e32 v41, v41, v41
	v_add_f32_e32 v44, v45, v44
	v_fmac_f32_e32 v41, v40, v40
	v_add_f32_e32 v40, v44, v41
	v_mul_f32_e32 v41, v43, v43
	v_fmac_f32_e32 v41, v42, v42
	s_waitcnt lgkmcnt(0)
	v_cvt_pk_bf16_f32 v53, v42, v43
	v_add_f32_e32 v40, v41, v40
	v_mul_f32_e32 v41, v37, v37
	v_mul_f32_e32 v42, v39, v39
	v_fmac_f32_e32 v41, v36, v36
	v_fmac_f32_e32 v42, v38, v38
	v_add_f32_e32 v41, v41, v42
	v_mul_f32_e32 v42, v33, v33
	v_fmac_f32_e32 v42, v32, v32
	v_add_f32_e32 v41, v41, v42
	v_mul_f32_e32 v42, v35, v35
	v_fmac_f32_e32 v42, v34, v34
	v_add_f32_e32 v41, v42, v41
	v_add_f32_e32 v42, v40, v41
	v_mov_b32_e32 v43, v42
	s_nop 1
	v_permlane16_swap_b32_e32 v43, v42
	v_add_u32_e32 v48, 0x90, v142
	v_ashrrev_i32_e32 v49, 31, v48
	v_lshlrev_b64 v[54:55], 11, v[48:49]
	v_lshl_add_u64 v[40:41], s[40:41], 0, v[54:55]
	v_lshl_add_u64 v[44:45], v[140:141], 1, v[40:41]
	v_cvt_pk_bf16_f32 v40, v36, v37
	s_waitcnt lgkmcnt(0)
	v_add_f32_e32 v36, v42, v43
	v_mov_b32_e32 v37, v36
	s_nop 1
	v_permlane32_swap_b32_e32 v37, v36
	v_cvt_pk_bf16_f32 v51, v46, v47
	global_store_dwordx4 v[44:45], v[50:53], off
	v_cvt_pk_bf16_f32 v41, v38, v39
	v_cvt_pk_bf16_f32 v42, v32, v33
	v_cvt_pk_bf16_f32 v43, v34, v35
	global_store_dwordx4 v[44:45], v[40:43], off offset:256
	s_and_saveexec_b64 s[0:1], vcc
	s_cbranch_execz .LBB0_627
	s_waitcnt lgkmcnt(0)
	v_add_f32_e32 v34, v36, v37
	v_lshl_add_u64 v[32:33], v[48:49], 2, s[14:15]
	global_atomic_add_f32 v[32:33], v34, off
.LBB0_627:
	s_or_b64 exec, exec, s[0:1]
	v_cvt_pk_bf16_f32 v34, v28, v29
	v_mul_f32_e32 v29, v29, v29
	v_fmac_f32_e32 v29, v28, v28
	v_mul_f32_e32 v28, v31, v31
	v_cvt_pk_bf16_f32 v36, v24, v25
	v_fmac_f32_e32 v28, v30, v30
	v_mul_f32_e32 v25, v25, v25
	v_add_f32_e32 v28, v29, v28
	v_fmac_f32_e32 v25, v24, v24
	v_add_f32_e32 v24, v28, v25
	v_mul_f32_e32 v25, v27, v27
	v_fmac_f32_e32 v25, v26, v26
	s_waitcnt lgkmcnt(0)
	v_cvt_pk_bf16_f32 v37, v26, v27
	v_add_f32_e32 v24, v25, v24
	v_mul_f32_e32 v25, v21, v21
	v_mul_f32_e32 v26, v23, v23
	v_fmac_f32_e32 v25, v20, v20
	v_fmac_f32_e32 v26, v22, v22
	v_add_f32_e32 v25, v25, v26
	v_mul_f32_e32 v26, v17, v17
	v_fmac_f32_e32 v26, v16, v16
	v_add_f32_e32 v25, v25, v26
	v_mul_f32_e32 v26, v19, v19
	v_fmac_f32_e32 v26, v18, v18
	v_add_f32_e32 v25, v26, v25
	v_add_f32_e32 v26, v24, v25
	v_mov_b32_e32 v27, v26
	s_nop 1
	v_permlane16_swap_b32_e32 v27, v26
	v_add_u32_e32 v32, 0xa0, v142
	v_ashrrev_i32_e32 v33, 31, v32
	v_lshlrev_b64 v[38:39], 11, v[32:33]
	v_lshl_add_u64 v[24:25], s[40:41], 0, v[38:39]
	v_lshl_add_u64 v[28:29], v[140:141], 1, v[24:25]
	v_cvt_pk_bf16_f32 v24, v20, v21
	s_waitcnt lgkmcnt(0)
	v_add_f32_e32 v20, v26, v27
	v_mov_b32_e32 v21, v20
	s_nop 1
	v_permlane32_swap_b32_e32 v21, v20
	v_cvt_pk_bf16_f32 v35, v30, v31
	global_store_dwordx4 v[28:29], v[34:37], off
	v_cvt_pk_bf16_f32 v25, v22, v23
	v_cvt_pk_bf16_f32 v26, v16, v17
	v_cvt_pk_bf16_f32 v27, v18, v19
	global_store_dwordx4 v[28:29], v[24:27], off offset:256
	s_and_saveexec_b64 s[0:1], vcc
	s_cbranch_execz .LBB0_629
	s_waitcnt lgkmcnt(0)
	v_add_f32_e32 v18, v20, v21
	v_lshl_add_u64 v[16:17], v[32:33], 2, s[14:15]
	global_atomic_add_f32 v[16:17], v18, off
.LBB0_629:
	s_or_b64 exec, exec, s[0:1]
	v_cvt_pk_bf16_f32 v18, v12, v13
	v_mul_f32_e32 v13, v13, v13
	v_fmac_f32_e32 v13, v12, v12
	v_mul_f32_e32 v12, v15, v15
	v_cvt_pk_bf16_f32 v20, v8, v9
	v_fmac_f32_e32 v12, v14, v14
	v_mul_f32_e32 v9, v9, v9
	v_add_f32_e32 v12, v13, v12
	v_fmac_f32_e32 v9, v8, v8
	v_add_f32_e32 v8, v12, v9
	v_mul_f32_e32 v9, v11, v11
	v_fmac_f32_e32 v9, v10, v10
	s_waitcnt lgkmcnt(0)
	v_cvt_pk_bf16_f32 v21, v10, v11
	v_add_f32_e32 v8, v9, v8
	v_mul_f32_e32 v9, v5, v5
	v_mul_f32_e32 v10, v7, v7
	v_fmac_f32_e32 v9, v4, v4
	v_fmac_f32_e32 v10, v6, v6
	v_add_f32_e32 v9, v9, v10
	v_mul_f32_e32 v10, v1, v1
	v_fmac_f32_e32 v10, v0, v0
	v_add_f32_e32 v9, v9, v10
	v_mul_f32_e32 v10, v3, v3
	v_fmac_f32_e32 v10, v2, v2
	v_add_f32_e32 v9, v10, v9
	v_add_f32_e32 v10, v8, v9
	v_mov_b32_e32 v11, v10
	s_nop 1
	v_permlane16_swap_b32_e32 v11, v10
	v_add_u32_e32 v16, 0xb0, v142
	v_ashrrev_i32_e32 v17, 31, v16
	v_lshlrev_b64 v[22:23], 11, v[16:17]
	v_lshl_add_u64 v[8:9], s[40:41], 0, v[22:23]
	v_lshl_add_u64 v[12:13], v[140:141], 1, v[8:9]
	v_cvt_pk_bf16_f32 v8, v4, v5
	s_waitcnt lgkmcnt(0)
	v_add_f32_e32 v4, v10, v11
	v_mov_b32_e32 v5, v4
	s_nop 1
	v_permlane32_swap_b32_e32 v5, v4
	v_cvt_pk_bf16_f32 v19, v14, v15
	global_store_dwordx4 v[12:13], v[18:21], off
	v_cvt_pk_bf16_f32 v9, v6, v7
	v_cvt_pk_bf16_f32 v10, v0, v1
	v_cvt_pk_bf16_f32 v11, v2, v3
	global_store_dwordx4 v[12:13], v[8:11], off offset:256
	s_and_saveexec_b64 s[0:1], vcc
	s_cbranch_execz .LBB0_631
	s_waitcnt lgkmcnt(0)
	v_add_f32_e32 v2, v4, v5
	v_lshl_add_u64 v[0:1], v[16:17], 2, s[14:15]
	global_atomic_add_f32 v[0:1], v2, off

; #define EPI_IT_ROW(it) EPI_ROW((it) >> 2, (it) & 3)
; #define EPI_PACK8(v0, v1) (u32x4){pk2((v0)[0], (v0)[1]), pk2((v0)[2], (v0)[3]), pk2((v1)[0], (v1)[1]), pk2((v1)[2], (v1)[3])}
;     __device__ __forceinline__ void operator()(AccRef acc, const Unit& u, int wr, int wc, int fr, int fq) const {
;         asm volatile("" : "+v"(fr), "+v"(fq));
;         f32x4 xc[2][2], xn[2][2];
; #pragma unroll
;         for (int bj = 0; bj < 2; ++bj) { const size_t p = (size_t)EPI_IT_ROW(0) * DM + EPI_COL(bj); xc[bj][0] = *(const f32x4*)(xin + p); xc[bj][1] = *(const f32x4*)(xin + p + 4); }
; #pragma unroll
;         for (int it = 0; it < 8; ++it) { const int ai = it >> 2, m = it & 3, row = EPI_IT_ROW(it);
;             if (it + 1 < 8) {
; #pragma unroll
;                 for (int bj = 0; bj < 2; ++bj) { const size_t p = (size_t)EPI_IT_ROW(it + 1) * DM + EPI_COL(bj); xn[bj][0] = *(const f32x4*)(xin + p); xn[bj][1] = *(const f32x4*)(xin + p + 4); } }
;             float q = 0.f;
; #pragma unroll
;             for (int bj = 0; bj < 2; ++bj) { const size_t p = (size_t)row * DM + EPI_COL(bj);
;                 const f32x4 x0 = xc[bj][0] + acc[ai][bj][m][0], x1 = xc[bj][1] + acc[ai][bj][m][1];
;                 __builtin_nontemporal_store(x0, (f32x4*)(xout + p)); __builtin_nontemporal_store(x1, (f32x4*)(xout + p + 4));
;                 *(u32x4*)(xb + p) = EPI_PACK8(x0, x1);
;                 q += EPI_SQ8(x0, x1); }
;             q += __shfl_xor(q, 16); q += __shfl_xor(q, 32);
;             if (fq == 0) atomicAdd(ssout + row, q);
; #pragma unroll
;             for (int bj = 0; bj < 2; ++bj) { xc[bj][0] = xn[bj][0]; xc[bj][1] = xn[bj][1]; } }
;     }
.LBB0_795:
	s_lshl_b32 s0, s74, 8
	v_mov_b32_e32 v128, v180
	v_mov_b32_e32 v186, v177
	s_add_i32 s0, s0, s56
	v_and_b32_e32 v202, 64, v185
	v_add_u32_e32 v164, s0, v128
	s_lshl_b32 s0, s73, 8
	s_or_b32 s0, s0, s57
	v_ashrrev_i32_e32 v165, 31, v164
	v_lshl_add_u32 v162, v186, 3, s0
	v_lshlrev_b64 v[128:129], 12, v[164:165]
	v_ashrrev_i32_e32 v163, 31, v162
	v_add_u32_e32 v160, 0x80, v162
	v_lshl_add_u64 v[128:129], s[48:49], 0, v[128:129]
	v_lshlrev_b64 v[130:131], 2, v[162:163]
	v_ashrrev_i32_e32 v161, 31, v160
	v_lshl_add_u64 v[178:179], v[128:129], 0, v[130:131]
	v_lshlrev_b64 v[132:133], 2, v[160:161]
	global_load_dwordx4 v[170:173], v[178:179], off offset:16
	global_load_dwordx4 v[188:191], v[178:179], off
	v_lshl_add_u64 v[200:201], v[128:129], 0, v[132:133]
	global_load_dwordx4 v[192:195], v[200:201], off
	global_load_dwordx4 v[196:199], v[200:201], off offset:16
	v_add_u32_e32 v166, 16, v164
	v_ashrrev_i32_e32 v167, 31, v166
	v_lshlrev_b64 v[128:129], 12, v[166:167]
	v_lshl_add_u64 v[128:129], s[48:49], 0, v[128:129]
	v_lshl_add_u64 v[174:175], v[128:129], 0, v[130:131]
	v_lshl_add_u64 v[168:169], v[128:129], 0, v[132:133]
	global_load_dwordx4 v[136:139], v[174:175], off offset:16
	global_load_dwordx4 v[140:143], v[174:175], off
	global_load_dwordx4 v[128:131], v[168:169], off offset:16
	global_load_dwordx4 v[132:135], v[168:169], off
	v_xor_b32_e32 v187, 16, v185
	v_add_u32_e32 v202, 64, v202
	v_cmp_lt_i32_e64 s[0:1], v187, v202
	v_cmp_eq_u32_e32 vcc, 0, v186
	v_xor_b32_e32 v203, 32, v185
	v_cndmask_b32_e64 v186, v185, v187, s[0:1]
	v_lshlrev_b32_e32 v186, 2, v186
	v_cmp_lt_i32_e64 s[0:1], v203, v202
	s_waitcnt vmcnt(0)
	v_pk_add_f32 v[122:123], v[122:123], v[172:173]
	v_pk_add_f32 v[126:127], v[126:127], v[190:191]
	v_pk_add_f32 v[124:125], v[124:125], v[188:189]
	v_pk_add_f32 v[118:119], v[118:119], v[194:195]
	v_pk_add_f32 v[116:117], v[116:117], v[192:193]
	v_pk_add_f32 v[120:121], v[120:121], v[170:171]
	v_pk_add_f32 v[170:171], v[112:113], v[196:197]
	global_store_dwordx4 v[178:179], v[124:127], off nt
	global_store_dwordx4 v[178:179], v[120:123], off offset:16 nt
	v_cvt_pk_bf16_f32 v112, v124, v125
	v_cvt_pk_bf16_f32 v113, v126, v127
	v_mul_f32_e32 v178, v117, v117
	v_mul_f32_e32 v125, v125, v125
	v_mul_f32_e32 v127, v127, v127
	v_mul_f32_e32 v179, v119, v119
	v_pk_add_f32 v[172:173], v[114:115], v[198:199]
	v_cvt_pk_bf16_f32 v114, v120, v121
	v_cvt_pk_bf16_f32 v115, v122, v123
	v_mul_f32_e32 v121, v121, v121
	v_mul_f32_e32 v123, v123, v123
	v_mul_f32_e32 v189, v171, v171
	v_fmac_f32_e32 v125, v124, v124
	v_fmac_f32_e32 v127, v126, v126
	v_fmac_f32_e32 v178, v116, v116
	v_fmac_f32_e32 v179, v118, v118
	v_mul_f32_e32 v190, v173, v173
	v_fmac_f32_e32 v121, v120, v120
	v_fmac_f32_e32 v123, v122, v122
	v_fmac_f32_e32 v189, v170, v170
	v_add_f32_e32 v120, v125, v127
	v_add_f32_e32 v122, v178, v179
	v_fmac_f32_e32 v190, v172, v172
	v_add_f32_e32 v120, v120, v121
	v_add_f32_e32 v121, v122, v189
	v_add_f32_e32 v120, v123, v120
	v_add_f32_e32 v121, v190, v121
	v_add_f32_e32 v120, v120, v121
	v_mov_b32_e32 v121, v120
	s_nop 1
	v_permlane16_swap_b32_e32 v121, v120
	v_cndmask_b32_e64 v187, v185, v203, s[0:1]
	v_lshlrev_b64 v[202:203], 10, v[164:165]
	v_lshl_add_u64 v[204:205], v[202:203], 0, v[162:163]
	v_lshl_add_u64 v[204:205], v[204:205], 1, s[30:31]
	global_store_dwordx4 v[204:205], v[112:115], off
	global_store_dwordx4 v[200:201], v[116:119], off nt
	global_store_dwordx4 v[200:201], v[170:173], off offset:16 nt
	s_waitcnt lgkmcnt(0)
	v_add_f32_e32 v112, v120, v121
	v_lshlrev_b32_e32 v187, 2, v187
	v_mov_b32_e32 v113, v112
	s_nop 1
	v_permlane32_swap_b32_e32 v113, v112
	v_lshl_add_u64 v[202:203], v[202:203], 0, v[160:161]
	v_lshl_add_u64 v[114:115], v[202:203], 1, s[30:31]
	v_cvt_pk_bf16_f32 v188, v116, v117
	v_cvt_pk_bf16_f32 v189, v118, v119
	v_cvt_pk_bf16_f32 v190, v170, v171
	v_cvt_pk_bf16_f32 v191, v172, v173
	global_store_dwordx4 v[114:115], v[188:191], off
	s_and_saveexec_b64 s[0:1], vcc
	s_cbranch_execz .LBB0_797
	v_lshl_add_u64 v[114:115], v[164:165], 2, s[12:13]
	s_waitcnt lgkmcnt(0)
	v_add_f32_e32 v112, v112, v113
	global_atomic_add_f32 v[114:115], v112, off
.LBB0_797:
	s_or_b64 exec, exec, s[0:1]
	v_add_u32_e32 v170, 32, v164
	v_ashrrev_i32_e32 v171, 31, v170
	s_waitcnt lgkmcnt(0)
	v_lshlrev_b64 v[112:113], 12, v[170:171]
	v_lshl_add_u64 v[112:113], s[48:49], 0, v[112:113]
	v_lshl_add_u64 v[178:179], v[162:163], 2, v[112:113]
	v_lshl_add_u64 v[172:173], v[160:161], 2, v[112:113]
	global_load_dwordx4 v[120:123], v[178:179], off offset:16
	global_load_dwordx4 v[124:127], v[178:179], off
	global_load_dwordx4 v[112:115], v[172:173], off offset:16
	global_load_dwordx4 v[116:119], v[172:173], off
	v_pk_add_f32 v[110:111], v[110:111], v[142:143]
	v_pk_add_f32 v[108:109], v[108:109], v[140:141]
	v_pk_add_f32 v[106:107], v[106:107], v[138:139]
	v_pk_add_f32 v[104:105], v[104:105], v[136:137]
	global_store_dwordx4 v[174:175], v[108:111], off nt
	global_store_dwordx4 v[174:175], v[104:107], off offset:16 nt
	v_cvt_pk_bf16_f32 v136, v108, v109
	v_cvt_pk_bf16_f32 v138, v104, v105
	v_pk_add_f32 v[102:103], v[102:103], v[134:135]
	v_mul_f32_e32 v109, v109, v109
	v_fmac_f32_e32 v109, v108, v108
	v_mul_f32_e32 v108, v111, v111
	v_fmac_f32_e32 v108, v110, v110
	v_mul_f32_e32 v105, v105, v105
	v_add_f32_e32 v108, v109, v108
	v_fmac_f32_e32 v105, v104, v104
	v_add_f32_e32 v104, v108, v105
	v_mul_f32_e32 v105, v107, v107
	v_fmac_f32_e32 v105, v106, v106
	v_pk_add_f32 v[100:101], v[100:101], v[132:133]
	v_cvt_pk_bf16_f32 v137, v110, v111
	v_add_f32_e32 v110, v105, v104
	v_pk_add_f32 v[104:105], v[96:97], v[128:129]
	v_mul_f32_e32 v96, v101, v101
	v_mul_f32_e32 v97, v103, v103
	v_fmac_f32_e32 v96, v100, v100
	v_fmac_f32_e32 v97, v102, v102
	v_add_f32_e32 v96, v96, v97
	v_mul_f32_e32 v97, v105, v105
	v_cvt_pk_bf16_f32 v139, v106, v107
	v_pk_add_f32 v[106:107], v[98:99], v[130:131]
	v_fmac_f32_e32 v97, v104, v104
	v_add_f32_e32 v96, v96, v97
	v_mul_f32_e32 v97, v107, v107
	v_fmac_f32_e32 v97, v106, v106
	v_add_f32_e32 v96, v97, v96
	v_add_f32_e32 v96, v110, v96
	v_mov_b32_e32 v97, v96
	s_nop 1
	v_permlane16_swap_b32_e32 v97, v96
	v_lshlrev_b64 v[188:189], 10, v[166:167]
	v_lshl_add_u64 v[190:191], v[188:189], 0, v[162:163]
	v_lshl_add_u64 v[140:141], v[190:191], 1, s[30:31]
	v_lshl_add_u64 v[108:109], v[188:189], 0, v[160:161]
	s_waitcnt lgkmcnt(0)
	v_add_f32_e32 v96, v96, v97
	v_mov_b32_e32 v97, v96
	s_nop 1
	v_permlane32_swap_b32_e32 v97, v96
	global_store_dwordx4 v[140:141], v[136:139], off
	global_store_dwordx4 v[168:169], v[100:103], off nt
	global_store_dwordx4 v[168:169], v[104:107], off offset:16 nt
	v_cvt_pk_bf16_f32 v99, v102, v103
	v_cvt_pk_bf16_f32 v98, v100, v101
	s_nop 0
	v_lshl_add_u64 v[102:103], v[108:109], 1, s[30:31]
	v_cvt_pk_bf16_f32 v100, v104, v105
	v_cvt_pk_bf16_f32 v101, v106, v107
	global_store_dwordx4 v[102:103], v[98:101], off
	s_and_saveexec_b64 s[0:1], vcc
	s_cbranch_execz .LBB0_799
; #define EPI_IT_ROW(it) EPI_ROW((it) >> 2, (it) & 3)
; #define EPI_PACK8(v0, v1) (u32x4){pk2((v0)[0], (v0)[1]), pk2((v0)[2], (v0)[3]), pk2((v1)[0], (v1)[1]), pk2((v1)[2], (v1)[3])}
;     __device__ __forceinline__ void operator()(AccRef acc, const Unit& u, int wr, int wc, int fr, int fq) const {
;         asm volatile("" : "+v"(fr), "+v"(fq));
;         f32x4 xc[2][2], xn[2][2];
; #pragma unroll
;         for (int bj = 0; bj < 2; ++bj) { const size_t p = (size_t)EPI_IT_ROW(0) * DM + EPI_COL(bj); xc[bj][0] = *(const f32x4*)(xin + p); xc[bj][1] = *(const f32x4*)(xin + p + 4); }
; #pragma unroll
;         for (int it = 0; it < 8; ++it) { const int ai = it >> 2, m = it & 3, row = EPI_IT_ROW(it);
;             if (it + 1 < 8) {
; #pragma unroll
;                 for (int bj = 0; bj < 2; ++bj) { const size_t p = (size_t)EPI_IT_ROW(it + 1) * DM + EPI_COL(bj); xn[bj][0] = *(const f32x4*)(xin + p); xn[bj][1] = *(const f32x4*)(xin + p + 4); } }
;             float q = 0.f;
; #pragma unroll
;             for (int bj = 0; bj < 2; ++bj) { const size_t p = (size_t)row * DM + EPI_COL(bj);
;                 const f32x4 x0 = xc[bj][0] + acc[ai][bj][m][0], x1 = xc[bj][1] + acc[ai][bj][m][1];
;                 __builtin_nontemporal_store(x0, (f32x4*)(xout + p)); __builtin_nontemporal_store(x1, (f32x4*)(xout + p + 4));
;                 *(u32x4*)(xb + p) = EPI_PACK8(x0, x1);
;                 q += EPI_SQ8(x0, x1); }
;             q += __shfl_xor(q, 16); q += __shfl_xor(q, 32);
;             if (fq == 0) atomicAdd(ssout + row, q);
; #pragma unroll
;             for (int bj = 0; bj < 2; ++bj) { xc[bj][0] = xn[bj][0]; xc[bj][1] = xn[bj][1]; } }
;     }
	v_lshl_add_u64 v[98:99], v[166:167], 2, s[12:13]
	s_waitcnt lgkmcnt(0)
	v_add_f32_e32 v96, v96, v97
	global_atomic_add_f32 v[98:99], v96, off
.LBB0_799:
	s_or_b64 exec, exec, s[0:1]
	v_add_u32_e32 v128, 48, v164
	v_ashrrev_i32_e32 v129, 31, v128
	s_waitcnt lgkmcnt(0)
	v_lshlrev_b64 v[96:97], 12, v[128:129]
	v_lshl_add_u64 v[96:97], s[48:49], 0, v[96:97]
	v_lshl_add_u64 v[132:133], v[162:163], 2, v[96:97]
	v_lshl_add_u64 v[130:131], v[160:161], 2, v[96:97]
	global_load_dwordx4 v[104:107], v[132:133], off offset:16
	global_load_dwordx4 v[108:111], v[132:133], off
	global_load_dwordx4 v[96:99], v[130:131], off offset:16
	global_load_dwordx4 v[100:103], v[130:131], off
	s_waitcnt vmcnt(12)
	v_pk_add_f32 v[94:95], v[94:95], v[126:127]
	v_pk_add_f32 v[92:93], v[92:93], v[124:125]
	v_pk_add_f32 v[90:91], v[90:91], v[122:123]
	v_pk_add_f32 v[88:89], v[88:89], v[120:121]
	global_store_dwordx4 v[178:179], v[92:95], off nt
	global_store_dwordx4 v[178:179], v[88:91], off offset:16 nt
	v_cvt_pk_bf16_f32 v120, v92, v93
	v_cvt_pk_bf16_f32 v122, v88, v89
	s_waitcnt vmcnt(12)
	v_pk_add_f32 v[86:87], v[86:87], v[118:119]
	v_mul_f32_e32 v93, v93, v93
	v_fmac_f32_e32 v93, v92, v92
	v_mul_f32_e32 v92, v95, v95
	v_fmac_f32_e32 v92, v94, v94
	v_mul_f32_e32 v89, v89, v89
	v_add_f32_e32 v92, v93, v92
	v_fmac_f32_e32 v89, v88, v88
	v_add_f32_e32 v88, v92, v89
	v_mul_f32_e32 v89, v91, v91
	v_fmac_f32_e32 v89, v90, v90
	v_pk_add_f32 v[84:85], v[84:85], v[116:117]
	v_cvt_pk_bf16_f32 v121, v94, v95
	v_add_f32_e32 v94, v89, v88
	v_pk_add_f32 v[88:89], v[80:81], v[112:113]
	v_mul_f32_e32 v80, v85, v85
	v_mul_f32_e32 v81, v87, v87
	v_fmac_f32_e32 v80, v84, v84
	v_fmac_f32_e32 v81, v86, v86
	v_add_f32_e32 v80, v80, v81
	v_mul_f32_e32 v81, v89, v89
	v_cvt_pk_bf16_f32 v123, v90, v91
	v_pk_add_f32 v[90:91], v[82:83], v[114:115]
	v_fmac_f32_e32 v81, v88, v88
	v_add_f32_e32 v80, v80, v81
	v_mul_f32_e32 v81, v91, v91
	v_fmac_f32_e32 v81, v90, v90
	v_add_f32_e32 v80, v81, v80
	v_add_f32_e32 v80, v94, v80
	v_mov_b32_e32 v81, v80
	s_nop 1
	v_permlane16_swap_b32_e32 v81, v80
	v_lshlrev_b64 v[134:135], 10, v[170:171]
	v_lshl_add_u64 v[136:137], v[134:135], 0, v[162:163]
	v_lshl_add_u64 v[124:125], v[136:137], 1, s[30:31]
	v_lshl_add_u64 v[92:93], v[134:135], 0, v[160:161]
	s_waitcnt lgkmcnt(0)
	v_add_f32_e32 v80, v80, v81
	v_mov_b32_e32 v81, v80
	s_nop 1
	v_permlane32_swap_b32_e32 v81, v80
	global_store_dwordx4 v[124:125], v[120:123], off
	global_store_dwordx4 v[172:173], v[84:87], off nt
	global_store_dwordx4 v[172:173], v[88:91], off offset:16 nt
	v_cvt_pk_bf16_f32 v83, v86, v87
	v_cvt_pk_bf16_f32 v82, v84, v85
	s_nop 0
	v_lshl_add_u64 v[86:87], v[92:93], 1, s[30:31]
	v_cvt_pk_bf16_f32 v84, v88, v89
	v_cvt_pk_bf16_f32 v85, v90, v91
	global_store_dwordx4 v[86:87], v[82:85], off
	s_and_saveexec_b64 s[0:1], vcc
	s_cbranch_execz .LBB0_801
	v_lshl_add_u64 v[82:83], v[170:171], 2, s[12:13]
	s_waitcnt lgkmcnt(0)
	v_add_f32_e32 v80, v80, v81
	global_atomic_add_f32 v[82:83], v80, off
.LBB0_801:
	s_or_b64 exec, exec, s[0:1]
	v_add_u32_e32 v112, 0x80, v164
	v_ashrrev_i32_e32 v113, 31, v112
	s_waitcnt lgkmcnt(0)
	v_lshlrev_b64 v[80:81], 12, v[112:113]
	v_lshl_add_u64 v[80:81], s[48:49], 0, v[80:81]
	v_lshl_add_u64 v[116:117], v[162:163], 2, v[80:81]
	v_lshl_add_u64 v[114:115], v[160:161], 2, v[80:81]
	global_load_dwordx4 v[88:91], v[116:117], off offset:16
	global_load_dwordx4 v[92:95], v[116:117], off
	global_load_dwordx4 v[80:83], v[114:115], off offset:16
	global_load_dwordx4 v[84:87], v[114:115], off
	s_waitcnt vmcnt(12)
	v_pk_add_f32 v[78:79], v[78:79], v[110:111]
	v_pk_add_f32 v[76:77], v[76:77], v[108:109]
	v_pk_add_f32 v[74:75], v[74:75], v[106:107]
	v_pk_add_f32 v[72:73], v[72:73], v[104:105]
	global_store_dwordx4 v[132:133], v[76:79], off nt
	global_store_dwordx4 v[132:133], v[72:75], off offset:16 nt
	v_cvt_pk_bf16_f32 v104, v76, v77
	v_cvt_pk_bf16_f32 v106, v72, v73
	s_waitcnt vmcnt(12)
	v_pk_add_f32 v[70:71], v[70:71], v[102:103]
	v_mul_f32_e32 v77, v77, v77
	v_fmac_f32_e32 v77, v76, v76
	v_mul_f32_e32 v76, v79, v79
	v_fmac_f32_e32 v76, v78, v78
	v_mul_f32_e32 v73, v73, v73
	v_add_f32_e32 v76, v77, v76
	v_fmac_f32_e32 v73, v72, v72
	v_add_f32_e32 v72, v76, v73
	v_mul_f32_e32 v73, v75, v75
	v_fmac_f32_e32 v73, v74, v74
	v_pk_add_f32 v[68:69], v[68:69], v[100:101]
	v_cvt_pk_bf16_f32 v105, v78, v79
	v_add_f32_e32 v78, v73, v72
	v_pk_add_f32 v[72:73], v[64:65], v[96:97]
	v_mul_f32_e32 v64, v69, v69
	v_mul_f32_e32 v65, v71, v71
	v_fmac_f32_e32 v64, v68, v68
	v_fmac_f32_e32 v65, v70, v70
	v_add_f32_e32 v64, v64, v65
	v_mul_f32_e32 v65, v73, v73
	v_cvt_pk_bf16_f32 v107, v74, v75
	v_pk_add_f32 v[74:75], v[66:67], v[98:99]
	v_fmac_f32_e32 v65, v72, v72
	v_add_f32_e32 v64, v64, v65
	v_mul_f32_e32 v65, v75, v75
	v_fmac_f32_e32 v65, v74, v74
	v_add_f32_e32 v64, v65, v64
	v_add_f32_e32 v64, v78, v64
	v_mov_b32_e32 v65, v64
	s_nop 1
	v_permlane16_swap_b32_e32 v65, v64
	v_lshlrev_b64 v[118:119], 10, v[128:129]
	v_lshl_add_u64 v[120:121], v[118:119], 0, v[162:163]
	v_lshl_add_u64 v[108:109], v[120:121], 1, s[30:31]
	v_lshl_add_u64 v[76:77], v[118:119], 0, v[160:161]
	s_waitcnt lgkmcnt(0)
	v_add_f32_e32 v64, v64, v65
	v_mov_b32_e32 v65, v64
	s_nop 1
	v_permlane32_swap_b32_e32 v65, v64
	global_store_dwordx4 v[108:109], v[104:107], off
	global_store_dwordx4 v[130:131], v[68:71], off nt
	global_store_dwordx4 v[130:131], v[72:75], off offset:16 nt
	v_cvt_pk_bf16_f32 v67, v70, v71
	v_cvt_pk_bf16_f32 v66, v68, v69
	s_nop 0
	v_lshl_add_u64 v[70:71], v[76:77], 1, s[30:31]
	v_cvt_pk_bf16_f32 v68, v72, v73
	v_cvt_pk_bf16_f32 v69, v74, v75
	global_store_dwordx4 v[70:71], v[66:69], off
	s_and_saveexec_b64 s[0:1], vcc
	s_cbranch_execz .LBB0_803
	v_lshl_add_u64 v[66:67], v[128:129], 2, s[12:13]
	s_waitcnt lgkmcnt(0)
	v_add_f32_e32 v64, v64, v65
	global_atomic_add_f32 v[66:67], v64, off
; #define EPI_IT_ROW(it) EPI_ROW((it) >> 2, (it) & 3)
; #define EPI_PACK8(v0, v1) (u32x4){pk2((v0)[0], (v0)[1]), pk2((v0)[2], (v0)[3]), pk2((v1)[0], (v1)[1]), pk2((v1)[2], (v1)[3])}
;     __device__ __forceinline__ void operator()(AccRef acc, const Unit& u, int wr, int wc, int fr, int fq) const {
;         asm volatile("" : "+v"(fr), "+v"(fq));
;         f32x4 xc[2][2], xn[2][2];
; #pragma unroll
;         for (int bj = 0; bj < 2; ++bj) { const size_t p = (size_t)EPI_IT_ROW(0) * DM + EPI_COL(bj); xc[bj][0] = *(const f32x4*)(xin + p); xc[bj][1] = *(const f32x4*)(xin + p + 4); }
; #pragma unroll
;         for (int it = 0; it < 8; ++it) { const int ai = it >> 2, m = it & 3, row = EPI_IT_ROW(it);
;             if (it + 1 < 8) {
; #pragma unroll
;                 for (int bj = 0; bj < 2; ++bj) { const size_t p = (size_t)EPI_IT_ROW(it + 1) * DM + EPI_COL(bj); xn[bj][0] = *(const f32x4*)(xin + p); xn[bj][1] = *(const f32x4*)(xin + p + 4); } }
;             float q = 0.f;
; #pragma unroll
;             for (int bj = 0; bj < 2; ++bj) { const size_t p = (size_t)row * DM + EPI_COL(bj);
;                 const f32x4 x0 = xc[bj][0] + acc[ai][bj][m][0], x1 = xc[bj][1] + acc[ai][bj][m][1];
;                 __builtin_nontemporal_store(x0, (f32x4*)(xout + p)); __builtin_nontemporal_store(x1, (f32x4*)(xout + p + 4));
;                 *(u32x4*)(xb + p) = EPI_PACK8(x0, x1);
;                 q += EPI_SQ8(x0, x1); }
;             q += __shfl_xor(q, 16); q += __shfl_xor(q, 32);
;             if (fq == 0) atomicAdd(ssout + row, q);
; #pragma unroll
;             for (int bj = 0; bj < 2; ++bj) { xc[bj][0] = xn[bj][0]; xc[bj][1] = xn[bj][1]; } }
;     }
.LBB0_803:
	s_or_b64 exec, exec, s[0:1]
	v_add_u32_e32 v96, 0x90, v164
	v_ashrrev_i32_e32 v97, 31, v96
	s_waitcnt lgkmcnt(0)
	v_lshlrev_b64 v[64:65], 12, v[96:97]
	v_lshl_add_u64 v[64:65], s[48:49], 0, v[64:65]
	v_lshl_add_u64 v[100:101], v[162:163], 2, v[64:65]
	v_lshl_add_u64 v[98:99], v[160:161], 2, v[64:65]
	global_load_dwordx4 v[72:75], v[100:101], off offset:16
	global_load_dwordx4 v[76:79], v[100:101], off
	global_load_dwordx4 v[64:67], v[98:99], off offset:16
	global_load_dwordx4 v[68:71], v[98:99], off
	s_waitcnt vmcnt(12)
	v_pk_add_f32 v[62:63], v[62:63], v[94:95]
	v_pk_add_f32 v[60:61], v[60:61], v[92:93]
	v_pk_add_f32 v[58:59], v[58:59], v[90:91]
	v_pk_add_f32 v[56:57], v[56:57], v[88:89]
	global_store_dwordx4 v[116:117], v[60:63], off nt
	global_store_dwordx4 v[116:117], v[56:59], off offset:16 nt
	v_cvt_pk_bf16_f32 v88, v60, v61
	v_cvt_pk_bf16_f32 v90, v56, v57
	s_waitcnt vmcnt(12)
	v_pk_add_f32 v[54:55], v[54:55], v[86:87]
	v_mul_f32_e32 v61, v61, v61
	v_fmac_f32_e32 v61, v60, v60
	v_mul_f32_e32 v60, v63, v63
	v_fmac_f32_e32 v60, v62, v62
	v_mul_f32_e32 v57, v57, v57
	v_add_f32_e32 v60, v61, v60
	v_fmac_f32_e32 v57, v56, v56
	v_add_f32_e32 v56, v60, v57
	v_mul_f32_e32 v57, v59, v59
	v_fmac_f32_e32 v57, v58, v58
	v_pk_add_f32 v[52:53], v[52:53], v[84:85]
	v_cvt_pk_bf16_f32 v89, v62, v63
	v_add_f32_e32 v62, v57, v56
	v_pk_add_f32 v[56:57], v[48:49], v[80:81]
	v_mul_f32_e32 v48, v53, v53
	v_mul_f32_e32 v49, v55, v55
	v_fmac_f32_e32 v48, v52, v52
	v_fmac_f32_e32 v49, v54, v54
	v_add_f32_e32 v48, v48, v49
	v_mul_f32_e32 v49, v57, v57
	v_cvt_pk_bf16_f32 v91, v58, v59
	v_pk_add_f32 v[58:59], v[50:51], v[82:83]
	v_fmac_f32_e32 v49, v56, v56
	v_add_f32_e32 v48, v48, v49
	v_mul_f32_e32 v49, v59, v59
	v_fmac_f32_e32 v49, v58, v58
	v_add_f32_e32 v48, v49, v48
	v_add_f32_e32 v48, v62, v48
	v_mov_b32_e32 v49, v48
	s_nop 1
	v_permlane16_swap_b32_e32 v49, v48
	v_lshlrev_b64 v[102:103], 10, v[112:113]
	v_lshl_add_u64 v[104:105], v[102:103], 0, v[162:163]
	v_lshl_add_u64 v[92:93], v[104:105], 1, s[30:31]
	v_lshl_add_u64 v[60:61], v[102:103], 0, v[160:161]
	s_waitcnt lgkmcnt(0)
	v_add_f32_e32 v48, v48, v49
	v_mov_b32_e32 v49, v48
	s_nop 1
	v_permlane32_swap_b32_e32 v49, v48
	global_store_dwordx4 v[92:93], v[88:91], off
	global_store_dwordx4 v[114:115], v[52:55], off nt
	global_store_dwordx4 v[114:115], v[56:59], off offset:16 nt
	v_cvt_pk_bf16_f32 v51, v54, v55
	v_cvt_pk_bf16_f32 v50, v52, v53
	s_nop 0
	v_lshl_add_u64 v[54:55], v[60:61], 1, s[30:31]
	v_cvt_pk_bf16_f32 v52, v56, v57
	v_cvt_pk_bf16_f32 v53, v58, v59
	global_store_dwordx4 v[54:55], v[50:53], off
	s_and_saveexec_b64 s[0:1], vcc
	s_cbranch_execz .LBB0_805
	v_lshl_add_u64 v[50:51], v[112:113], 2, s[12:13]
	s_waitcnt lgkmcnt(0)
	v_add_f32_e32 v48, v48, v49
	global_atomic_add_f32 v[50:51], v48, off
.LBB0_805:
	s_or_b64 exec, exec, s[0:1]
	v_add_u32_e32 v80, 0xa0, v164
	v_ashrrev_i32_e32 v81, 31, v80
	s_waitcnt lgkmcnt(0)
	v_lshlrev_b64 v[48:49], 12, v[80:81]
	v_lshl_add_u64 v[48:49], s[48:49], 0, v[48:49]
	v_lshl_add_u64 v[84:85], v[162:163], 2, v[48:49]
	v_lshl_add_u64 v[82:83], v[160:161], 2, v[48:49]
	global_load_dwordx4 v[56:59], v[84:85], off offset:16
	global_load_dwordx4 v[60:63], v[84:85], off
	global_load_dwordx4 v[48:51], v[82:83], off offset:16
	global_load_dwordx4 v[52:55], v[82:83], off
	s_waitcnt vmcnt(12)
	v_pk_add_f32 v[46:47], v[46:47], v[78:79]
	v_pk_add_f32 v[44:45], v[44:45], v[76:77]
	v_pk_add_f32 v[42:43], v[42:43], v[74:75]
	v_pk_add_f32 v[40:41], v[40:41], v[72:73]
	global_store_dwordx4 v[100:101], v[44:47], off nt
	global_store_dwordx4 v[100:101], v[40:43], off offset:16 nt
	v_cvt_pk_bf16_f32 v72, v44, v45
	v_cvt_pk_bf16_f32 v74, v40, v41
	s_waitcnt vmcnt(12)
	v_pk_add_f32 v[38:39], v[38:39], v[70:71]
	v_mul_f32_e32 v45, v45, v45
	v_fmac_f32_e32 v45, v44, v44
	v_mul_f32_e32 v44, v47, v47
	v_fmac_f32_e32 v44, v46, v46
	v_mul_f32_e32 v41, v41, v41
	v_add_f32_e32 v44, v45, v44
	v_fmac_f32_e32 v41, v40, v40
	v_add_f32_e32 v40, v44, v41
	v_mul_f32_e32 v41, v43, v43
	v_fmac_f32_e32 v41, v42, v42
	v_pk_add_f32 v[36:37], v[36:37], v[68:69]
	v_cvt_pk_bf16_f32 v73, v46, v47
	v_add_f32_e32 v46, v41, v40
	v_pk_add_f32 v[40:41], v[32:33], v[64:65]
	v_mul_f32_e32 v32, v37, v37
	v_mul_f32_e32 v33, v39, v39
	v_fmac_f32_e32 v32, v36, v36
	v_fmac_f32_e32 v33, v38, v38
	v_add_f32_e32 v32, v32, v33
	v_mul_f32_e32 v33, v41, v41
	v_cvt_pk_bf16_f32 v75, v42, v43
	v_pk_add_f32 v[42:43], v[34:35], v[66:67]
	v_fmac_f32_e32 v33, v40, v40
	v_add_f32_e32 v32, v32, v33
	v_mul_f32_e32 v33, v43, v43
	v_fmac_f32_e32 v33, v42, v42
	v_add_f32_e32 v32, v33, v32
	v_add_f32_e32 v32, v46, v32
	v_mov_b32_e32 v33, v32
	s_nop 1
	v_permlane16_swap_b32_e32 v33, v32
	v_lshlrev_b64 v[86:87], 10, v[96:97]
	v_lshl_add_u64 v[88:89], v[86:87], 0, v[162:163]
	v_lshl_add_u64 v[76:77], v[88:89], 1, s[30:31]
	v_lshl_add_u64 v[44:45], v[86:87], 0, v[160:161]
	s_waitcnt lgkmcnt(0)
	v_add_f32_e32 v32, v32, v33
	v_mov_b32_e32 v33, v32
	s_nop 1
	v_permlane32_swap_b32_e32 v33, v32
	global_store_dwordx4 v[76:77], v[72:75], off
	global_store_dwordx4 v[98:99], v[36:39], off nt
	global_store_dwordx4 v[98:99], v[40:43], off offset:16 nt
	v_cvt_pk_bf16_f32 v35, v38, v39
	v_cvt_pk_bf16_f32 v34, v36, v37
	s_nop 0
	v_lshl_add_u64 v[38:39], v[44:45], 1, s[30:31]
	v_cvt_pk_bf16_f32 v36, v40, v41
	v_cvt_pk_bf16_f32 v37, v42, v43
	global_store_dwordx4 v[38:39], v[34:37], off
	s_and_saveexec_b64 s[0:1], vcc
	s_cbranch_execz .LBB0_807
	v_lshl_add_u64 v[34:35], v[96:97], 2, s[12:13]
	s_waitcnt lgkmcnt(0)
	v_add_f32_e32 v32, v32, v33
	global_atomic_add_f32 v[34:35], v32, off
; #define EPI_IT_ROW(it) EPI_ROW((it) >> 2, (it) & 3)
; #define EPI_PACK8(v0, v1) (u32x4){pk2((v0)[0], (v0)[1]), pk2((v0)[2], (v0)[3]), pk2((v1)[0], (v1)[1]), pk2((v1)[2], (v1)[3])}
;     __device__ __forceinline__ void operator()(AccRef acc, const Unit& u, int wr, int wc, int fr, int fq) const {
;         asm volatile("" : "+v"(fr), "+v"(fq));
;         f32x4 xc[2][2], xn[2][2];
; #pragma unroll
;         for (int bj = 0; bj < 2; ++bj) { const size_t p = (size_t)EPI_IT_ROW(0) * DM + EPI_COL(bj); xc[bj][0] = *(const f32x4*)(xin + p); xc[bj][1] = *(const f32x4*)(xin + p + 4); }
; #pragma unroll
;         for (int it = 0; it < 8; ++it) { const int ai = it >> 2, m = it & 3, row = EPI_IT_ROW(it);
;             if (it + 1 < 8) {
; #pragma unroll
;                 for (int bj = 0; bj < 2; ++bj) { const size_t p = (size_t)EPI_IT_ROW(it + 1) * DM + EPI_COL(bj); xn[bj][0] = *(const f32x4*)(xin + p); xn[bj][1] = *(const f32x4*)(xin + p + 4); } }
;             float q = 0.f;
; #pragma unroll
;             for (int bj = 0; bj < 2; ++bj) { const size_t p = (size_t)row * DM + EPI_COL(bj);
;                 const f32x4 x0 = xc[bj][0] + acc[ai][bj][m][0], x1 = xc[bj][1] + acc[ai][bj][m][1];
;                 __builtin_nontemporal_store(x0, (f32x4*)(xout + p)); __builtin_nontemporal_store(x1, (f32x4*)(xout + p + 4));
;                 *(u32x4*)(xb + p) = EPI_PACK8(x0, x1);
;                 q += EPI_SQ8(x0, x1); }
;             q += __shfl_xor(q, 16); q += __shfl_xor(q, 32);
;             if (fq == 0) atomicAdd(ssout + row, q);
; #pragma unroll
;             for (int bj = 0; bj < 2; ++bj) { xc[bj][0] = xn[bj][0]; xc[bj][1] = xn[bj][1]; } }
;     }
.LBB0_807:
	s_or_b64 exec, exec, s[0:1]
	v_add_u32_e32 v64, 0xb0, v164
	v_ashrrev_i32_e32 v65, 31, v64
	s_waitcnt lgkmcnt(0)
	v_lshlrev_b64 v[32:33], 12, v[64:65]
	v_lshl_add_u64 v[32:33], s[48:49], 0, v[32:33]
	v_lshl_add_u64 v[68:69], v[162:163], 2, v[32:33]
	v_lshl_add_u64 v[66:67], v[160:161], 2, v[32:33]
	global_load_dwordx4 v[40:43], v[68:69], off offset:16
	global_load_dwordx4 v[44:47], v[68:69], off
	global_load_dwordx4 v[32:35], v[66:67], off offset:16
	global_load_dwordx4 v[36:39], v[66:67], off
	s_waitcnt vmcnt(12)
	v_pk_add_f32 v[30:31], v[30:31], v[62:63]
	v_pk_add_f32 v[28:29], v[28:29], v[60:61]
	v_pk_add_f32 v[26:27], v[26:27], v[58:59]
	v_pk_add_f32 v[24:25], v[24:25], v[56:57]
	global_store_dwordx4 v[84:85], v[28:31], off nt
	global_store_dwordx4 v[84:85], v[24:27], off offset:16 nt
	v_cvt_pk_bf16_f32 v56, v28, v29
	v_cvt_pk_bf16_f32 v58, v24, v25
	s_waitcnt vmcnt(12)
	v_pk_add_f32 v[22:23], v[22:23], v[54:55]
	v_mul_f32_e32 v29, v29, v29
	v_fmac_f32_e32 v29, v28, v28
	v_mul_f32_e32 v28, v31, v31
	v_fmac_f32_e32 v28, v30, v30
	v_mul_f32_e32 v25, v25, v25
	v_add_f32_e32 v28, v29, v28
	v_fmac_f32_e32 v25, v24, v24
	v_add_f32_e32 v24, v28, v25
	v_mul_f32_e32 v25, v27, v27
	v_fmac_f32_e32 v25, v26, v26
	v_pk_add_f32 v[20:21], v[20:21], v[52:53]
	v_cvt_pk_bf16_f32 v57, v30, v31
	v_add_f32_e32 v30, v25, v24
	v_pk_add_f32 v[24:25], v[16:17], v[48:49]
	v_mul_f32_e32 v16, v21, v21
	v_mul_f32_e32 v17, v23, v23
	v_fmac_f32_e32 v16, v20, v20
	v_fmac_f32_e32 v17, v22, v22
	v_add_f32_e32 v16, v16, v17
	v_mul_f32_e32 v17, v25, v25
	v_cvt_pk_bf16_f32 v59, v26, v27
	v_pk_add_f32 v[26:27], v[18:19], v[50:51]
	v_fmac_f32_e32 v17, v24, v24
	v_add_f32_e32 v16, v16, v17
	v_mul_f32_e32 v17, v27, v27
	v_fmac_f32_e32 v17, v26, v26
	v_add_f32_e32 v16, v17, v16
	v_add_f32_e32 v16, v30, v16
	v_mov_b32_e32 v17, v16
	s_nop 1
	v_permlane16_swap_b32_e32 v17, v16
	v_lshlrev_b64 v[70:71], 10, v[80:81]
	v_lshl_add_u64 v[72:73], v[70:71], 0, v[162:163]
	v_lshl_add_u64 v[60:61], v[72:73], 1, s[30:31]
	v_lshl_add_u64 v[28:29], v[70:71], 0, v[160:161]
	s_waitcnt lgkmcnt(0)
	v_add_f32_e32 v16, v16, v17
	v_mov_b32_e32 v17, v16
	s_nop 1
	v_permlane32_swap_b32_e32 v17, v16
	global_store_dwordx4 v[60:61], v[56:59], off
	global_store_dwordx4 v[82:83], v[20:23], off nt
	global_store_dwordx4 v[82:83], v[24:27], off offset:16 nt
	v_cvt_pk_bf16_f32 v19, v22, v23
	v_cvt_pk_bf16_f32 v18, v20, v21
	s_nop 0
	v_lshl_add_u64 v[22:23], v[28:29], 1, s[30:31]
	v_cvt_pk_bf16_f32 v20, v24, v25
	v_cvt_pk_bf16_f32 v21, v26, v27
	global_store_dwordx4 v[22:23], v[18:21], off
	s_and_saveexec_b64 s[0:1], vcc
	s_cbranch_execz .LBB0_809
	v_lshl_add_u64 v[18:19], v[80:81], 2, s[12:13]
	s_waitcnt lgkmcnt(0)
	v_add_f32_e32 v16, v16, v17
	global_atomic_add_f32 v[18:19], v16, off
.LBB0_809:
	s_or_b64 exec, exec, s[0:1]
	s_waitcnt vmcnt(8)
	v_pk_add_f32 v[14:15], v[14:15], v[46:47]
	v_pk_add_f32 v[12:13], v[12:13], v[44:45]
	v_pk_add_f32 v[10:11], v[10:11], v[42:43]
	v_pk_add_f32 v[8:9], v[8:9], v[40:41]
	global_store_dwordx4 v[68:69], v[12:15], off nt
	global_store_dwordx4 v[68:69], v[8:11], off offset:16 nt
	v_cvt_pk_bf16_f32 v16, v12, v13
	v_cvt_pk_bf16_f32 v18, v8, v9
	s_waitcnt vmcnt(8)
	v_pk_add_f32 v[6:7], v[6:7], v[38:39]
	v_mul_f32_e32 v13, v13, v13
	v_fmac_f32_e32 v13, v12, v12
	v_mul_f32_e32 v12, v15, v15
	v_fmac_f32_e32 v12, v14, v14
	v_mul_f32_e32 v9, v9, v9
	v_add_f32_e32 v12, v13, v12
	v_fmac_f32_e32 v9, v8, v8
	v_add_f32_e32 v8, v12, v9
	v_mul_f32_e32 v9, v11, v11
	v_fmac_f32_e32 v9, v10, v10
	v_pk_add_f32 v[4:5], v[4:5], v[36:37]
	s_waitcnt lgkmcnt(0)
	v_cvt_pk_bf16_f32 v17, v14, v15
	v_add_f32_e32 v14, v9, v8
	v_pk_add_f32 v[8:9], v[0:1], v[32:33]
	v_mul_f32_e32 v0, v5, v5
	v_mul_f32_e32 v1, v7, v7
	v_fmac_f32_e32 v0, v4, v4
	v_fmac_f32_e32 v1, v6, v6
	v_add_f32_e32 v0, v0, v1
	v_mul_f32_e32 v1, v9, v9
	v_cvt_pk_bf16_f32 v19, v10, v11
	v_pk_add_f32 v[10:11], v[2:3], v[34:35]
	v_fmac_f32_e32 v1, v8, v8
	v_add_f32_e32 v0, v0, v1
	v_mul_f32_e32 v1, v11, v11
	v_fmac_f32_e32 v1, v10, v10
	v_add_f32_e32 v0, v1, v0
	v_add_f32_e32 v0, v14, v0
	v_mov_b32_e32 v1, v0
	s_nop 1
	v_permlane16_swap_b32_e32 v1, v0
	v_lshlrev_b64 v[20:21], 10, v[64:65]
	v_lshl_add_u64 v[22:23], v[20:21], 0, v[162:163]
	v_lshl_add_u64 v[22:23], v[22:23], 1, s[30:31]
	v_lshl_add_u64 v[12:13], v[20:21], 0, v[160:161]
	s_waitcnt lgkmcnt(0)
	v_add_f32_e32 v0, v0, v1
	v_mov_b32_e32 v1, v0
	s_nop 1
	v_permlane32_swap_b32_e32 v1, v0
	global_store_dwordx4 v[22:23], v[16:19], off
	global_store_dwordx4 v[66:67], v[4:7], off nt
	global_store_dwordx4 v[66:67], v[8:11], off offset:16 nt
	v_cvt_pk_bf16_f32 v3, v6, v7
	v_cvt_pk_bf16_f32 v2, v4, v5
	s_nop 0
	v_lshl_add_u64 v[6:7], v[12:13], 1, s[30:31]
	v_cvt_pk_bf16_f32 v4, v8, v9
	v_cvt_pk_bf16_f32 v5, v10, v11
	global_store_dwordx4 v[6:7], v[2:5], off
	s_and_saveexec_b64 s[0:1], vcc
	s_cbranch_execz .LBB0_811
	v_lshl_add_u64 v[2:3], v[64:65], 2, s[12:13]
	s_waitcnt lgkmcnt(0)
	v_add_f32_e32 v0, v0, v1
	global_atomic_add_f32 v[2:3], v0, off

; __device__ __forceinline__ float sigmoid_f(float z) { return __builtin_amdgcn_rcpf(1.f + fexp(-z)); }
; __device__ __forceinline__ float rms_r(float ss) { return __builtin_amdgcn_rsqf(ss * (1.0f / DM) + RMS_EPS); }
; #define EPI_IT_ROW(it) EPI_ROW((it) >> 2, (it) & 3)
; #define EPI_PACK8(v0, v1) (u32x4){pk2((v0)[0], (v0)[1]), pk2((v0)[2], (v0)[3]), pk2((v1)[0], (v1)[1]), pk2((v1)[2], (v1)[3])}
;     __device__ __forceinline__ void operator()(AccRef acc, const Unit& u, int wr, int wc, int fr, int fq) const {
;     ...
;         for (int st = 0; st < 16; ++st) { const int it = st >> 1, bj = st & 1, ai = it >> 2, m = it & 3, row = EPI_IT_ROW(it);
;             if (st + 1 < 16) { const int it1 = (st + 1) >> 1, bj1 = (st + 1) & 1; const size_t p = (size_t)EPI_IT_ROW(it1) * DM + EPI_COL(bj1);
;                 xn0 = *(const f32x4*)(x + p); xn1 = *(const f32x4*)(x + p + 4); pn = *(const u32x4*)(pp + p);
;                 if (bj1 == 0) { sn_ = ssin[EPI_IT_ROW(it1)]; qn = ppss[EPI_IT_ROW(it1)]; } }
;             const float r = rms_r(sc), rp = rms_r(qc);
;             const size_t p = (size_t)row * DM + EPI_COL(bj);
;             const f32x4 p0 = (f32x4){bflo(pc.x), bfhi(pc.x), bflo(pc.y), bfhi(pc.y)}, p1 = (f32x4){bflo(pc.z), bfhi(pc.z), bflo(pc.w), bfhi(pc.w)};
;             const f32x4 z0 = acc[ai][bj][m][0] * r, z1 = acc[ai][bj][m][1] * r;
;             f32x4 g0, g1;
; #pragma unroll
;             for (int e = 0; e < 4; ++e) { g0[e] = sigmoid_f(z0[e]); g1[e] = sigmoid_f(z1[e]); }
;             const f32x4 x0 = xc0 + g0 * (p0 * rp) * pg[bj][0], x1 = xc1 + g1 * (p1 * rp) * pg[bj][1];
;             if (xo) { __builtin_nontemporal_store(x0, (f32x4*)(xo + p)); __builtin_nontemporal_store(x1, (f32x4*)(xo + p + 4)); }
;             *(u32x4*)(xb + p) = EPI_PACK8(x0, x1);
;             q += EPI_SQ8(x0, x1);
;             if (bj == 1) { q += __shfl_xor(q, 16); q += __shfl_xor(q, 32); if (fq == 0) atomicAdd(ssout + row, q); q = 0.f; sc = sn_; qc = qn; }
.LBB0_896:
	v_mul_f32_e32 v144, v165, v165
	v_mul_f32_e32 v145, v167, v167
	v_fmac_f32_e32 v144, v164, v164
	v_fmac_f32_e32 v145, v166, v166
	v_add_f32_e32 v144, v144, v145
	v_mul_f32_e32 v145, v161, v161
	v_fmac_f32_e32 v145, v160, v160
	v_mul_f32_e32 v146, v129, v129
	v_mul_f32_e32 v147, v131, v131
	v_add_f32_e32 v144, v145, v144
	v_mul_f32_e32 v145, v163, v163
	v_fmac_f32_e32 v146, v128, v128
	v_fmac_f32_e32 v147, v130, v130
	v_fmac_f32_e32 v145, v162, v162
	v_add_f32_e32 v146, v146, v147
	v_mul_f32_e32 v147, v133, v133
	v_add_f32_e32 v144, v145, v144
	v_mul_f32_e32 v145, v135, v135
	v_fmac_f32_e32 v147, v132, v132
	v_fmac_f32_e32 v145, v134, v134
	v_add_f32_e32 v146, v147, v146
	v_add_f32_e32 v145, v145, v146
	v_add_f32_e32 v146, v144, v145
	v_and_b32_e32 v145, 64, v212
	v_xor_b32_e32 v144, 16, v212
	v_add_u32_e32 v147, 64, v145
	v_cmp_lt_i32_e32 vcc, v144, v147
	v_cmp_eq_u32_e64 s[8:9], 0, v213
	v_cvt_pk_bf16_f32 v145, v130, v131
	v_lshl_add_u64 v[130:131], v[194:195], 1, s[24:25]
	v_cndmask_b32_e32 v144, v212, v144, vcc
	v_lshlrev_b32_e32 v166, 2, v144
	v_mov_b32_e32 v148, v146
	s_nop 1
	v_permlane16_swap_b32_e32 v148, v146
	v_cvt_pk_bf16_f32 v144, v128, v129
	v_xor_b32_e32 v129, 32, v212
	v_cmp_lt_i32_e32 vcc, v129, v147
	v_cvt_pk_bf16_f32 v147, v134, v135
	s_waitcnt lgkmcnt(0)
	v_add_f32_e32 v128, v146, v148
	v_cvt_pk_bf16_f32 v146, v132, v133
	global_store_dwordx4 v[130:131], v[144:147], off
	v_cndmask_b32_e32 v129, v212, v129, vcc
	v_lshlrev_b32_e32 v167, 2, v129
	v_mov_b32_e32 v129, v128
	s_nop 1
	v_permlane32_swap_b32_e32 v129, v128
	s_and_saveexec_b64 s[56:57], s[8:9]
	s_cbranch_execz .LBB0_898
	v_lshl_add_u64 v[130:131], v[190:191], 2, s[16:17]
	s_waitcnt lgkmcnt(0)
	v_add_f32_e32 v128, v128, v129
	global_atomic_add_f32 v[130:131], v128, off

; __device__ __forceinline__ float sigmoid_f(float z) { return __builtin_amdgcn_rcpf(1.f + fexp(-z)); }
; __device__ __forceinline__ float rms_r(float ss) { return __builtin_amdgcn_rsqf(ss * (1.0f / DM) + RMS_EPS); }
; #define EPI_IT_ROW(it) EPI_ROW((it) >> 2, (it) & 3)
; #define EPI_PACK8(v0, v1) (u32x4){pk2((v0)[0], (v0)[1]), pk2((v0)[2], (v0)[3]), pk2((v1)[0], (v1)[1]), pk2((v1)[2], (v1)[3])}
;     __device__ __forceinline__ void operator()(AccRef acc, const Unit& u, int wr, int wc, int fr, int fq) const {
;     ...
;         for (int st = 0; st < 16; ++st) { const int it = st >> 1, bj = st & 1, ai = it >> 2, m = it & 3, row = EPI_IT_ROW(it);
;             if (st + 1 < 16) { const int it1 = (st + 1) >> 1, bj1 = (st + 1) & 1; const size_t p = (size_t)EPI_IT_ROW(it1) * DM + EPI_COL(bj1);
;                 xn0 = *(const f32x4*)(x + p); xn1 = *(const f32x4*)(x + p + 4); pn = *(const u32x4*)(pp + p);
;                 if (bj1 == 0) { sn_ = ssin[EPI_IT_ROW(it1)]; qn = ppss[EPI_IT_ROW(it1)]; } }
;             const float r = rms_r(sc), rp = rms_r(qc);
;             const size_t p = (size_t)row * DM + EPI_COL(bj);
;             const f32x4 p0 = (f32x4){bflo(pc.x), bfhi(pc.x), bflo(pc.y), bfhi(pc.y)}, p1 = (f32x4){bflo(pc.z), bfhi(pc.z), bflo(pc.w), bfhi(pc.w)};
;             const f32x4 z0 = acc[ai][bj][m][0] * r, z1 = acc[ai][bj][m][1] * r;
;             f32x4 g0, g1;
; #pragma unroll
;             for (int e = 0; e < 4; ++e) { g0[e] = sigmoid_f(z0[e]); g1[e] = sigmoid_f(z1[e]); }
;             const f32x4 x0 = xc0 + g0 * (p0 * rp) * pg[bj][0], x1 = xc1 + g1 * (p1 * rp) * pg[bj][1];
;             if (xo) { __builtin_nontemporal_store(x0, (f32x4*)(xo + p)); __builtin_nontemporal_store(x1, (f32x4*)(xo + p + 4)); }
;             *(u32x4*)(xb + p) = EPI_PACK8(x0, x1);
;             q += EPI_SQ8(x0, x1);
;             if (bj == 1) { q += __shfl_xor(q, 16); q += __shfl_xor(q, 32); if (fq == 0) atomicAdd(ssout + row, q); q = 0.f; sc = sn_; qc = qn; }
.LBB0_902:
	v_mul_f32_e32 v128, v141, v141
	v_mul_f32_e32 v129, v143, v143
	v_fmac_f32_e32 v128, v140, v140
	v_fmac_f32_e32 v129, v142, v142
	v_add_f32_e32 v128, v128, v129
	v_mul_f32_e32 v129, v145, v145
	v_fmac_f32_e32 v129, v144, v144
	v_mul_f32_e32 v130, v113, v113
	v_mul_f32_e32 v131, v115, v115
	v_add_f32_e32 v128, v129, v128
	v_mul_f32_e32 v129, v147, v147
	v_fmac_f32_e32 v130, v112, v112
	v_fmac_f32_e32 v131, v114, v114
	v_fmac_f32_e32 v129, v146, v146
	v_add_f32_e32 v130, v130, v131
	v_mul_f32_e32 v131, v117, v117
	v_add_f32_e32 v128, v129, v128
	v_mul_f32_e32 v129, v119, v119
	v_fmac_f32_e32 v131, v116, v116
	v_fmac_f32_e32 v129, v118, v118
	v_add_f32_e32 v130, v131, v130
	v_add_f32_e32 v129, v129, v130
	v_add_f32_e32 v130, v128, v129
	v_mov_b32_e32 v131, v130
	s_nop 1
	v_permlane16_swap_b32_e32 v131, v130
	v_cvt_pk_bf16_f32 v128, v112, v113
	v_cvt_pk_bf16_f32 v129, v114, v115
	v_lshl_add_u64 v[114:115], v[156:157], 1, s[24:25]
	s_waitcnt lgkmcnt(0)
	v_add_f32_e32 v112, v130, v131
	v_mov_b32_e32 v113, v112
	s_nop 1
	v_permlane32_swap_b32_e32 v113, v112
	v_cvt_pk_bf16_f32 v130, v116, v117
	v_cvt_pk_bf16_f32 v131, v118, v119
	global_store_dwordx4 v[114:115], v[128:131], off
	s_and_saveexec_b64 s[56:57], s[8:9]
	s_cbranch_execz .LBB0_904
	v_lshl_add_u64 v[114:115], v[192:193], 2, s[16:17]
	s_waitcnt lgkmcnt(0)
	v_add_f32_e32 v112, v112, v113
	global_atomic_add_f32 v[114:115], v112, off

; __device__ __forceinline__ float sigmoid_f(float z) { return __builtin_amdgcn_rcpf(1.f + fexp(-z)); }
; __device__ __forceinline__ float rms_r(float ss) { return __builtin_amdgcn_rsqf(ss * (1.0f / DM) + RMS_EPS); }
; #define EPI_IT_ROW(it) EPI_ROW((it) >> 2, (it) & 3)
; #define EPI_PACK8(v0, v1) (u32x4){pk2((v0)[0], (v0)[1]), pk2((v0)[2], (v0)[3]), pk2((v1)[0], (v1)[1]), pk2((v1)[2], (v1)[3])}
;     __device__ __forceinline__ void operator()(AccRef acc, const Unit& u, int wr, int wc, int fr, int fq) const {
;     ...
;         for (int st = 0; st < 16; ++st) { const int it = st >> 1, bj = st & 1, ai = it >> 2, m = it & 3, row = EPI_IT_ROW(it);
;             if (st + 1 < 16) { const int it1 = (st + 1) >> 1, bj1 = (st + 1) & 1; const size_t p = (size_t)EPI_IT_ROW(it1) * DM + EPI_COL(bj1);
;                 xn0 = *(const f32x4*)(x + p); xn1 = *(const f32x4*)(x + p + 4); pn = *(const u32x4*)(pp + p);
;                 if (bj1 == 0) { sn_ = ssin[EPI_IT_ROW(it1)]; qn = ppss[EPI_IT_ROW(it1)]; } }
;             const float r = rms_r(sc), rp = rms_r(qc);
;             const size_t p = (size_t)row * DM + EPI_COL(bj);
;             const f32x4 p0 = (f32x4){bflo(pc.x), bfhi(pc.x), bflo(pc.y), bfhi(pc.y)}, p1 = (f32x4){bflo(pc.z), bfhi(pc.z), bflo(pc.w), bfhi(pc.w)};
;             const f32x4 z0 = acc[ai][bj][m][0] * r, z1 = acc[ai][bj][m][1] * r;
;             f32x4 g0, g1;
; #pragma unroll
;             for (int e = 0; e < 4; ++e) { g0[e] = sigmoid_f(z0[e]); g1[e] = sigmoid_f(z1[e]); }
;             const f32x4 x0 = xc0 + g0 * (p0 * rp) * pg[bj][0], x1 = xc1 + g1 * (p1 * rp) * pg[bj][1];
;             if (xo) { __builtin_nontemporal_store(x0, (f32x4*)(xo + p)); __builtin_nontemporal_store(x1, (f32x4*)(xo + p + 4)); }
;             *(u32x4*)(xb + p) = EPI_PACK8(x0, x1);
;             q += EPI_SQ8(x0, x1);
;             if (bj == 1) { q += __shfl_xor(q, 16); q += __shfl_xor(q, 32); if (fq == 0) atomicAdd(ssout + row, q); q = 0.f; sc = sn_; qc = qn; }
.LBB0_908:
	v_mul_f32_e32 v112, v125, v125
	v_mul_f32_e32 v113, v127, v127
	v_fmac_f32_e32 v112, v124, v124
	v_fmac_f32_e32 v113, v126, v126
	v_add_f32_e32 v112, v112, v113
	v_mul_f32_e32 v113, v129, v129
	v_fmac_f32_e32 v113, v128, v128
	v_mul_f32_e32 v114, v97, v97
	v_mul_f32_e32 v115, v99, v99
	v_add_f32_e32 v112, v113, v112
	v_mul_f32_e32 v113, v131, v131
	v_fmac_f32_e32 v114, v96, v96
	v_fmac_f32_e32 v115, v98, v98
	v_fmac_f32_e32 v113, v130, v130
	v_add_f32_e32 v114, v114, v115
	v_mul_f32_e32 v115, v101, v101
	v_add_f32_e32 v112, v113, v112
	v_mul_f32_e32 v113, v103, v103
	v_fmac_f32_e32 v115, v100, v100
	v_fmac_f32_e32 v113, v102, v102
	v_add_f32_e32 v114, v115, v114
	v_add_f32_e32 v113, v113, v114
	v_add_f32_e32 v114, v112, v113
	v_mov_b32_e32 v115, v114
	s_nop 1
	v_permlane16_swap_b32_e32 v115, v114
	v_cvt_pk_bf16_f32 v112, v96, v97
	v_cvt_pk_bf16_f32 v113, v98, v99
	v_lshl_add_u64 v[98:99], v[140:141], 1, s[24:25]
	s_waitcnt lgkmcnt(0)
	v_add_f32_e32 v96, v114, v115
	v_mov_b32_e32 v97, v96
	s_nop 1
	v_permlane32_swap_b32_e32 v97, v96
	v_cvt_pk_bf16_f32 v114, v100, v101
	v_cvt_pk_bf16_f32 v115, v102, v103
	global_store_dwordx4 v[98:99], v[112:115], off
	s_and_saveexec_b64 s[56:57], s[8:9]
	s_cbranch_execz .LBB0_910
	v_lshl_add_u64 v[98:99], v[152:153], 2, s[16:17]
	s_waitcnt lgkmcnt(0)
	v_add_f32_e32 v96, v96, v97
	global_atomic_add_f32 v[98:99], v96, off

; __device__ __forceinline__ float sigmoid_f(float z) { return __builtin_amdgcn_rcpf(1.f + fexp(-z)); }
; __device__ __forceinline__ float rms_r(float ss) { return __builtin_amdgcn_rsqf(ss * (1.0f / DM) + RMS_EPS); }
; #define EPI_IT_ROW(it) EPI_ROW((it) >> 2, (it) & 3)
; #define EPI_PACK8(v0, v1) (u32x4){pk2((v0)[0], (v0)[1]), pk2((v0)[2], (v0)[3]), pk2((v1)[0], (v1)[1]), pk2((v1)[2], (v1)[3])}
;     __device__ __forceinline__ void operator()(AccRef acc, const Unit& u, int wr, int wc, int fr, int fq) const {
;     ...
;         for (int st = 0; st < 16; ++st) { const int it = st >> 1, bj = st & 1, ai = it >> 2, m = it & 3, row = EPI_IT_ROW(it);
;             if (st + 1 < 16) { const int it1 = (st + 1) >> 1, bj1 = (st + 1) & 1; const size_t p = (size_t)EPI_IT_ROW(it1) * DM + EPI_COL(bj1);
;                 xn0 = *(const f32x4*)(x + p); xn1 = *(const f32x4*)(x + p + 4); pn = *(const u32x4*)(pp + p);
;                 if (bj1 == 0) { sn_ = ssin[EPI_IT_ROW(it1)]; qn = ppss[EPI_IT_ROW(it1)]; } }
;             const float r = rms_r(sc), rp = rms_r(qc);
;             const size_t p = (size_t)row * DM + EPI_COL(bj);
;             const f32x4 p0 = (f32x4){bflo(pc.x), bfhi(pc.x), bflo(pc.y), bfhi(pc.y)}, p1 = (f32x4){bflo(pc.z), bfhi(pc.z), bflo(pc.w), bfhi(pc.w)};
;             const f32x4 z0 = acc[ai][bj][m][0] * r, z1 = acc[ai][bj][m][1] * r;
;             f32x4 g0, g1;
; #pragma unroll
;             for (int e = 0; e < 4; ++e) { g0[e] = sigmoid_f(z0[e]); g1[e] = sigmoid_f(z1[e]); }
;             const f32x4 x0 = xc0 + g0 * (p0 * rp) * pg[bj][0], x1 = xc1 + g1 * (p1 * rp) * pg[bj][1];
;             if (xo) { __builtin_nontemporal_store(x0, (f32x4*)(xo + p)); __builtin_nontemporal_store(x1, (f32x4*)(xo + p + 4)); }
;             *(u32x4*)(xb + p) = EPI_PACK8(x0, x1);
;             q += EPI_SQ8(x0, x1);
;             if (bj == 1) { q += __shfl_xor(q, 16); q += __shfl_xor(q, 32); if (fq == 0) atomicAdd(ssout + row, q); q = 0.f; sc = sn_; qc = qn; }
.LBB0_914:
	v_mul_f32_e32 v96, v109, v109
	v_mul_f32_e32 v97, v111, v111
	v_fmac_f32_e32 v96, v108, v108
	v_fmac_f32_e32 v97, v110, v110
	v_add_f32_e32 v96, v96, v97
	v_mul_f32_e32 v97, v113, v113
	v_fmac_f32_e32 v97, v112, v112
	v_mul_f32_e32 v98, v81, v81
	v_mul_f32_e32 v99, v83, v83
	v_add_f32_e32 v96, v97, v96
	v_mul_f32_e32 v97, v115, v115
	v_fmac_f32_e32 v98, v80, v80
	v_fmac_f32_e32 v99, v82, v82
	v_fmac_f32_e32 v97, v114, v114
	v_add_f32_e32 v98, v98, v99
	v_mul_f32_e32 v99, v85, v85
	v_add_f32_e32 v96, v97, v96
	v_mul_f32_e32 v97, v87, v87
	v_fmac_f32_e32 v99, v84, v84
	v_fmac_f32_e32 v97, v86, v86
	v_add_f32_e32 v98, v99, v98
	v_add_f32_e32 v97, v97, v98
	v_add_f32_e32 v98, v96, v97
	v_mov_b32_e32 v99, v98
	s_nop 1
	v_permlane16_swap_b32_e32 v99, v98
	v_cvt_pk_bf16_f32 v96, v80, v81
	v_cvt_pk_bf16_f32 v97, v82, v83
	v_lshl_add_u64 v[82:83], v[124:125], 1, s[24:25]
	s_waitcnt lgkmcnt(0)
	v_add_f32_e32 v80, v98, v99
	v_mov_b32_e32 v81, v80
	s_nop 1
	v_permlane32_swap_b32_e32 v81, v80
	v_cvt_pk_bf16_f32 v98, v84, v85
	v_cvt_pk_bf16_f32 v99, v86, v87
	global_store_dwordx4 v[82:83], v[96:99], off
	s_and_saveexec_b64 s[56:57], s[8:9]
	s_cbranch_execz .LBB0_916
	v_lshl_add_u64 v[82:83], v[136:137], 2, s[16:17]
	s_waitcnt lgkmcnt(0)
	v_add_f32_e32 v80, v80, v81
	global_atomic_add_f32 v[82:83], v80, off

; __device__ __forceinline__ float sigmoid_f(float z) { return __builtin_amdgcn_rcpf(1.f + fexp(-z)); }
; __device__ __forceinline__ float rms_r(float ss) { return __builtin_amdgcn_rsqf(ss * (1.0f / DM) + RMS_EPS); }
; #define EPI_IT_ROW(it) EPI_ROW((it) >> 2, (it) & 3)
; #define EPI_PACK8(v0, v1) (u32x4){pk2((v0)[0], (v0)[1]), pk2((v0)[2], (v0)[3]), pk2((v1)[0], (v1)[1]), pk2((v1)[2], (v1)[3])}
;     __device__ __forceinline__ void operator()(AccRef acc, const Unit& u, int wr, int wc, int fr, int fq) const {
;     ...
;         for (int st = 0; st < 16; ++st) { const int it = st >> 1, bj = st & 1, ai = it >> 2, m = it & 3, row = EPI_IT_ROW(it);
;             if (st + 1 < 16) { const int it1 = (st + 1) >> 1, bj1 = (st + 1) & 1; const size_t p = (size_t)EPI_IT_ROW(it1) * DM + EPI_COL(bj1);
;                 xn0 = *(const f32x4*)(x + p); xn1 = *(const f32x4*)(x + p + 4); pn = *(const u32x4*)(pp + p);
;                 if (bj1 == 0) { sn_ = ssin[EPI_IT_ROW(it1)]; qn = ppss[EPI_IT_ROW(it1)]; } }
;             const float r = rms_r(sc), rp = rms_r(qc);
;             const size_t p = (size_t)row * DM + EPI_COL(bj);
;             const f32x4 p0 = (f32x4){bflo(pc.x), bfhi(pc.x), bflo(pc.y), bfhi(pc.y)}, p1 = (f32x4){bflo(pc.z), bfhi(pc.z), bflo(pc.w), bfhi(pc.w)};
;             const f32x4 z0 = acc[ai][bj][m][0] * r, z1 = acc[ai][bj][m][1] * r;
;             f32x4 g0, g1;
; #pragma unroll
;             for (int e = 0; e < 4; ++e) { g0[e] = sigmoid_f(z0[e]); g1[e] = sigmoid_f(z1[e]); }
;             const f32x4 x0 = xc0 + g0 * (p0 * rp) * pg[bj][0], x1 = xc1 + g1 * (p1 * rp) * pg[bj][1];
;             if (xo) { __builtin_nontemporal_store(x0, (f32x4*)(xo + p)); __builtin_nontemporal_store(x1, (f32x4*)(xo + p + 4)); }
;             *(u32x4*)(xb + p) = EPI_PACK8(x0, x1);
;             q += EPI_SQ8(x0, x1);
;             if (bj == 1) { q += __shfl_xor(q, 16); q += __shfl_xor(q, 32); if (fq == 0) atomicAdd(ssout + row, q); q = 0.f; sc = sn_; qc = qn; }
.LBB0_920:
	v_mul_f32_e32 v80, v93, v93
	v_mul_f32_e32 v81, v95, v95
	v_fmac_f32_e32 v80, v92, v92
	v_fmac_f32_e32 v81, v94, v94
	v_add_f32_e32 v80, v80, v81
	v_mul_f32_e32 v81, v97, v97
	v_fmac_f32_e32 v81, v96, v96
	v_mul_f32_e32 v82, v65, v65
	v_mul_f32_e32 v83, v67, v67
	v_add_f32_e32 v80, v81, v80
	v_mul_f32_e32 v81, v99, v99
	v_fmac_f32_e32 v82, v64, v64
	v_fmac_f32_e32 v83, v66, v66
	v_fmac_f32_e32 v81, v98, v98
	v_add_f32_e32 v82, v82, v83
	v_mul_f32_e32 v83, v69, v69
	v_add_f32_e32 v80, v81, v80
	v_mul_f32_e32 v81, v71, v71
	v_fmac_f32_e32 v83, v68, v68
	v_fmac_f32_e32 v81, v70, v70
	v_add_f32_e32 v82, v83, v82
	v_add_f32_e32 v81, v81, v82
	v_add_f32_e32 v82, v80, v81
	v_mov_b32_e32 v83, v82
	s_nop 1
	v_permlane16_swap_b32_e32 v83, v82
	v_cvt_pk_bf16_f32 v80, v64, v65
	v_cvt_pk_bf16_f32 v81, v66, v67
	v_lshl_add_u64 v[66:67], v[108:109], 1, s[24:25]
	s_waitcnt lgkmcnt(0)
	v_add_f32_e32 v64, v82, v83
	v_mov_b32_e32 v65, v64
	s_nop 1
	v_permlane32_swap_b32_e32 v65, v64
	v_cvt_pk_bf16_f32 v82, v68, v69
	v_cvt_pk_bf16_f32 v83, v70, v71
	global_store_dwordx4 v[66:67], v[80:83], off
	s_and_saveexec_b64 s[56:57], s[8:9]
	s_cbranch_execz .LBB0_922
	v_lshl_add_u64 v[66:67], v[120:121], 2, s[16:17]
	s_waitcnt lgkmcnt(0)
	v_add_f32_e32 v64, v64, v65
	global_atomic_add_f32 v[66:67], v64, off

; __device__ __forceinline__ float sigmoid_f(float z) { return __builtin_amdgcn_rcpf(1.f + fexp(-z)); }
; __device__ __forceinline__ float rms_r(float ss) { return __builtin_amdgcn_rsqf(ss * (1.0f / DM) + RMS_EPS); }
; #define EPI_IT_ROW(it) EPI_ROW((it) >> 2, (it) & 3)
; #define EPI_PACK8(v0, v1) (u32x4){pk2((v0)[0], (v0)[1]), pk2((v0)[2], (v0)[3]), pk2((v1)[0], (v1)[1]), pk2((v1)[2], (v1)[3])}
;     __device__ __forceinline__ void operator()(AccRef acc, const Unit& u, int wr, int wc, int fr, int fq) const {
;     ...
;         for (int st = 0; st < 16; ++st) { const int it = st >> 1, bj = st & 1, ai = it >> 2, m = it & 3, row = EPI_IT_ROW(it);
;             if (st + 1 < 16) { const int it1 = (st + 1) >> 1, bj1 = (st + 1) & 1; const size_t p = (size_t)EPI_IT_ROW(it1) * DM + EPI_COL(bj1);
;                 xn0 = *(const f32x4*)(x + p); xn1 = *(const f32x4*)(x + p + 4); pn = *(const u32x4*)(pp + p);
;                 if (bj1 == 0) { sn_ = ssin[EPI_IT_ROW(it1)]; qn = ppss[EPI_IT_ROW(it1)]; } }
;             const float r = rms_r(sc), rp = rms_r(qc);
;             const size_t p = (size_t)row * DM + EPI_COL(bj);
;             const f32x4 p0 = (f32x4){bflo(pc.x), bfhi(pc.x), bflo(pc.y), bfhi(pc.y)}, p1 = (f32x4){bflo(pc.z), bfhi(pc.z), bflo(pc.w), bfhi(pc.w)};
;             const f32x4 z0 = acc[ai][bj][m][0] * r, z1 = acc[ai][bj][m][1] * r;
;             f32x4 g0, g1;
; #pragma unroll
;             for (int e = 0; e < 4; ++e) { g0[e] = sigmoid_f(z0[e]); g1[e] = sigmoid_f(z1[e]); }
;             const f32x4 x0 = xc0 + g0 * (p0 * rp) * pg[bj][0], x1 = xc1 + g1 * (p1 * rp) * pg[bj][1];
;             if (xo) { __builtin_nontemporal_store(x0, (f32x4*)(xo + p)); __builtin_nontemporal_store(x1, (f32x4*)(xo + p + 4)); }
;             *(u32x4*)(xb + p) = EPI_PACK8(x0, x1);
;             q += EPI_SQ8(x0, x1);
;             if (bj == 1) { q += __shfl_xor(q, 16); q += __shfl_xor(q, 32); if (fq == 0) atomicAdd(ssout + row, q); q = 0.f; sc = sn_; qc = qn; }
.LBB0_926:
	v_mul_f32_e32 v64, v77, v77
	v_mul_f32_e32 v65, v79, v79
	v_fmac_f32_e32 v64, v76, v76
	v_fmac_f32_e32 v65, v78, v78
	v_add_f32_e32 v64, v64, v65
	v_mul_f32_e32 v65, v81, v81
	v_fmac_f32_e32 v65, v80, v80
	v_mul_f32_e32 v66, v33, v33
	v_mul_f32_e32 v67, v35, v35
	v_add_f32_e32 v64, v65, v64
	v_mul_f32_e32 v65, v83, v83
	v_fmac_f32_e32 v66, v32, v32
	v_fmac_f32_e32 v67, v34, v34
	v_fmac_f32_e32 v65, v82, v82
	v_add_f32_e32 v66, v66, v67
	v_mul_f32_e32 v67, v37, v37
	v_add_f32_e32 v64, v65, v64
	v_mul_f32_e32 v65, v39, v39
	v_fmac_f32_e32 v67, v36, v36
	v_fmac_f32_e32 v65, v38, v38
	v_add_f32_e32 v66, v67, v66
	v_add_f32_e32 v65, v65, v66
	v_add_f32_e32 v66, v64, v65
	v_mov_b32_e32 v67, v66
	s_nop 1
	v_permlane16_swap_b32_e32 v67, v66
	v_cvt_pk_bf16_f32 v64, v32, v33
	v_cvt_pk_bf16_f32 v65, v34, v35
	v_lshl_add_u64 v[34:35], v[92:93], 1, s[24:25]
	s_waitcnt lgkmcnt(0)
	v_add_f32_e32 v32, v66, v67
	v_mov_b32_e32 v33, v32
	s_nop 1
	v_permlane32_swap_b32_e32 v33, v32
	v_cvt_pk_bf16_f32 v66, v36, v37
	v_cvt_pk_bf16_f32 v67, v38, v39
	global_store_dwordx4 v[34:35], v[64:67], off
	s_and_saveexec_b64 s[56:57], s[8:9]
	s_cbranch_execz .LBB0_928
	v_lshl_add_u64 v[34:35], v[104:105], 2, s[16:17]
	s_waitcnt lgkmcnt(0)
	v_add_f32_e32 v32, v32, v33
	global_atomic_add_f32 v[34:35], v32, off

; __device__ __forceinline__ float sigmoid_f(float z) { return __builtin_amdgcn_rcpf(1.f + fexp(-z)); }
; __device__ __forceinline__ float rms_r(float ss) { return __builtin_amdgcn_rsqf(ss * (1.0f / DM) + RMS_EPS); }
; #define EPI_IT_ROW(it) EPI_ROW((it) >> 2, (it) & 3)
; #define EPI_PACK8(v0, v1) (u32x4){pk2((v0)[0], (v0)[1]), pk2((v0)[2], (v0)[3]), pk2((v1)[0], (v1)[1]), pk2((v1)[2], (v1)[3])}
;     __device__ __forceinline__ void operator()(AccRef acc, const Unit& u, int wr, int wc, int fr, int fq) const {
;     ...
;         for (int st = 0; st < 16; ++st) { const int it = st >> 1, bj = st & 1, ai = it >> 2, m = it & 3, row = EPI_IT_ROW(it);
;             if (st + 1 < 16) { const int it1 = (st + 1) >> 1, bj1 = (st + 1) & 1; const size_t p = (size_t)EPI_IT_ROW(it1) * DM + EPI_COL(bj1);
;                 xn0 = *(const f32x4*)(x + p); xn1 = *(const f32x4*)(x + p + 4); pn = *(const u32x4*)(pp + p);
;                 if (bj1 == 0) { sn_ = ssin[EPI_IT_ROW(it1)]; qn = ppss[EPI_IT_ROW(it1)]; } }
;             const float r = rms_r(sc), rp = rms_r(qc);
;             const size_t p = (size_t)row * DM + EPI_COL(bj);
;             const f32x4 p0 = (f32x4){bflo(pc.x), bfhi(pc.x), bflo(pc.y), bfhi(pc.y)}, p1 = (f32x4){bflo(pc.z), bfhi(pc.z), bflo(pc.w), bfhi(pc.w)};
;             const f32x4 z0 = acc[ai][bj][m][0] * r, z1 = acc[ai][bj][m][1] * r;
;             f32x4 g0, g1;
; #pragma unroll
;             for (int e = 0; e < 4; ++e) { g0[e] = sigmoid_f(z0[e]); g1[e] = sigmoid_f(z1[e]); }
;             const f32x4 x0 = xc0 + g0 * (p0 * rp) * pg[bj][0], x1 = xc1 + g1 * (p1 * rp) * pg[bj][1];
;             if (xo) { __builtin_nontemporal_store(x0, (f32x4*)(xo + p)); __builtin_nontemporal_store(x1, (f32x4*)(xo + p + 4)); }
;             *(u32x4*)(xb + p) = EPI_PACK8(x0, x1);
;             q += EPI_SQ8(x0, x1);
;             if (bj == 1) { q += __shfl_xor(q, 16); q += __shfl_xor(q, 32); if (fq == 0) atomicAdd(ssout + row, q); q = 0.f; sc = sn_; qc = qn; }
.LBB0_932:
	v_mul_f32_e32 v32, v53, v53
	v_mul_f32_e32 v33, v55, v55
	v_fmac_f32_e32 v32, v52, v52
	v_fmac_f32_e32 v33, v54, v54
	v_add_f32_e32 v32, v32, v33
	v_mul_f32_e32 v33, v65, v65
	v_fmac_f32_e32 v33, v64, v64
	v_mul_f32_e32 v34, v17, v17
	v_mul_f32_e32 v35, v19, v19
	v_add_f32_e32 v32, v33, v32
	v_mul_f32_e32 v33, v67, v67
	v_fmac_f32_e32 v34, v16, v16
	v_fmac_f32_e32 v35, v18, v18
	v_fmac_f32_e32 v33, v66, v66
	v_add_f32_e32 v34, v34, v35
	v_mul_f32_e32 v35, v21, v21
	v_add_f32_e32 v32, v33, v32
	v_mul_f32_e32 v33, v23, v23
	v_fmac_f32_e32 v35, v20, v20
	v_fmac_f32_e32 v33, v22, v22
	v_add_f32_e32 v34, v35, v34
	v_add_f32_e32 v33, v33, v34
	v_add_f32_e32 v34, v32, v33
	v_mov_b32_e32 v35, v34
	s_nop 1
	v_permlane16_swap_b32_e32 v35, v34
	v_cvt_pk_bf16_f32 v32, v16, v17
	v_cvt_pk_bf16_f32 v33, v18, v19
	v_lshl_add_u64 v[18:19], v[76:77], 1, s[24:25]
	s_waitcnt lgkmcnt(0)
	v_add_f32_e32 v16, v34, v35
	v_mov_b32_e32 v17, v16
	s_nop 1
	v_permlane32_swap_b32_e32 v17, v16
	v_cvt_pk_bf16_f32 v34, v20, v21
	v_cvt_pk_bf16_f32 v35, v22, v23
	global_store_dwordx4 v[18:19], v[32:35], off
	s_and_saveexec_b64 s[56:57], s[8:9]
	s_cbranch_execz .LBB0_934
	v_lshl_add_u64 v[18:19], v[88:89], 2, s[16:17]
	s_waitcnt lgkmcnt(0)
	v_add_f32_e32 v16, v16, v17
	global_atomic_add_f32 v[18:19], v16, off

; __device__ __forceinline__ float sigmoid_f(float z) { return __builtin_amdgcn_rcpf(1.f + fexp(-z)); }
; __device__ __forceinline__ float rms_r(float ss) { return __builtin_amdgcn_rsqf(ss * (1.0f / DM) + RMS_EPS); }
; #define EPI_IT_ROW(it) EPI_ROW((it) >> 2, (it) & 3)
; #define EPI_PACK8(v0, v1) (u32x4){pk2((v0)[0], (v0)[1]), pk2((v0)[2], (v0)[3]), pk2((v1)[0], (v1)[1]), pk2((v1)[2], (v1)[3])}
;     __device__ __forceinline__ void operator()(AccRef acc, const Unit& u, int wr, int wc, int fr, int fq) const {
;     ...
;         for (int st = 0; st < 16; ++st) { const int it = st >> 1, bj = st & 1, ai = it >> 2, m = it & 3, row = EPI_IT_ROW(it);
;             if (st + 1 < 16) { const int it1 = (st + 1) >> 1, bj1 = (st + 1) & 1; const size_t p = (size_t)EPI_IT_ROW(it1) * DM + EPI_COL(bj1);
;                 xn0 = *(const f32x4*)(x + p); xn1 = *(const f32x4*)(x + p + 4); pn = *(const u32x4*)(pp + p);
;                 if (bj1 == 0) { sn_ = ssin[EPI_IT_ROW(it1)]; qn = ppss[EPI_IT_ROW(it1)]; } }
;             const float r = rms_r(sc), rp = rms_r(qc);
;             const size_t p = (size_t)row * DM + EPI_COL(bj);
;             const f32x4 p0 = (f32x4){bflo(pc.x), bfhi(pc.x), bflo(pc.y), bfhi(pc.y)}, p1 = (f32x4){bflo(pc.z), bfhi(pc.z), bflo(pc.w), bfhi(pc.w)};
;             const f32x4 z0 = acc[ai][bj][m][0] * r, z1 = acc[ai][bj][m][1] * r;
;             f32x4 g0, g1;
; #pragma unroll
;             for (int e = 0; e < 4; ++e) { g0[e] = sigmoid_f(z0[e]); g1[e] = sigmoid_f(z1[e]); }
;             const f32x4 x0 = xc0 + g0 * (p0 * rp) * pg[bj][0], x1 = xc1 + g1 * (p1 * rp) * pg[bj][1];
;             if (xo) { __builtin_nontemporal_store(x0, (f32x4*)(xo + p)); __builtin_nontemporal_store(x1, (f32x4*)(xo + p + 4)); }
;             *(u32x4*)(xb + p) = EPI_PACK8(x0, x1);
;             q += EPI_SQ8(x0, x1);
;             if (bj == 1) { q += __shfl_xor(q, 16); q += __shfl_xor(q, 32); if (fq == 0) atomicAdd(ssout + row, q); q = 0.f; sc = sn_; qc = qn; }
.LBB0_938:
	v_mul_f32_e32 v9, v9, v9
	v_fmac_f32_e32 v9, v8, v8
	v_mul_f32_e32 v8, v11, v11
	v_fmac_f32_e32 v8, v10, v10
	v_add_f32_e32 v8, v9, v8
	v_mul_f32_e32 v9, v13, v13
	v_fmac_f32_e32 v9, v12, v12
	v_mul_f32_e32 v10, v1, v1
	v_mul_f32_e32 v11, v3, v3
	v_add_f32_e32 v8, v9, v8
	v_mul_f32_e32 v9, v15, v15
	v_fmac_f32_e32 v10, v0, v0
	v_fmac_f32_e32 v11, v2, v2
	v_fmac_f32_e32 v9, v14, v14
	v_add_f32_e32 v10, v10, v11
	v_mul_f32_e32 v11, v5, v5
	v_add_f32_e32 v8, v9, v8
	v_mul_f32_e32 v9, v7, v7
	v_fmac_f32_e32 v11, v4, v4
	v_fmac_f32_e32 v9, v6, v6
	v_add_f32_e32 v10, v11, v10
	v_add_f32_e32 v9, v9, v10
	v_add_f32_e32 v10, v8, v9
	v_mov_b32_e32 v11, v10
	s_nop 1
	v_permlane16_swap_b32_e32 v11, v10
	v_cvt_pk_bf16_f32 v8, v0, v1
	v_cvt_pk_bf16_f32 v9, v2, v3
	v_lshl_add_u64 v[2:3], v[36:37], 1, s[24:25]
	s_waitcnt lgkmcnt(0)
	v_add_f32_e32 v0, v10, v11
	v_mov_b32_e32 v1, v0
	s_nop 1
	v_permlane32_swap_b32_e32 v1, v0
	v_cvt_pk_bf16_f32 v10, v4, v5
	v_cvt_pk_bf16_f32 v11, v6, v7
	global_store_dwordx4 v[2:3], v[8:11], off
	s_and_saveexec_b64 s[6:7], s[8:9]
	s_cbranch_execz .LBB0_940
	v_lshl_add_u64 v[2:3], v[72:73], 2, s[16:17]
	s_waitcnt lgkmcnt(0)
	v_add_f32_e32 v0, v0, v1
	global_atomic_add_f32 v[2:3], v0, off

; #define EPI_IT_ROW(it) EPI_ROW((it) >> 2, (it) & 3)
; #define EPI_PACK8(v0, v1) (u32x4){pk2((v0)[0], (v0)[1]), pk2((v0)[2], (v0)[3]), pk2((v1)[0], (v1)[1]), pk2((v1)[2], (v1)[3])}
;     __device__ __forceinline__ void operator()(AccRef acc, const Unit& u, int wr, int wc, int fr, int fq) const {
;         asm volatile("" : "+v"(fr), "+v"(fq));
;         f32x4 xc[2][2], xn[2][2];
; #pragma unroll
;         for (int bj = 0; bj < 2; ++bj) { const size_t p = (size_t)EPI_IT_ROW(0) * DM + EPI_COL(bj); xc[bj][0] = *(const f32x4*)(xin + p); xc[bj][1] = *(const f32x4*)(xin + p + 4); }
; #pragma unroll
;         for (int it = 0; it < 8; ++it) { const int ai = it >> 2, m = it & 3, row = EPI_IT_ROW(it);
;             if (it + 1 < 8) {
; #pragma unroll
;                 for (int bj = 0; bj < 2; ++bj) { const size_t p = (size_t)EPI_IT_ROW(it + 1) * DM + EPI_COL(bj); xn[bj][0] = *(const f32x4*)(xin + p); xn[bj][1] = *(const f32x4*)(xin + p + 4); } }
;             float q = 0.f;
; #pragma unroll
;             for (int bj = 0; bj < 2; ++bj) { const size_t p = (size_t)row * DM + EPI_COL(bj);
;                 const f32x4 x0 = xc[bj][0] + acc[ai][bj][m][0], x1 = xc[bj][1] + acc[ai][bj][m][1];
;                 __builtin_nontemporal_store(x0, (f32x4*)(xout + p)); __builtin_nontemporal_store(x1, (f32x4*)(xout + p + 4));
;                 *(u32x4*)(xb + p) = EPI_PACK8(x0, x1);
;                 q += EPI_SQ8(x0, x1); }
;             q += __shfl_xor(q, 16); q += __shfl_xor(q, 32);
;             if (fq == 0) atomicAdd(ssout + row, q);
; #pragma unroll
;             for (int bj = 0; bj < 2; ++bj) { xc[bj][0] = xn[bj][0]; xc[bj][1] = xn[bj][1]; } }
;     }
.LBB0_1317:
	s_lshl_b32 s1, s34, 8
	v_mov_b32_e32 v128, v180
	v_mov_b32_e32 v186, v177
	s_add_i32 s1, s1, s59
	s_lshl_b32 s0, s0, 8
	s_or_b32 s0, s0, s60
	v_add_u32_e32 v164, s1, v128
	v_ashrrev_i32_e32 v165, 31, v164
	v_lshl_add_u32 v162, v186, 3, s0
	v_lshlrev_b64 v[128:129], 12, v[164:165]
	v_ashrrev_i32_e32 v163, 31, v162
	v_add_u32_e32 v160, 0x80, v162
	v_lshl_add_u64 v[128:129], s[48:49], 0, v[128:129]
	v_lshlrev_b64 v[130:131], 2, v[162:163]
	v_ashrrev_i32_e32 v161, 31, v160
	v_lshl_add_u64 v[178:179], v[128:129], 0, v[130:131]
	v_lshlrev_b64 v[132:133], 2, v[160:161]
	global_load_dwordx4 v[170:173], v[178:179], off offset:16
	global_load_dwordx4 v[188:191], v[178:179], off
	v_lshl_add_u64 v[200:201], v[128:129], 0, v[132:133]
	global_load_dwordx4 v[192:195], v[200:201], off
	global_load_dwordx4 v[196:199], v[200:201], off offset:16
	v_add_u32_e32 v166, 16, v164
	v_ashrrev_i32_e32 v167, 31, v166
	v_lshlrev_b64 v[128:129], 12, v[166:167]
	v_lshl_add_u64 v[128:129], s[48:49], 0, v[128:129]
	v_lshl_add_u64 v[174:175], v[128:129], 0, v[130:131]
	v_lshl_add_u64 v[168:169], v[128:129], 0, v[132:133]
	global_load_dwordx4 v[136:139], v[174:175], off offset:16
	global_load_dwordx4 v[140:143], v[174:175], off
	global_load_dwordx4 v[128:131], v[168:169], off offset:16
	global_load_dwordx4 v[132:135], v[168:169], off
	v_and_b32_e32 v202, 64, v185
	v_xor_b32_e32 v187, 16, v185
	v_add_u32_e32 v202, 64, v202
	v_cmp_lt_i32_e64 s[0:1], v187, v202
	v_cmp_eq_u32_e32 vcc, 0, v186
	v_xor_b32_e32 v203, 32, v185
	v_cndmask_b32_e64 v186, v185, v187, s[0:1]
	v_lshlrev_b32_e32 v186, 2, v186
	v_cmp_lt_i32_e64 s[0:1], v203, v202
	s_waitcnt vmcnt(0)
	v_pk_add_f32 v[122:123], v[122:123], v[172:173]
	v_pk_add_f32 v[126:127], v[126:127], v[190:191]
	v_pk_add_f32 v[124:125], v[124:125], v[188:189]
	v_pk_add_f32 v[118:119], v[118:119], v[194:195]
	v_pk_add_f32 v[116:117], v[116:117], v[192:193]
	v_pk_add_f32 v[120:121], v[120:121], v[170:171]
	v_pk_add_f32 v[170:171], v[112:113], v[196:197]
	global_store_dwordx4 v[178:179], v[124:127], off nt
	global_store_dwordx4 v[178:179], v[120:123], off offset:16 nt
	v_cvt_pk_bf16_f32 v112, v124, v125
	v_cvt_pk_bf16_f32 v113, v126, v127
	v_mul_f32_e32 v178, v117, v117
	v_mul_f32_e32 v125, v125, v125
	v_mul_f32_e32 v127, v127, v127
	v_mul_f32_e32 v179, v119, v119
	v_pk_add_f32 v[172:173], v[114:115], v[198:199]
	v_cvt_pk_bf16_f32 v114, v120, v121
	v_cvt_pk_bf16_f32 v115, v122, v123
	v_mul_f32_e32 v121, v121, v121
	v_mul_f32_e32 v123, v123, v123
	v_mul_f32_e32 v189, v171, v171
	v_fmac_f32_e32 v125, v124, v124
	v_fmac_f32_e32 v127, v126, v126
	v_fmac_f32_e32 v178, v116, v116
	v_fmac_f32_e32 v179, v118, v118
	v_mul_f32_e32 v190, v173, v173
	v_fmac_f32_e32 v121, v120, v120
	v_fmac_f32_e32 v123, v122, v122
	v_fmac_f32_e32 v189, v170, v170
	v_add_f32_e32 v120, v125, v127
	v_add_f32_e32 v122, v178, v179
	v_fmac_f32_e32 v190, v172, v172
	v_add_f32_e32 v120, v120, v121
	v_add_f32_e32 v121, v122, v189
	v_add_f32_e32 v120, v123, v120
	v_add_f32_e32 v121, v190, v121
	v_add_f32_e32 v120, v120, v121
	v_mov_b32_e32 v121, v120
	s_nop 1
	v_permlane16_swap_b32_e32 v121, v120
	v_cndmask_b32_e64 v187, v185, v203, s[0:1]
	v_lshlrev_b64 v[202:203], 10, v[164:165]
	v_lshl_add_u64 v[204:205], v[202:203], 0, v[162:163]
	v_lshl_add_u64 v[204:205], v[204:205], 1, s[24:25]
	global_store_dwordx4 v[204:205], v[112:115], off
	global_store_dwordx4 v[200:201], v[116:119], off nt
	global_store_dwordx4 v[200:201], v[170:173], off offset:16 nt
	s_waitcnt lgkmcnt(0)
	v_add_f32_e32 v112, v120, v121
	v_lshlrev_b32_e32 v187, 2, v187
	v_mov_b32_e32 v113, v112
	s_nop 1
	v_permlane32_swap_b32_e32 v113, v112
	v_lshl_add_u64 v[202:203], v[202:203], 0, v[160:161]
	v_lshl_add_u64 v[114:115], v[202:203], 1, s[24:25]
	v_cvt_pk_bf16_f32 v188, v116, v117
	v_cvt_pk_bf16_f32 v189, v118, v119
	v_cvt_pk_bf16_f32 v190, v170, v171
	v_cvt_pk_bf16_f32 v191, v172, v173
	global_store_dwordx4 v[114:115], v[188:191], off
	s_and_saveexec_b64 s[0:1], vcc
	v_readlane_b32 s72, v254, 6
	v_readlane_b32 s73, v254, 7
	v_readlane_b32 s74, v254, 8
	v_readlane_b32 s75, v254, 9
	s_cbranch_execz .LBB0_1319
	v_lshl_add_u64 v[114:115], v[164:165], 2, s[10:11]
	s_waitcnt lgkmcnt(0)
	v_add_f32_e32 v112, v112, v113
	global_atomic_add_f32 v[114:115], v112, off
; #define EPI_IT_ROW(it) EPI_ROW((it) >> 2, (it) & 3)
; #define EPI_PACK8(v0, v1) (u32x4){pk2((v0)[0], (v0)[1]), pk2((v0)[2], (v0)[3]), pk2((v1)[0], (v1)[1]), pk2((v1)[2], (v1)[3])}
;     __device__ __forceinline__ void operator()(AccRef acc, const Unit& u, int wr, int wc, int fr, int fq) const {
;         asm volatile("" : "+v"(fr), "+v"(fq));
;         f32x4 xc[2][2], xn[2][2];
; #pragma unroll
;         for (int bj = 0; bj < 2; ++bj) { const size_t p = (size_t)EPI_IT_ROW(0) * DM + EPI_COL(bj); xc[bj][0] = *(const f32x4*)(xin + p); xc[bj][1] = *(const f32x4*)(xin + p + 4); }
; #pragma unroll
;         for (int it = 0; it < 8; ++it) { const int ai = it >> 2, m = it & 3, row = EPI_IT_ROW(it);
;             if (it + 1 < 8) {
; #pragma unroll
;                 for (int bj = 0; bj < 2; ++bj) { const size_t p = (size_t)EPI_IT_ROW(it + 1) * DM + EPI_COL(bj); xn[bj][0] = *(const f32x4*)(xin + p); xn[bj][1] = *(const f32x4*)(xin + p + 4); } }
;             float q = 0.f;
; #pragma unroll
;             for (int bj = 0; bj < 2; ++bj) { const size_t p = (size_t)row * DM + EPI_COL(bj);
;                 const f32x4 x0 = xc[bj][0] + acc[ai][bj][m][0], x1 = xc[bj][1] + acc[ai][bj][m][1];
;                 __builtin_nontemporal_store(x0, (f32x4*)(xout + p)); __builtin_nontemporal_store(x1, (f32x4*)(xout + p + 4));
;                 *(u32x4*)(xb + p) = EPI_PACK8(x0, x1);
;                 q += EPI_SQ8(x0, x1); }
;             q += __shfl_xor(q, 16); q += __shfl_xor(q, 32);
;             if (fq == 0) atomicAdd(ssout + row, q);
; #pragma unroll
;             for (int bj = 0; bj < 2; ++bj) { xc[bj][0] = xn[bj][0]; xc[bj][1] = xn[bj][1]; } }
;     }
.LBB0_1319:
	s_or_b64 exec, exec, s[0:1]
	v_add_u32_e32 v170, 32, v164
	v_ashrrev_i32_e32 v171, 31, v170
	s_waitcnt lgkmcnt(0)
	v_lshlrev_b64 v[112:113], 12, v[170:171]
	v_lshl_add_u64 v[112:113], s[48:49], 0, v[112:113]
	v_lshl_add_u64 v[178:179], v[162:163], 2, v[112:113]
	v_lshl_add_u64 v[172:173], v[160:161], 2, v[112:113]
	global_load_dwordx4 v[120:123], v[178:179], off offset:16
	global_load_dwordx4 v[124:127], v[178:179], off
	global_load_dwordx4 v[112:115], v[172:173], off offset:16
	global_load_dwordx4 v[116:119], v[172:173], off
	v_pk_add_f32 v[110:111], v[110:111], v[142:143]
	v_pk_add_f32 v[108:109], v[108:109], v[140:141]
	v_pk_add_f32 v[106:107], v[106:107], v[138:139]
	v_pk_add_f32 v[104:105], v[104:105], v[136:137]
	global_store_dwordx4 v[174:175], v[108:111], off nt
	global_store_dwordx4 v[174:175], v[104:107], off offset:16 nt
	v_cvt_pk_bf16_f32 v136, v108, v109
	v_cvt_pk_bf16_f32 v138, v104, v105
	v_pk_add_f32 v[102:103], v[102:103], v[134:135]
	v_mul_f32_e32 v109, v109, v109
	v_fmac_f32_e32 v109, v108, v108
	v_mul_f32_e32 v108, v111, v111
	v_fmac_f32_e32 v108, v110, v110
	v_mul_f32_e32 v105, v105, v105
	v_add_f32_e32 v108, v109, v108
	v_fmac_f32_e32 v105, v104, v104
	v_add_f32_e32 v104, v108, v105
	v_mul_f32_e32 v105, v107, v107
	v_fmac_f32_e32 v105, v106, v106
	v_pk_add_f32 v[100:101], v[100:101], v[132:133]
	v_cvt_pk_bf16_f32 v137, v110, v111
	v_add_f32_e32 v110, v105, v104
	v_pk_add_f32 v[104:105], v[96:97], v[128:129]
	v_mul_f32_e32 v96, v101, v101
	v_mul_f32_e32 v97, v103, v103
	v_fmac_f32_e32 v96, v100, v100
	v_fmac_f32_e32 v97, v102, v102
	v_add_f32_e32 v96, v96, v97
	v_mul_f32_e32 v97, v105, v105
	v_cvt_pk_bf16_f32 v139, v106, v107
	v_pk_add_f32 v[106:107], v[98:99], v[130:131]
	v_fmac_f32_e32 v97, v104, v104
	v_add_f32_e32 v96, v96, v97
	v_mul_f32_e32 v97, v107, v107
	v_fmac_f32_e32 v97, v106, v106
	v_add_f32_e32 v96, v97, v96
	v_add_f32_e32 v96, v110, v96
	v_mov_b32_e32 v97, v96
	s_nop 1
	v_permlane16_swap_b32_e32 v97, v96
	v_lshlrev_b64 v[188:189], 10, v[166:167]
	v_lshl_add_u64 v[190:191], v[188:189], 0, v[162:163]
	v_lshl_add_u64 v[140:141], v[190:191], 1, s[24:25]
	v_lshl_add_u64 v[108:109], v[188:189], 0, v[160:161]
	s_waitcnt lgkmcnt(0)
	v_add_f32_e32 v96, v96, v97
	v_mov_b32_e32 v97, v96
	s_nop 1
	v_permlane32_swap_b32_e32 v97, v96
	global_store_dwordx4 v[140:141], v[136:139], off
	global_store_dwordx4 v[168:169], v[100:103], off nt
	global_store_dwordx4 v[168:169], v[104:107], off offset:16 nt
	v_cvt_pk_bf16_f32 v99, v102, v103
	v_cvt_pk_bf16_f32 v98, v100, v101
	s_nop 0
	v_lshl_add_u64 v[102:103], v[108:109], 1, s[24:25]
	v_cvt_pk_bf16_f32 v100, v104, v105
	v_cvt_pk_bf16_f32 v101, v106, v107
	global_store_dwordx4 v[102:103], v[98:101], off
	s_and_saveexec_b64 s[0:1], vcc
	s_cbranch_execz .LBB0_1321
	v_lshl_add_u64 v[98:99], v[166:167], 2, s[10:11]
	s_waitcnt lgkmcnt(0)
	v_add_f32_e32 v96, v96, v97
	global_atomic_add_f32 v[98:99], v96, off
.LBB0_1321:
	s_or_b64 exec, exec, s[0:1]
	v_add_u32_e32 v128, 48, v164
	v_ashrrev_i32_e32 v129, 31, v128
	s_waitcnt lgkmcnt(0)
	v_lshlrev_b64 v[96:97], 12, v[128:129]
	v_lshl_add_u64 v[96:97], s[48:49], 0, v[96:97]
	v_lshl_add_u64 v[132:133], v[162:163], 2, v[96:97]
	v_lshl_add_u64 v[130:131], v[160:161], 2, v[96:97]
	global_load_dwordx4 v[104:107], v[132:133], off offset:16
	global_load_dwordx4 v[108:111], v[132:133], off
	global_load_dwordx4 v[96:99], v[130:131], off offset:16
	global_load_dwordx4 v[100:103], v[130:131], off
	s_waitcnt vmcnt(12)
	v_pk_add_f32 v[94:95], v[94:95], v[126:127]
	v_pk_add_f32 v[92:93], v[92:93], v[124:125]
	v_pk_add_f32 v[90:91], v[90:91], v[122:123]
	v_pk_add_f32 v[88:89], v[88:89], v[120:121]
	global_store_dwordx4 v[178:179], v[92:95], off nt
	global_store_dwordx4 v[178:179], v[88:91], off offset:16 nt
	v_cvt_pk_bf16_f32 v120, v92, v93
	v_cvt_pk_bf16_f32 v122, v88, v89
	s_waitcnt vmcnt(12)
	v_pk_add_f32 v[86:87], v[86:87], v[118:119]
	v_mul_f32_e32 v93, v93, v93
	v_fmac_f32_e32 v93, v92, v92
	v_mul_f32_e32 v92, v95, v95
	v_fmac_f32_e32 v92, v94, v94
	v_mul_f32_e32 v89, v89, v89
	v_add_f32_e32 v92, v93, v92
	v_fmac_f32_e32 v89, v88, v88
	v_add_f32_e32 v88, v92, v89
	v_mul_f32_e32 v89, v91, v91
	v_fmac_f32_e32 v89, v90, v90
	v_pk_add_f32 v[84:85], v[84:85], v[116:117]
	v_cvt_pk_bf16_f32 v121, v94, v95
	v_add_f32_e32 v94, v89, v88
	v_pk_add_f32 v[88:89], v[80:81], v[112:113]
	v_mul_f32_e32 v80, v85, v85
	v_mul_f32_e32 v81, v87, v87
	v_fmac_f32_e32 v80, v84, v84
	v_fmac_f32_e32 v81, v86, v86
	v_add_f32_e32 v80, v80, v81
	v_mul_f32_e32 v81, v89, v89
	v_cvt_pk_bf16_f32 v123, v90, v91
	v_pk_add_f32 v[90:91], v[82:83], v[114:115]
	v_fmac_f32_e32 v81, v88, v88
	v_add_f32_e32 v80, v80, v81
	v_mul_f32_e32 v81, v91, v91
	v_fmac_f32_e32 v81, v90, v90
	v_add_f32_e32 v80, v81, v80
	v_add_f32_e32 v80, v94, v80
	v_mov_b32_e32 v81, v80
	s_nop 1
	v_permlane16_swap_b32_e32 v81, v80
	v_lshlrev_b64 v[134:135], 10, v[170:171]
	v_lshl_add_u64 v[136:137], v[134:135], 0, v[162:163]
	v_lshl_add_u64 v[124:125], v[136:137], 1, s[24:25]
	v_lshl_add_u64 v[92:93], v[134:135], 0, v[160:161]
	s_waitcnt lgkmcnt(0)
	v_add_f32_e32 v80, v80, v81
	v_mov_b32_e32 v81, v80
	s_nop 1
	v_permlane32_swap_b32_e32 v81, v80
	global_store_dwordx4 v[124:125], v[120:123], off
	global_store_dwordx4 v[172:173], v[84:87], off nt
	global_store_dwordx4 v[172:173], v[88:91], off offset:16 nt
	v_cvt_pk_bf16_f32 v83, v86, v87
	v_cvt_pk_bf16_f32 v82, v84, v85
	s_nop 0
	v_lshl_add_u64 v[86:87], v[92:93], 1, s[24:25]
	v_cvt_pk_bf16_f32 v84, v88, v89
	v_cvt_pk_bf16_f32 v85, v90, v91
	global_store_dwordx4 v[86:87], v[82:85], off
	s_and_saveexec_b64 s[0:1], vcc
	s_cbranch_execz .LBB0_1323
	v_lshl_add_u64 v[82:83], v[170:171], 2, s[10:11]
	s_waitcnt lgkmcnt(0)
	v_add_f32_e32 v80, v80, v81
	global_atomic_add_f32 v[82:83], v80, off
; #define EPI_IT_ROW(it) EPI_ROW((it) >> 2, (it) & 3)
; #define EPI_PACK8(v0, v1) (u32x4){pk2((v0)[0], (v0)[1]), pk2((v0)[2], (v0)[3]), pk2((v1)[0], (v1)[1]), pk2((v1)[2], (v1)[3])}
;     __device__ __forceinline__ void operator()(AccRef acc, const Unit& u, int wr, int wc, int fr, int fq) const {
;         asm volatile("" : "+v"(fr), "+v"(fq));
;         f32x4 xc[2][2], xn[2][2];
; #pragma unroll
;         for (int bj = 0; bj < 2; ++bj) { const size_t p = (size_t)EPI_IT_ROW(0) * DM + EPI_COL(bj); xc[bj][0] = *(const f32x4*)(xin + p); xc[bj][1] = *(const f32x4*)(xin + p + 4); }
; #pragma unroll
;         for (int it = 0; it < 8; ++it) { const int ai = it >> 2, m = it & 3, row = EPI_IT_ROW(it);
;             if (it + 1 < 8) {
; #pragma unroll
;                 for (int bj = 0; bj < 2; ++bj) { const size_t p = (size_t)EPI_IT_ROW(it + 1) * DM + EPI_COL(bj); xn[bj][0] = *(const f32x4*)(xin + p); xn[bj][1] = *(const f32x4*)(xin + p + 4); } }
;             float q = 0.f;
; #pragma unroll
;             for (int bj = 0; bj < 2; ++bj) { const size_t p = (size_t)row * DM + EPI_COL(bj);
;                 const f32x4 x0 = xc[bj][0] + acc[ai][bj][m][0], x1 = xc[bj][1] + acc[ai][bj][m][1];
;                 __builtin_nontemporal_store(x0, (f32x4*)(xout + p)); __builtin_nontemporal_store(x1, (f32x4*)(xout + p + 4));
;                 *(u32x4*)(xb + p) = EPI_PACK8(x0, x1);
;                 q += EPI_SQ8(x0, x1); }
;             q += __shfl_xor(q, 16); q += __shfl_xor(q, 32);
;             if (fq == 0) atomicAdd(ssout + row, q);
; #pragma unroll
;             for (int bj = 0; bj < 2; ++bj) { xc[bj][0] = xn[bj][0]; xc[bj][1] = xn[bj][1]; } }
;     }
.LBB0_1323:
	s_or_b64 exec, exec, s[0:1]
	v_add_u32_e32 v112, 0x80, v164
	v_ashrrev_i32_e32 v113, 31, v112
	s_waitcnt lgkmcnt(0)
	v_lshlrev_b64 v[80:81], 12, v[112:113]
	v_lshl_add_u64 v[80:81], s[48:49], 0, v[80:81]
	v_lshl_add_u64 v[116:117], v[162:163], 2, v[80:81]
	v_lshl_add_u64 v[114:115], v[160:161], 2, v[80:81]
	global_load_dwordx4 v[88:91], v[116:117], off offset:16
	global_load_dwordx4 v[92:95], v[116:117], off
	global_load_dwordx4 v[80:83], v[114:115], off offset:16
	global_load_dwordx4 v[84:87], v[114:115], off
	s_waitcnt vmcnt(12)
	v_pk_add_f32 v[78:79], v[78:79], v[110:111]
	v_pk_add_f32 v[76:77], v[76:77], v[108:109]
	v_pk_add_f32 v[74:75], v[74:75], v[106:107]
	v_pk_add_f32 v[72:73], v[72:73], v[104:105]
	global_store_dwordx4 v[132:133], v[76:79], off nt
	global_store_dwordx4 v[132:133], v[72:75], off offset:16 nt
	v_cvt_pk_bf16_f32 v104, v76, v77
	v_cvt_pk_bf16_f32 v106, v72, v73
	s_waitcnt vmcnt(12)
	v_pk_add_f32 v[70:71], v[70:71], v[102:103]
	v_mul_f32_e32 v77, v77, v77
	v_fmac_f32_e32 v77, v76, v76
	v_mul_f32_e32 v76, v79, v79
	v_fmac_f32_e32 v76, v78, v78
	v_mul_f32_e32 v73, v73, v73
	v_add_f32_e32 v76, v77, v76
	v_fmac_f32_e32 v73, v72, v72
	v_add_f32_e32 v72, v76, v73
	v_mul_f32_e32 v73, v75, v75
	v_fmac_f32_e32 v73, v74, v74
	v_pk_add_f32 v[68:69], v[68:69], v[100:101]
	v_cvt_pk_bf16_f32 v105, v78, v79
	v_add_f32_e32 v78, v73, v72
	v_pk_add_f32 v[72:73], v[64:65], v[96:97]
	v_mul_f32_e32 v64, v69, v69
	v_mul_f32_e32 v65, v71, v71
	v_fmac_f32_e32 v64, v68, v68
	v_fmac_f32_e32 v65, v70, v70
	v_add_f32_e32 v64, v64, v65
	v_mul_f32_e32 v65, v73, v73
	v_cvt_pk_bf16_f32 v107, v74, v75
	v_pk_add_f32 v[74:75], v[66:67], v[98:99]
	v_fmac_f32_e32 v65, v72, v72
	v_add_f32_e32 v64, v64, v65
	v_mul_f32_e32 v65, v75, v75
	v_fmac_f32_e32 v65, v74, v74
	v_add_f32_e32 v64, v65, v64
	v_add_f32_e32 v64, v78, v64
	v_mov_b32_e32 v65, v64
	s_nop 1
	v_permlane16_swap_b32_e32 v65, v64
	v_lshlrev_b64 v[118:119], 10, v[128:129]
	v_lshl_add_u64 v[120:121], v[118:119], 0, v[162:163]
	v_lshl_add_u64 v[108:109], v[120:121], 1, s[24:25]
	v_lshl_add_u64 v[76:77], v[118:119], 0, v[160:161]
	s_waitcnt lgkmcnt(0)
	v_add_f32_e32 v64, v64, v65
	v_mov_b32_e32 v65, v64
	s_nop 1
	v_permlane32_swap_b32_e32 v65, v64
	global_store_dwordx4 v[108:109], v[104:107], off
	global_store_dwordx4 v[130:131], v[68:71], off nt
	global_store_dwordx4 v[130:131], v[72:75], off offset:16 nt
	v_cvt_pk_bf16_f32 v67, v70, v71
	v_cvt_pk_bf16_f32 v66, v68, v69
	s_nop 0
	v_lshl_add_u64 v[70:71], v[76:77], 1, s[24:25]
	v_cvt_pk_bf16_f32 v68, v72, v73
	v_cvt_pk_bf16_f32 v69, v74, v75
	global_store_dwordx4 v[70:71], v[66:69], off
	s_and_saveexec_b64 s[0:1], vcc
	s_cbranch_execz .LBB0_1325
	v_lshl_add_u64 v[66:67], v[128:129], 2, s[10:11]
	s_waitcnt lgkmcnt(0)
	v_add_f32_e32 v64, v64, v65
	global_atomic_add_f32 v[66:67], v64, off
.LBB0_1325:
	s_or_b64 exec, exec, s[0:1]
	v_add_u32_e32 v96, 0x90, v164
	v_ashrrev_i32_e32 v97, 31, v96
	s_waitcnt lgkmcnt(0)
	v_lshlrev_b64 v[64:65], 12, v[96:97]
	v_lshl_add_u64 v[64:65], s[48:49], 0, v[64:65]
	v_lshl_add_u64 v[100:101], v[162:163], 2, v[64:65]
	v_lshl_add_u64 v[98:99], v[160:161], 2, v[64:65]
	global_load_dwordx4 v[72:75], v[100:101], off offset:16
	global_load_dwordx4 v[76:79], v[100:101], off
	global_load_dwordx4 v[64:67], v[98:99], off offset:16
	global_load_dwordx4 v[68:71], v[98:99], off
	s_waitcnt vmcnt(12)
	v_pk_add_f32 v[62:63], v[62:63], v[94:95]
	v_pk_add_f32 v[60:61], v[60:61], v[92:93]
	v_pk_add_f32 v[58:59], v[58:59], v[90:91]
	v_pk_add_f32 v[56:57], v[56:57], v[88:89]
	global_store_dwordx4 v[116:117], v[60:63], off nt
	global_store_dwordx4 v[116:117], v[56:59], off offset:16 nt
	v_cvt_pk_bf16_f32 v88, v60, v61
	v_cvt_pk_bf16_f32 v90, v56, v57
	s_waitcnt vmcnt(12)
	v_pk_add_f32 v[54:55], v[54:55], v[86:87]
	v_mul_f32_e32 v61, v61, v61
	v_fmac_f32_e32 v61, v60, v60
	v_mul_f32_e32 v60, v63, v63
	v_fmac_f32_e32 v60, v62, v62
	v_mul_f32_e32 v57, v57, v57
	v_add_f32_e32 v60, v61, v60
	v_fmac_f32_e32 v57, v56, v56
	v_add_f32_e32 v56, v60, v57
	v_mul_f32_e32 v57, v59, v59
	v_fmac_f32_e32 v57, v58, v58
	v_pk_add_f32 v[52:53], v[52:53], v[84:85]
	v_cvt_pk_bf16_f32 v89, v62, v63
	v_add_f32_e32 v62, v57, v56
	v_pk_add_f32 v[56:57], v[48:49], v[80:81]
	v_mul_f32_e32 v48, v53, v53
	v_mul_f32_e32 v49, v55, v55
	v_fmac_f32_e32 v48, v52, v52
	v_fmac_f32_e32 v49, v54, v54
	v_add_f32_e32 v48, v48, v49
	v_mul_f32_e32 v49, v57, v57
	v_cvt_pk_bf16_f32 v91, v58, v59
	v_pk_add_f32 v[58:59], v[50:51], v[82:83]
	v_fmac_f32_e32 v49, v56, v56
	v_add_f32_e32 v48, v48, v49
	v_mul_f32_e32 v49, v59, v59
	v_fmac_f32_e32 v49, v58, v58
	v_add_f32_e32 v48, v49, v48
	v_add_f32_e32 v48, v62, v48
	v_mov_b32_e32 v49, v48
	s_nop 1
	v_permlane16_swap_b32_e32 v49, v48
	v_lshlrev_b64 v[102:103], 10, v[112:113]
	v_lshl_add_u64 v[104:105], v[102:103], 0, v[162:163]
	v_lshl_add_u64 v[92:93], v[104:105], 1, s[24:25]
	v_lshl_add_u64 v[60:61], v[102:103], 0, v[160:161]
	s_waitcnt lgkmcnt(0)
	v_add_f32_e32 v48, v48, v49
	v_mov_b32_e32 v49, v48
	s_nop 1
	v_permlane32_swap_b32_e32 v49, v48
	global_store_dwordx4 v[92:93], v[88:91], off
	global_store_dwordx4 v[114:115], v[52:55], off nt
	global_store_dwordx4 v[114:115], v[56:59], off offset:16 nt
	v_cvt_pk_bf16_f32 v51, v54, v55
	v_cvt_pk_bf16_f32 v50, v52, v53
	s_nop 0
	v_lshl_add_u64 v[54:55], v[60:61], 1, s[24:25]
	v_cvt_pk_bf16_f32 v52, v56, v57
	v_cvt_pk_bf16_f32 v53, v58, v59
	global_store_dwordx4 v[54:55], v[50:53], off
	s_and_saveexec_b64 s[0:1], vcc
	s_cbranch_execz .LBB0_1327
	v_lshl_add_u64 v[50:51], v[112:113], 2, s[10:11]
	s_waitcnt lgkmcnt(0)
	v_add_f32_e32 v48, v48, v49
	global_atomic_add_f32 v[50:51], v48, off
; #define EPI_IT_ROW(it) EPI_ROW((it) >> 2, (it) & 3)
; #define EPI_PACK8(v0, v1) (u32x4){pk2((v0)[0], (v0)[1]), pk2((v0)[2], (v0)[3]), pk2((v1)[0], (v1)[1]), pk2((v1)[2], (v1)[3])}
;     __device__ __forceinline__ void operator()(AccRef acc, const Unit& u, int wr, int wc, int fr, int fq) const {
;         asm volatile("" : "+v"(fr), "+v"(fq));
;         f32x4 xc[2][2], xn[2][2];
; #pragma unroll
;         for (int bj = 0; bj < 2; ++bj) { const size_t p = (size_t)EPI_IT_ROW(0) * DM + EPI_COL(bj); xc[bj][0] = *(const f32x4*)(xin + p); xc[bj][1] = *(const f32x4*)(xin + p + 4); }
; #pragma unroll
;         for (int it = 0; it < 8; ++it) { const int ai = it >> 2, m = it & 3, row = EPI_IT_ROW(it);
;             if (it + 1 < 8) {
; #pragma unroll
;                 for (int bj = 0; bj < 2; ++bj) { const size_t p = (size_t)EPI_IT_ROW(it + 1) * DM + EPI_COL(bj); xn[bj][0] = *(const f32x4*)(xin + p); xn[bj][1] = *(const f32x4*)(xin + p + 4); } }
;             float q = 0.f;
; #pragma unroll
;             for (int bj = 0; bj < 2; ++bj) { const size_t p = (size_t)row * DM + EPI_COL(bj);
;                 const f32x4 x0 = xc[bj][0] + acc[ai][bj][m][0], x1 = xc[bj][1] + acc[ai][bj][m][1];
;                 __builtin_nontemporal_store(x0, (f32x4*)(xout + p)); __builtin_nontemporal_store(x1, (f32x4*)(xout + p + 4));
;                 *(u32x4*)(xb + p) = EPI_PACK8(x0, x1);
;                 q += EPI_SQ8(x0, x1); }
;             q += __shfl_xor(q, 16); q += __shfl_xor(q, 32);
;             if (fq == 0) atomicAdd(ssout + row, q);
; #pragma unroll
;             for (int bj = 0; bj < 2; ++bj) { xc[bj][0] = xn[bj][0]; xc[bj][1] = xn[bj][1]; } }
;     }
.LBB0_1327:
	s_or_b64 exec, exec, s[0:1]
	v_add_u32_e32 v80, 0xa0, v164
	v_ashrrev_i32_e32 v81, 31, v80
	s_waitcnt lgkmcnt(0)
	v_lshlrev_b64 v[48:49], 12, v[80:81]
	v_lshl_add_u64 v[48:49], s[48:49], 0, v[48:49]
	v_lshl_add_u64 v[84:85], v[162:163], 2, v[48:49]
	v_lshl_add_u64 v[82:83], v[160:161], 2, v[48:49]
	global_load_dwordx4 v[56:59], v[84:85], off offset:16
	global_load_dwordx4 v[60:63], v[84:85], off
	global_load_dwordx4 v[48:51], v[82:83], off offset:16
	global_load_dwordx4 v[52:55], v[82:83], off
	s_waitcnt vmcnt(12)
	v_pk_add_f32 v[46:47], v[46:47], v[78:79]
	v_pk_add_f32 v[44:45], v[44:45], v[76:77]
	v_pk_add_f32 v[42:43], v[42:43], v[74:75]
	v_pk_add_f32 v[40:41], v[40:41], v[72:73]
	global_store_dwordx4 v[100:101], v[44:47], off nt
	global_store_dwordx4 v[100:101], v[40:43], off offset:16 nt
	v_cvt_pk_bf16_f32 v72, v44, v45
	v_cvt_pk_bf16_f32 v74, v40, v41
	s_waitcnt vmcnt(12)
	v_pk_add_f32 v[38:39], v[38:39], v[70:71]
	v_mul_f32_e32 v45, v45, v45
	v_fmac_f32_e32 v45, v44, v44
	v_mul_f32_e32 v44, v47, v47
	v_fmac_f32_e32 v44, v46, v46
	v_mul_f32_e32 v41, v41, v41
	v_add_f32_e32 v44, v45, v44
	v_fmac_f32_e32 v41, v40, v40
	v_add_f32_e32 v40, v44, v41
	v_mul_f32_e32 v41, v43, v43
	v_fmac_f32_e32 v41, v42, v42
	v_pk_add_f32 v[36:37], v[36:37], v[68:69]
	v_cvt_pk_bf16_f32 v73, v46, v47
	v_add_f32_e32 v46, v41, v40
	v_pk_add_f32 v[40:41], v[32:33], v[64:65]
	v_mul_f32_e32 v32, v37, v37
	v_mul_f32_e32 v33, v39, v39
	v_fmac_f32_e32 v32, v36, v36
	v_fmac_f32_e32 v33, v38, v38
	v_add_f32_e32 v32, v32, v33
	v_mul_f32_e32 v33, v41, v41
	v_cvt_pk_bf16_f32 v75, v42, v43
	v_pk_add_f32 v[42:43], v[34:35], v[66:67]
	v_fmac_f32_e32 v33, v40, v40
	v_add_f32_e32 v32, v32, v33
	v_mul_f32_e32 v33, v43, v43
	v_fmac_f32_e32 v33, v42, v42
	v_add_f32_e32 v32, v33, v32
	v_add_f32_e32 v32, v46, v32
	v_mov_b32_e32 v33, v32
	s_nop 1
	v_permlane16_swap_b32_e32 v33, v32
	v_lshlrev_b64 v[86:87], 10, v[96:97]
	v_lshl_add_u64 v[88:89], v[86:87], 0, v[162:163]
	v_lshl_add_u64 v[76:77], v[88:89], 1, s[24:25]
	v_lshl_add_u64 v[44:45], v[86:87], 0, v[160:161]
	s_waitcnt lgkmcnt(0)
	v_add_f32_e32 v32, v32, v33
	v_mov_b32_e32 v33, v32
	s_nop 1
	v_permlane32_swap_b32_e32 v33, v32
	global_store_dwordx4 v[76:77], v[72:75], off
	global_store_dwordx4 v[98:99], v[36:39], off nt
	global_store_dwordx4 v[98:99], v[40:43], off offset:16 nt
	v_cvt_pk_bf16_f32 v35, v38, v39
	v_cvt_pk_bf16_f32 v34, v36, v37
	s_nop 0
	v_lshl_add_u64 v[38:39], v[44:45], 1, s[24:25]
	v_cvt_pk_bf16_f32 v36, v40, v41
	v_cvt_pk_bf16_f32 v37, v42, v43
	global_store_dwordx4 v[38:39], v[34:37], off
	s_and_saveexec_b64 s[0:1], vcc
	s_cbranch_execz .LBB0_1329
	v_lshl_add_u64 v[34:35], v[96:97], 2, s[10:11]
	s_waitcnt lgkmcnt(0)
	v_add_f32_e32 v32, v32, v33
	global_atomic_add_f32 v[34:35], v32, off
; #define EPI_IT_ROW(it) EPI_ROW((it) >> 2, (it) & 3)
; #define EPI_PACK8(v0, v1) (u32x4){pk2((v0)[0], (v0)[1]), pk2((v0)[2], (v0)[3]), pk2((v1)[0], (v1)[1]), pk2((v1)[2], (v1)[3])}
;     __device__ __forceinline__ void operator()(AccRef acc, const Unit& u, int wr, int wc, int fr, int fq) const {
;         asm volatile("" : "+v"(fr), "+v"(fq));
;         f32x4 xc[2][2], xn[2][2];
; #pragma unroll
;         for (int bj = 0; bj < 2; ++bj) { const size_t p = (size_t)EPI_IT_ROW(0) * DM + EPI_COL(bj); xc[bj][0] = *(const f32x4*)(xin + p); xc[bj][1] = *(const f32x4*)(xin + p + 4); }
; #pragma unroll
;         for (int it = 0; it < 8; ++it) { const int ai = it >> 2, m = it & 3, row = EPI_IT_ROW(it);
;             if (it + 1 < 8) {
; #pragma unroll
;                 for (int bj = 0; bj < 2; ++bj) { const size_t p = (size_t)EPI_IT_ROW(it + 1) * DM + EPI_COL(bj); xn[bj][0] = *(const f32x4*)(xin + p); xn[bj][1] = *(const f32x4*)(xin + p + 4); } }
;             float q = 0.f;
; #pragma unroll
;             for (int bj = 0; bj < 2; ++bj) { const size_t p = (size_t)row * DM + EPI_COL(bj);
;                 const f32x4 x0 = xc[bj][0] + acc[ai][bj][m][0], x1 = xc[bj][1] + acc[ai][bj][m][1];
;                 __builtin_nontemporal_store(x0, (f32x4*)(xout + p)); __builtin_nontemporal_store(x1, (f32x4*)(xout + p + 4));
;                 *(u32x4*)(xb + p) = EPI_PACK8(x0, x1);
;                 q += EPI_SQ8(x0, x1); }
;             q += __shfl_xor(q, 16); q += __shfl_xor(q, 32);
;             if (fq == 0) atomicAdd(ssout + row, q);
; #pragma unroll
;             for (int bj = 0; bj < 2; ++bj) { xc[bj][0] = xn[bj][0]; xc[bj][1] = xn[bj][1]; } }
;     }
.LBB0_1329:
	s_or_b64 exec, exec, s[0:1]
	v_add_u32_e32 v64, 0xb0, v164
	v_ashrrev_i32_e32 v65, 31, v64
	s_waitcnt lgkmcnt(0)
	v_lshlrev_b64 v[32:33], 12, v[64:65]
	v_lshl_add_u64 v[32:33], s[48:49], 0, v[32:33]
	v_lshl_add_u64 v[68:69], v[162:163], 2, v[32:33]
	v_lshl_add_u64 v[66:67], v[160:161], 2, v[32:33]
	global_load_dwordx4 v[40:43], v[68:69], off offset:16
	global_load_dwordx4 v[44:47], v[68:69], off
	global_load_dwordx4 v[32:35], v[66:67], off offset:16
	global_load_dwordx4 v[36:39], v[66:67], off
	s_waitcnt vmcnt(12)
	v_pk_add_f32 v[30:31], v[30:31], v[62:63]
	v_pk_add_f32 v[28:29], v[28:29], v[60:61]
	v_pk_add_f32 v[26:27], v[26:27], v[58:59]
	v_pk_add_f32 v[24:25], v[24:25], v[56:57]
	global_store_dwordx4 v[84:85], v[28:31], off nt
	global_store_dwordx4 v[84:85], v[24:27], off offset:16 nt
	v_cvt_pk_bf16_f32 v56, v28, v29
	v_cvt_pk_bf16_f32 v58, v24, v25
	s_waitcnt vmcnt(12)
	v_pk_add_f32 v[22:23], v[22:23], v[54:55]
	v_mul_f32_e32 v29, v29, v29
	v_fmac_f32_e32 v29, v28, v28
	v_mul_f32_e32 v28, v31, v31
	v_fmac_f32_e32 v28, v30, v30
	v_mul_f32_e32 v25, v25, v25
	v_add_f32_e32 v28, v29, v28
	v_fmac_f32_e32 v25, v24, v24
	v_add_f32_e32 v24, v28, v25
	v_mul_f32_e32 v25, v27, v27
	v_fmac_f32_e32 v25, v26, v26
	v_pk_add_f32 v[20:21], v[20:21], v[52:53]
	v_cvt_pk_bf16_f32 v57, v30, v31
	v_add_f32_e32 v30, v25, v24
	v_pk_add_f32 v[24:25], v[16:17], v[48:49]
	v_mul_f32_e32 v16, v21, v21
	v_mul_f32_e32 v17, v23, v23
	v_fmac_f32_e32 v16, v20, v20
	v_fmac_f32_e32 v17, v22, v22
	v_add_f32_e32 v16, v16, v17
	v_mul_f32_e32 v17, v25, v25
	v_cvt_pk_bf16_f32 v59, v26, v27
	v_pk_add_f32 v[26:27], v[18:19], v[50:51]
	v_fmac_f32_e32 v17, v24, v24
	v_add_f32_e32 v16, v16, v17
	v_mul_f32_e32 v17, v27, v27
	v_fmac_f32_e32 v17, v26, v26
	v_add_f32_e32 v16, v17, v16
	v_add_f32_e32 v16, v30, v16
	v_mov_b32_e32 v17, v16
	s_nop 1
	v_permlane16_swap_b32_e32 v17, v16
	v_lshlrev_b64 v[70:71], 10, v[80:81]
	v_lshl_add_u64 v[72:73], v[70:71], 0, v[162:163]
	v_lshl_add_u64 v[60:61], v[72:73], 1, s[24:25]
	v_lshl_add_u64 v[28:29], v[70:71], 0, v[160:161]
	s_waitcnt lgkmcnt(0)
	v_add_f32_e32 v16, v16, v17
	v_mov_b32_e32 v17, v16
	s_nop 1
	v_permlane32_swap_b32_e32 v17, v16
	global_store_dwordx4 v[60:61], v[56:59], off
	global_store_dwordx4 v[82:83], v[20:23], off nt
	global_store_dwordx4 v[82:83], v[24:27], off offset:16 nt
	v_cvt_pk_bf16_f32 v19, v22, v23
	v_cvt_pk_bf16_f32 v18, v20, v21
	s_nop 0
	v_lshl_add_u64 v[22:23], v[28:29], 1, s[24:25]
	v_cvt_pk_bf16_f32 v20, v24, v25
	v_cvt_pk_bf16_f32 v21, v26, v27
	global_store_dwordx4 v[22:23], v[18:21], off
	s_and_saveexec_b64 s[0:1], vcc
	s_cbranch_execz .LBB0_1331
	v_lshl_add_u64 v[18:19], v[80:81], 2, s[10:11]
	s_waitcnt lgkmcnt(0)
	v_add_f32_e32 v16, v16, v17
	global_atomic_add_f32 v[18:19], v16, off
.LBB0_1331:
	s_or_b64 exec, exec, s[0:1]
	s_waitcnt vmcnt(8)
	v_pk_add_f32 v[14:15], v[14:15], v[46:47]
	v_pk_add_f32 v[12:13], v[12:13], v[44:45]
	v_pk_add_f32 v[10:11], v[10:11], v[42:43]
	v_pk_add_f32 v[8:9], v[8:9], v[40:41]
	global_store_dwordx4 v[68:69], v[12:15], off nt
	global_store_dwordx4 v[68:69], v[8:11], off offset:16 nt
	v_cvt_pk_bf16_f32 v16, v12, v13
	v_cvt_pk_bf16_f32 v18, v8, v9
	s_waitcnt vmcnt(8)
	v_pk_add_f32 v[6:7], v[6:7], v[38:39]
	v_mul_f32_e32 v13, v13, v13
	v_fmac_f32_e32 v13, v12, v12
	v_mul_f32_e32 v12, v15, v15
	v_fmac_f32_e32 v12, v14, v14
	v_mul_f32_e32 v9, v9, v9
	v_add_f32_e32 v12, v13, v12
	v_fmac_f32_e32 v9, v8, v8
	v_add_f32_e32 v8, v12, v9
	v_mul_f32_e32 v9, v11, v11
	v_fmac_f32_e32 v9, v10, v10
	v_pk_add_f32 v[4:5], v[4:5], v[36:37]
	s_waitcnt lgkmcnt(0)
	v_cvt_pk_bf16_f32 v17, v14, v15
	v_add_f32_e32 v14, v9, v8
	v_pk_add_f32 v[8:9], v[0:1], v[32:33]
	v_mul_f32_e32 v0, v5, v5
	v_mul_f32_e32 v1, v7, v7
	v_fmac_f32_e32 v0, v4, v4
	v_fmac_f32_e32 v1, v6, v6
	v_add_f32_e32 v0, v0, v1
	v_mul_f32_e32 v1, v9, v9
	v_cvt_pk_bf16_f32 v19, v10, v11
	v_pk_add_f32 v[10:11], v[2:3], v[34:35]
	v_fmac_f32_e32 v1, v8, v8
	v_add_f32_e32 v0, v0, v1
	v_mul_f32_e32 v1, v11, v11
	v_fmac_f32_e32 v1, v10, v10
	v_add_f32_e32 v0, v1, v0
	v_add_f32_e32 v0, v14, v0
	v_mov_b32_e32 v1, v0
	s_nop 1
	v_permlane16_swap_b32_e32 v1, v0
	v_lshlrev_b64 v[20:21], 10, v[64:65]
	v_lshl_add_u64 v[22:23], v[20:21], 0, v[162:163]
	v_lshl_add_u64 v[22:23], v[22:23], 1, s[24:25]
	v_lshl_add_u64 v[12:13], v[20:21], 0, v[160:161]
	s_waitcnt lgkmcnt(0)
	v_add_f32_e32 v0, v0, v1
	v_mov_b32_e32 v1, v0
	s_nop 1
	v_permlane32_swap_b32_e32 v1, v0
	global_store_dwordx4 v[22:23], v[16:19], off
	global_store_dwordx4 v[66:67], v[4:7], off nt
	global_store_dwordx4 v[66:67], v[8:11], off offset:16 nt
	v_cvt_pk_bf16_f32 v3, v6, v7
	v_cvt_pk_bf16_f32 v2, v4, v5
	s_nop 0
	v_lshl_add_u64 v[6:7], v[12:13], 1, s[24:25]
	v_cvt_pk_bf16_f32 v4, v8, v9
	v_cvt_pk_bf16_f32 v5, v10, v11
	global_store_dwordx4 v[6:7], v[2:5], off
	s_and_saveexec_b64 s[0:1], vcc
	s_cbranch_execz .LBB0_1333
	v_lshl_add_u64 v[2:3], v[64:65], 2, s[10:11]
	s_waitcnt lgkmcnt(0)
	v_add_f32_e32 v0, v0, v1
	global_atomic_add_f32 v[2:3], v0, off

; #define EPI_IT_ROW(it) EPI_ROW((it) >> 2, (it) & 3)
; #define EPI_PACK8(v0, v1) (u32x4){pk2((v0)[0], (v0)[1]), pk2((v0)[2], (v0)[3]), pk2((v1)[0], (v1)[1]), pk2((v1)[2], (v1)[3])}
;     __device__ __forceinline__ void operator()(AccRef acc, const Unit& u, int wr, int wc, int fr, int fq) const {
;         asm volatile("" : "+v"(fr), "+v"(fq));
; #pragma unroll
;         for (int it = 0; it < 8; ++it) { const int ai = it >> 2, m = it & 3, row = EPI_IT_ROW(it); float q = 0.f;
; #pragma unroll
;             for (int bj = 0; bj < 2; ++bj) { const f32x4 x0 = acc[ai][bj][m][0], x1 = acc[ai][bj][m][1];
;                 *(u32x4*)(O + (size_t)row * DM + EPI_COL(bj)) = EPI_PACK8(x0, x1);
;                 q += EPI_SQ8(x0, x1); }
;             q += __shfl_xor(q, 16); q += __shfl_xor(q, 32);
;             if (fq == 0) atomicAdd(ssout + row, q); }
.LBB0_1472:
	v_cvt_pk_bf16_f32 v154, v124, v125
	v_mul_f32_e32 v125, v125, v125
	v_fmac_f32_e32 v125, v124, v124
	v_mul_f32_e32 v124, v127, v127
	v_cvt_pk_bf16_f32 v156, v120, v121
	v_fmac_f32_e32 v124, v126, v126
	v_mul_f32_e32 v121, v121, v121
	v_add_f32_e32 v124, v125, v124
	v_fmac_f32_e32 v121, v120, v120
	v_add_f32_e32 v120, v124, v121
	v_mul_f32_e32 v121, v123, v123
	v_fmac_f32_e32 v121, v122, v122
	v_cvt_pk_bf16_f32 v157, v122, v123
	v_add_f32_e32 v120, v121, v120
	v_mul_f32_e32 v121, v117, v117
	v_mul_f32_e32 v122, v119, v119
	v_fmac_f32_e32 v121, v116, v116
	v_fmac_f32_e32 v122, v118, v118
	v_add_f32_e32 v121, v121, v122
	v_mul_f32_e32 v122, v113, v113
	v_fmac_f32_e32 v122, v112, v112
	v_add_f32_e32 v121, v121, v122
	v_mul_f32_e32 v122, v115, v115
	v_fmac_f32_e32 v122, v114, v114
	v_mov_b32_e32 v140, v151
	v_mov_b32_e32 v141, v153
	s_lshl_b32 s1, s34, 8
	s_lshl_b32 s0, s0, 8
	v_add_f32_e32 v121, v122, v121
	v_and_b32_e32 v122, 64, v148
	s_add_i32 s1, s1, s75
	s_or_b32 s0, s0, s76
	v_add_f32_e32 v121, v120, v121
	v_xor_b32_e32 v120, 16, v148
	v_add_u32_e32 v123, 64, v122
	v_add_u32_e32 v142, s1, v140
	v_lshl_add_u32 v140, v141, 3, s0
	v_cmp_lt_i32_e64 s[0:1], v120, v123
	v_cvt_pk_bf16_f32 v122, v116, v117
	v_xor_b32_e32 v116, 32, v148
	v_ashrrev_i32_e32 v143, 31, v142
	v_cndmask_b32_e64 v120, v148, v120, s[0:1]
	v_lshlrev_b32_e32 v120, 2, v120
	v_mov_b32_e32 v124, v121
	s_nop 1
	v_permlane16_swap_b32_e32 v124, v121
	v_cmp_lt_i32_e64 s[0:1], v116, v123
	v_lshlrev_b64 v[158:159], 11, v[142:143]
	v_cmp_eq_u32_e32 vcc, 0, v141
	v_cndmask_b32_e64 v116, v148, v116, s[0:1]
	s_waitcnt lgkmcnt(0)
	v_add_f32_e32 v117, v121, v124
	v_lshlrev_b32_e32 v116, 2, v116
	v_mov_b32_e32 v121, v117
	s_nop 1
	v_permlane32_swap_b32_e32 v121, v117
	v_lshl_add_u64 v[158:159], s[40:41], 0, v[158:159]
	v_ashrrev_i32_e32 v141, 31, v140
	v_cvt_pk_bf16_f32 v155, v126, v127
	v_lshl_add_u64 v[126:127], v[140:141], 1, v[158:159]
	global_store_dwordx4 v[126:127], v[154:157], off
	v_cvt_pk_bf16_f32 v123, v118, v119
	v_cvt_pk_bf16_f32 v124, v112, v113
	v_cvt_pk_bf16_f32 v125, v114, v115
	global_store_dwordx4 v[126:127], v[122:125], off offset:256
	s_and_saveexec_b64 s[0:1], vcc
	s_cbranch_execz .LBB0_1474
	s_waitcnt lgkmcnt(0)
	v_add_f32_e32 v114, v117, v121
	v_lshl_add_u64 v[112:113], v[142:143], 2, s[8:9]
	global_atomic_add_f32 v[112:113], v114, off
.LBB0_1474:
	s_or_b64 exec, exec, s[0:1]
	v_cvt_pk_bf16_f32 v122, v108, v109
	v_mul_f32_e32 v109, v109, v109
	v_fmac_f32_e32 v109, v108, v108
	v_mul_f32_e32 v108, v111, v111
	v_cvt_pk_bf16_f32 v124, v104, v105
	v_fmac_f32_e32 v108, v110, v110
	v_mul_f32_e32 v105, v105, v105
	v_add_f32_e32 v108, v109, v108
	v_fmac_f32_e32 v105, v104, v104
	v_add_f32_e32 v104, v108, v105
	v_mul_f32_e32 v105, v107, v107
	v_fmac_f32_e32 v105, v106, v106
	v_cvt_pk_bf16_f32 v125, v106, v107
	v_add_f32_e32 v104, v105, v104
	v_mul_f32_e32 v105, v101, v101
	v_mul_f32_e32 v106, v103, v103
	v_fmac_f32_e32 v105, v100, v100
	v_fmac_f32_e32 v106, v102, v102
	v_add_f32_e32 v105, v105, v106
	v_mul_f32_e32 v106, v97, v97
	v_fmac_f32_e32 v106, v96, v96
	v_add_f32_e32 v105, v105, v106
	v_mul_f32_e32 v106, v99, v99
	v_fmac_f32_e32 v106, v98, v98
	v_add_f32_e32 v105, v106, v105
	v_add_f32_e32 v106, v104, v105
	v_mov_b32_e32 v107, v106
	s_nop 1
	v_permlane16_swap_b32_e32 v107, v106
	v_add_u32_e32 v112, 16, v142
	v_ashrrev_i32_e32 v113, 31, v112
	v_lshlrev_b64 v[114:115], 11, v[112:113]
	v_lshl_add_u64 v[104:105], s[40:41], 0, v[114:115]
	v_lshl_add_u64 v[108:109], v[140:141], 1, v[104:105]
	v_cvt_pk_bf16_f32 v104, v100, v101
	s_waitcnt lgkmcnt(0)
	v_add_f32_e32 v100, v106, v107
	v_mov_b32_e32 v101, v100
	s_nop 1
	v_permlane32_swap_b32_e32 v101, v100
	v_cvt_pk_bf16_f32 v123, v110, v111
	global_store_dwordx4 v[108:109], v[122:125], off
	v_cvt_pk_bf16_f32 v105, v102, v103
	v_cvt_pk_bf16_f32 v106, v96, v97
	v_cvt_pk_bf16_f32 v107, v98, v99
	global_store_dwordx4 v[108:109], v[104:107], off offset:256
	s_and_saveexec_b64 s[0:1], vcc
	s_cbranch_execz .LBB0_1476
	s_waitcnt lgkmcnt(0)
	v_add_f32_e32 v98, v100, v101
	v_lshl_add_u64 v[96:97], v[112:113], 2, s[8:9]
	global_atomic_add_f32 v[96:97], v98, off
.LBB0_1476:
	s_or_b64 exec, exec, s[0:1]
	v_cvt_pk_bf16_f32 v98, v92, v93
	v_mul_f32_e32 v93, v93, v93
	v_fmac_f32_e32 v93, v92, v92
	v_mul_f32_e32 v92, v95, v95
	v_cvt_pk_bf16_f32 v100, v88, v89
	v_fmac_f32_e32 v92, v94, v94
	v_mul_f32_e32 v89, v89, v89
	v_add_f32_e32 v92, v93, v92
	v_fmac_f32_e32 v89, v88, v88
	v_add_f32_e32 v88, v92, v89
	v_mul_f32_e32 v89, v91, v91
	v_fmac_f32_e32 v89, v90, v90
	s_waitcnt lgkmcnt(0)
	v_cvt_pk_bf16_f32 v101, v90, v91
	v_add_f32_e32 v88, v89, v88
	v_mul_f32_e32 v89, v85, v85
	v_mul_f32_e32 v90, v87, v87
	v_fmac_f32_e32 v89, v84, v84
	v_fmac_f32_e32 v90, v86, v86
	v_add_f32_e32 v89, v89, v90
	v_mul_f32_e32 v90, v81, v81
	v_fmac_f32_e32 v90, v80, v80
	v_add_f32_e32 v89, v89, v90
	v_mul_f32_e32 v90, v83, v83
	v_fmac_f32_e32 v90, v82, v82
	v_add_f32_e32 v89, v90, v89
	v_add_f32_e32 v90, v88, v89
	v_mov_b32_e32 v91, v90
	s_nop 1
	v_permlane16_swap_b32_e32 v91, v90
	v_add_u32_e32 v96, 32, v142
	v_ashrrev_i32_e32 v97, 31, v96
	v_lshlrev_b64 v[102:103], 11, v[96:97]
	v_lshl_add_u64 v[88:89], s[40:41], 0, v[102:103]
	v_lshl_add_u64 v[92:93], v[140:141], 1, v[88:89]
	v_cvt_pk_bf16_f32 v88, v84, v85
	s_waitcnt lgkmcnt(0)
	v_add_f32_e32 v84, v90, v91
	v_mov_b32_e32 v85, v84
	s_nop 1
	v_permlane32_swap_b32_e32 v85, v84
	v_cvt_pk_bf16_f32 v99, v94, v95
	global_store_dwordx4 v[92:93], v[98:101], off
	v_cvt_pk_bf16_f32 v89, v86, v87
	v_cvt_pk_bf16_f32 v90, v80, v81
	v_cvt_pk_bf16_f32 v91, v82, v83
	global_store_dwordx4 v[92:93], v[88:91], off offset:256
	s_and_saveexec_b64 s[0:1], vcc
	s_cbranch_execz .LBB0_1478
	s_waitcnt lgkmcnt(0)
	v_add_f32_e32 v82, v84, v85
	v_lshl_add_u64 v[80:81], v[96:97], 2, s[8:9]
	global_atomic_add_f32 v[80:81], v82, off
; #define EPI_IT_ROW(it) EPI_ROW((it) >> 2, (it) & 3)
; #define EPI_PACK8(v0, v1) (u32x4){pk2((v0)[0], (v0)[1]), pk2((v0)[2], (v0)[3]), pk2((v1)[0], (v1)[1]), pk2((v1)[2], (v1)[3])}
;     __device__ __forceinline__ void operator()(AccRef acc, const Unit& u, int wr, int wc, int fr, int fq) const {
;         asm volatile("" : "+v"(fr), "+v"(fq));
; #pragma unroll
;         for (int it = 0; it < 8; ++it) { const int ai = it >> 2, m = it & 3, row = EPI_IT_ROW(it); float q = 0.f;
; #pragma unroll
;             for (int bj = 0; bj < 2; ++bj) { const f32x4 x0 = acc[ai][bj][m][0], x1 = acc[ai][bj][m][1];
;                 *(u32x4*)(O + (size_t)row * DM + EPI_COL(bj)) = EPI_PACK8(x0, x1);
;                 q += EPI_SQ8(x0, x1); }
;             q += __shfl_xor(q, 16); q += __shfl_xor(q, 32);
;             if (fq == 0) atomicAdd(ssout + row, q); }
.LBB0_1478:
	s_or_b64 exec, exec, s[0:1]
	v_cvt_pk_bf16_f32 v82, v76, v77
	v_mul_f32_e32 v77, v77, v77
	v_fmac_f32_e32 v77, v76, v76
	v_mul_f32_e32 v76, v79, v79
	v_cvt_pk_bf16_f32 v84, v72, v73
	v_fmac_f32_e32 v76, v78, v78
	v_mul_f32_e32 v73, v73, v73
	v_add_f32_e32 v76, v77, v76
	v_fmac_f32_e32 v73, v72, v72
	v_add_f32_e32 v72, v76, v73
	v_mul_f32_e32 v73, v75, v75
	v_fmac_f32_e32 v73, v74, v74
	s_waitcnt lgkmcnt(0)
	v_cvt_pk_bf16_f32 v85, v74, v75
	v_add_f32_e32 v72, v73, v72
	v_mul_f32_e32 v73, v69, v69
	v_mul_f32_e32 v74, v71, v71
	v_fmac_f32_e32 v73, v68, v68
	v_fmac_f32_e32 v74, v70, v70
	v_add_f32_e32 v73, v73, v74
	v_mul_f32_e32 v74, v65, v65
	v_fmac_f32_e32 v74, v64, v64
	v_add_f32_e32 v73, v73, v74
	v_mul_f32_e32 v74, v67, v67
	v_fmac_f32_e32 v74, v66, v66
	v_add_f32_e32 v73, v74, v73
	v_add_f32_e32 v74, v72, v73
	v_mov_b32_e32 v75, v74
	s_nop 1
	v_permlane16_swap_b32_e32 v75, v74
	v_add_u32_e32 v80, 48, v142
	v_ashrrev_i32_e32 v81, 31, v80
	v_lshlrev_b64 v[86:87], 11, v[80:81]
	v_lshl_add_u64 v[72:73], s[40:41], 0, v[86:87]
	v_lshl_add_u64 v[76:77], v[140:141], 1, v[72:73]
	v_cvt_pk_bf16_f32 v72, v68, v69
	s_waitcnt lgkmcnt(0)
	v_add_f32_e32 v68, v74, v75
	v_mov_b32_e32 v69, v68
	s_nop 1
	v_permlane32_swap_b32_e32 v69, v68
	v_cvt_pk_bf16_f32 v83, v78, v79
	global_store_dwordx4 v[76:77], v[82:85], off
	v_cvt_pk_bf16_f32 v73, v70, v71
	v_cvt_pk_bf16_f32 v74, v64, v65
	v_cvt_pk_bf16_f32 v75, v66, v67
	global_store_dwordx4 v[76:77], v[72:75], off offset:256
	s_and_saveexec_b64 s[0:1], vcc
	s_cbranch_execz .LBB0_1480
	s_waitcnt lgkmcnt(0)
	v_add_f32_e32 v66, v68, v69
	v_lshl_add_u64 v[64:65], v[80:81], 2, s[8:9]
	global_atomic_add_f32 v[64:65], v66, off
.LBB0_1480:
	s_or_b64 exec, exec, s[0:1]
	v_cvt_pk_bf16_f32 v66, v60, v61
	v_mul_f32_e32 v61, v61, v61
	v_fmac_f32_e32 v61, v60, v60
	v_mul_f32_e32 v60, v63, v63
	v_cvt_pk_bf16_f32 v68, v56, v57
	v_fmac_f32_e32 v60, v62, v62
	v_mul_f32_e32 v57, v57, v57
	v_add_f32_e32 v60, v61, v60
	v_fmac_f32_e32 v57, v56, v56
	v_add_f32_e32 v56, v60, v57
	v_mul_f32_e32 v57, v59, v59
	v_fmac_f32_e32 v57, v58, v58
	s_waitcnt lgkmcnt(0)
	v_cvt_pk_bf16_f32 v69, v58, v59
	v_add_f32_e32 v56, v57, v56
	v_mul_f32_e32 v57, v53, v53
	v_mul_f32_e32 v58, v55, v55
	v_fmac_f32_e32 v57, v52, v52
	v_fmac_f32_e32 v58, v54, v54
	v_add_f32_e32 v57, v57, v58
	v_mul_f32_e32 v58, v49, v49
	v_fmac_f32_e32 v58, v48, v48
	v_add_f32_e32 v57, v57, v58
	v_mul_f32_e32 v58, v51, v51
	v_fmac_f32_e32 v58, v50, v50
	v_add_f32_e32 v57, v58, v57
	v_add_f32_e32 v58, v56, v57
	v_mov_b32_e32 v59, v58
	s_nop 1
	v_permlane16_swap_b32_e32 v59, v58
	v_add_u32_e32 v64, 0x80, v142
	v_ashrrev_i32_e32 v65, 31, v64
	v_lshlrev_b64 v[70:71], 11, v[64:65]
	v_lshl_add_u64 v[56:57], s[40:41], 0, v[70:71]
	v_lshl_add_u64 v[60:61], v[140:141], 1, v[56:57]
	v_cvt_pk_bf16_f32 v56, v52, v53
	s_waitcnt lgkmcnt(0)
	v_add_f32_e32 v52, v58, v59
	v_mov_b32_e32 v53, v52
	s_nop 1
	v_permlane32_swap_b32_e32 v53, v52
	v_cvt_pk_bf16_f32 v67, v62, v63
	global_store_dwordx4 v[60:61], v[66:69], off
	v_cvt_pk_bf16_f32 v57, v54, v55
	v_cvt_pk_bf16_f32 v58, v48, v49
	v_cvt_pk_bf16_f32 v59, v50, v51
	global_store_dwordx4 v[60:61], v[56:59], off offset:256
	s_and_saveexec_b64 s[0:1], vcc
	s_cbranch_execz .LBB0_1482
	s_waitcnt lgkmcnt(0)
	v_add_f32_e32 v50, v52, v53
	v_lshl_add_u64 v[48:49], v[64:65], 2, s[8:9]
	global_atomic_add_f32 v[48:49], v50, off
; #define EPI_IT_ROW(it) EPI_ROW((it) >> 2, (it) & 3)
; #define EPI_PACK8(v0, v1) (u32x4){pk2((v0)[0], (v0)[1]), pk2((v0)[2], (v0)[3]), pk2((v1)[0], (v1)[1]), pk2((v1)[2], (v1)[3])}
;     __device__ __forceinline__ void operator()(AccRef acc, const Unit& u, int wr, int wc, int fr, int fq) const {
;     ...
;         for (int it = 0; it < 8; ++it) { const int ai = it >> 2, m = it & 3, row = EPI_IT_ROW(it); float q = 0.f;
; #pragma unroll
;             for (int bj = 0; bj < 2; ++bj) { const f32x4 x0 = acc[ai][bj][m][0], x1 = acc[ai][bj][m][1];
;                 *(u32x4*)(O + (size_t)row * DM + EPI_COL(bj)) = EPI_PACK8(x0, x1);
;                 q += EPI_SQ8(x0, x1); }
;             q += __shfl_xor(q, 16); q += __shfl_xor(q, 32);
;             if (fq == 0) atomicAdd(ssout + row, q); }
.LBB0_1482:
	s_or_b64 exec, exec, s[0:1]
	v_cvt_pk_bf16_f32 v50, v44, v45
	v_mul_f32_e32 v45, v45, v45
	v_fmac_f32_e32 v45, v44, v44
	v_mul_f32_e32 v44, v47, v47
	v_cvt_pk_bf16_f32 v52, v40, v41
	v_fmac_f32_e32 v44, v46, v46
	v_mul_f32_e32 v41, v41, v41
	v_add_f32_e32 v44, v45, v44
	v_fmac_f32_e32 v41, v40, v40
	v_add_f32_e32 v40, v44, v41
	v_mul_f32_e32 v41, v43, v43
	v_fmac_f32_e32 v41, v42, v42
	s_waitcnt lgkmcnt(0)
	v_cvt_pk_bf16_f32 v53, v42, v43
	v_add_f32_e32 v40, v41, v40
	v_mul_f32_e32 v41, v37, v37
	v_mul_f32_e32 v42, v39, v39
	v_fmac_f32_e32 v41, v36, v36
	v_fmac_f32_e32 v42, v38, v38
	v_add_f32_e32 v41, v41, v42
	v_mul_f32_e32 v42, v33, v33
	v_fmac_f32_e32 v42, v32, v32
	v_add_f32_e32 v41, v41, v42
	v_mul_f32_e32 v42, v35, v35
	v_fmac_f32_e32 v42, v34, v34
	v_add_f32_e32 v41, v42, v41
	v_add_f32_e32 v42, v40, v41
	v_mov_b32_e32 v43, v42
	s_nop 1
	v_permlane16_swap_b32_e32 v43, v42
	v_add_u32_e32 v48, 0x90, v142
	v_ashrrev_i32_e32 v49, 31, v48
	v_lshlrev_b64 v[54:55], 11, v[48:49]
	v_lshl_add_u64 v[40:41], s[40:41], 0, v[54:55]
	v_lshl_add_u64 v[44:45], v[140:141], 1, v[40:41]
	v_cvt_pk_bf16_f32 v40, v36, v37
	s_waitcnt lgkmcnt(0)
	v_add_f32_e32 v36, v42, v43
	v_mov_b32_e32 v37, v36
	s_nop 1
	v_permlane32_swap_b32_e32 v37, v36
	v_cvt_pk_bf16_f32 v51, v46, v47
	global_store_dwordx4 v[44:45], v[50:53], off
	v_cvt_pk_bf16_f32 v41, v38, v39
	v_cvt_pk_bf16_f32 v42, v32, v33
	v_cvt_pk_bf16_f32 v43, v34, v35
	global_store_dwordx4 v[44:45], v[40:43], off offset:256
	s_and_saveexec_b64 s[0:1], vcc
	s_cbranch_execz .LBB0_1484
	s_waitcnt lgkmcnt(0)
	v_add_f32_e32 v34, v36, v37
	v_lshl_add_u64 v[32:33], v[48:49], 2, s[8:9]
	global_atomic_add_f32 v[32:33], v34, off
.LBB0_1484:
	s_or_b64 exec, exec, s[0:1]
	v_cvt_pk_bf16_f32 v34, v28, v29
	v_mul_f32_e32 v29, v29, v29
	v_fmac_f32_e32 v29, v28, v28
	v_mul_f32_e32 v28, v31, v31
	v_cvt_pk_bf16_f32 v36, v24, v25
	v_fmac_f32_e32 v28, v30, v30
	v_mul_f32_e32 v25, v25, v25
	v_add_f32_e32 v28, v29, v28
	v_fmac_f32_e32 v25, v24, v24
	v_add_f32_e32 v24, v28, v25
	v_mul_f32_e32 v25, v27, v27
	v_fmac_f32_e32 v25, v26, v26
	s_waitcnt lgkmcnt(0)
	v_cvt_pk_bf16_f32 v37, v26, v27
	v_add_f32_e32 v24, v25, v24
	v_mul_f32_e32 v25, v21, v21
	v_mul_f32_e32 v26, v23, v23
	v_fmac_f32_e32 v25, v20, v20
	v_fmac_f32_e32 v26, v22, v22
	v_add_f32_e32 v25, v25, v26
	v_mul_f32_e32 v26, v17, v17
	v_fmac_f32_e32 v26, v16, v16
	v_add_f32_e32 v25, v25, v26
	v_mul_f32_e32 v26, v19, v19
	v_fmac_f32_e32 v26, v18, v18
	v_add_f32_e32 v25, v26, v25
	v_add_f32_e32 v26, v24, v25
	v_mov_b32_e32 v27, v26
	s_nop 1
	v_permlane16_swap_b32_e32 v27, v26
	v_add_u32_e32 v32, 0xa0, v142
	v_ashrrev_i32_e32 v33, 31, v32
	v_lshlrev_b64 v[38:39], 11, v[32:33]
	v_lshl_add_u64 v[24:25], s[40:41], 0, v[38:39]
	v_lshl_add_u64 v[28:29], v[140:141], 1, v[24:25]
	v_cvt_pk_bf16_f32 v24, v20, v21
	s_waitcnt lgkmcnt(0)
	v_add_f32_e32 v20, v26, v27
	v_mov_b32_e32 v21, v20
	s_nop 1
	v_permlane32_swap_b32_e32 v21, v20
	v_cvt_pk_bf16_f32 v35, v30, v31
	global_store_dwordx4 v[28:29], v[34:37], off
	v_cvt_pk_bf16_f32 v25, v22, v23
	v_cvt_pk_bf16_f32 v26, v16, v17
	v_cvt_pk_bf16_f32 v27, v18, v19
	global_store_dwordx4 v[28:29], v[24:27], off offset:256
	s_and_saveexec_b64 s[0:1], vcc
	s_cbranch_execz .LBB0_1486
	s_waitcnt lgkmcnt(0)
	v_add_f32_e32 v18, v20, v21
	v_lshl_add_u64 v[16:17], v[32:33], 2, s[8:9]
	global_atomic_add_f32 v[16:17], v18, off
.LBB0_1486:
	s_or_b64 exec, exec, s[0:1]
	v_cvt_pk_bf16_f32 v18, v12, v13
	v_mul_f32_e32 v13, v13, v13
	v_fmac_f32_e32 v13, v12, v12
	v_mul_f32_e32 v12, v15, v15
	v_cvt_pk_bf16_f32 v20, v8, v9
	v_fmac_f32_e32 v12, v14, v14
	v_mul_f32_e32 v9, v9, v9
	v_add_f32_e32 v12, v13, v12
	v_fmac_f32_e32 v9, v8, v8
	v_add_f32_e32 v8, v12, v9
	v_mul_f32_e32 v9, v11, v11
	v_fmac_f32_e32 v9, v10, v10
	s_waitcnt lgkmcnt(0)
	v_cvt_pk_bf16_f32 v21, v10, v11
	v_add_f32_e32 v8, v9, v8
	v_mul_f32_e32 v9, v5, v5
	v_mul_f32_e32 v10, v7, v7
	v_fmac_f32_e32 v9, v4, v4
	v_fmac_f32_e32 v10, v6, v6
	v_add_f32_e32 v9, v9, v10
	v_mul_f32_e32 v10, v1, v1
	v_fmac_f32_e32 v10, v0, v0
	v_add_f32_e32 v9, v9, v10
	v_mul_f32_e32 v10, v3, v3
	v_fmac_f32_e32 v10, v2, v2
	v_add_f32_e32 v9, v10, v9
	v_add_f32_e32 v10, v8, v9
	v_mov_b32_e32 v11, v10
	s_nop 1
	v_permlane16_swap_b32_e32 v11, v10
	v_add_u32_e32 v16, 0xb0, v142
	v_ashrrev_i32_e32 v17, 31, v16
	v_lshlrev_b64 v[22:23], 11, v[16:17]
	v_lshl_add_u64 v[8:9], s[40:41], 0, v[22:23]
	v_lshl_add_u64 v[12:13], v[140:141], 1, v[8:9]
	v_cvt_pk_bf16_f32 v8, v4, v5
	s_waitcnt lgkmcnt(0)
	v_add_f32_e32 v4, v10, v11
	v_mov_b32_e32 v5, v4
	s_nop 1
	v_permlane32_swap_b32_e32 v5, v4
	v_cvt_pk_bf16_f32 v19, v14, v15
	global_store_dwordx4 v[12:13], v[18:21], off
	v_cvt_pk_bf16_f32 v9, v6, v7
	v_cvt_pk_bf16_f32 v10, v0, v1
	v_cvt_pk_bf16_f32 v11, v2, v3
	global_store_dwordx4 v[12:13], v[8:11], off offset:256
	s_and_saveexec_b64 s[0:1], vcc
	s_cbranch_execz .LBB0_1488
	s_waitcnt lgkmcnt(0)
	v_add_f32_e32 v2, v4, v5
	v_lshl_add_u64 v[0:1], v[16:17], 2, s[8:9]
	global_atomic_add_f32 v[0:1], v2, off

; #define EPI_IT_ROW(it) EPI_ROW((it) >> 2, (it) & 3)
; #define EPI_PACK8(v0, v1) (u32x4){pk2((v0)[0], (v0)[1]), pk2((v0)[2], (v0)[3]), pk2((v1)[0], (v1)[1]), pk2((v1)[2], (v1)[3])}
;     __device__ __forceinline__ void operator()(AccRef acc, const Unit& u, int wr, int wc, int fr, int fq) const {
;     ...
;         f32x4 xc[2][2], xn[2][2];
; #pragma unroll
;         for (int bj = 0; bj < 2; ++bj) { const size_t p = (size_t)EPI_IT_ROW(0) * DM + EPI_COL(bj); xc[bj][0] = *(const f32x4*)(xin + p); xc[bj][1] = *(const f32x4*)(xin + p + 4); }
; #pragma unroll
;         for (int it = 0; it < 8; ++it) { const int ai = it >> 2, m = it & 3, row = EPI_IT_ROW(it);
;             if (it + 1 < 8) {
; #pragma unroll
;                 for (int bj = 0; bj < 2; ++bj) { const size_t p = (size_t)EPI_IT_ROW(it + 1) * DM + EPI_COL(bj); xn[bj][0] = *(const f32x4*)(xin + p); xn[bj][1] = *(const f32x4*)(xin + p + 4); } }
;             float q = 0.f;
; #pragma unroll
;             for (int bj = 0; bj < 2; ++bj) { const size_t p = (size_t)row * DM + EPI_COL(bj);
;                 const f32x4 x0 = xc[bj][0] + acc[ai][bj][m][0], x1 = xc[bj][1] + acc[ai][bj][m][1];
;                 __builtin_nontemporal_store(x0, (f32x4*)(xout + p)); __builtin_nontemporal_store(x1, (f32x4*)(xout + p + 4));
;                 *(u32x4*)(xb + p) = EPI_PACK8(x0, x1);
;                 q += EPI_SQ8(x0, x1); }
;             q += __shfl_xor(q, 16); q += __shfl_xor(q, 32);
;             if (fq == 0) atomicAdd(ssout + row, q);
; #pragma unroll
;             for (int bj = 0; bj < 2; ++bj) { xc[bj][0] = xn[bj][0]; xc[bj][1] = xn[bj][1]; } }
.LBB0_1652:
	s_lshl_b32 s0, s60, 8
	v_mov_b32_e32 v128, v180
	v_mov_b32_e32 v186, v177
	s_add_i32 s0, s0, s38
	v_and_b32_e32 v202, 64, v185
	v_add_u32_e32 v164, s0, v128
	s_lshl_b32 s0, s59, 8
	s_or_b32 s0, s0, s39
	v_ashrrev_i32_e32 v165, 31, v164
	v_lshl_add_u32 v162, v186, 3, s0
	v_lshlrev_b64 v[128:129], 12, v[164:165]
	v_ashrrev_i32_e32 v163, 31, v162
	v_add_u32_e32 v160, 0x80, v162
	v_lshl_add_u64 v[128:129], s[48:49], 0, v[128:129]
	v_lshlrev_b64 v[130:131], 2, v[162:163]
	v_ashrrev_i32_e32 v161, 31, v160
	v_lshl_add_u64 v[178:179], v[128:129], 0, v[130:131]
	v_lshlrev_b64 v[132:133], 2, v[160:161]
	global_load_dwordx4 v[170:173], v[178:179], off offset:16
	global_load_dwordx4 v[188:191], v[178:179], off
	v_lshl_add_u64 v[200:201], v[128:129], 0, v[132:133]
	global_load_dwordx4 v[192:195], v[200:201], off
	global_load_dwordx4 v[196:199], v[200:201], off offset:16
	v_add_u32_e32 v166, 16, v164
	v_ashrrev_i32_e32 v167, 31, v166
	v_lshlrev_b64 v[128:129], 12, v[166:167]
	v_lshl_add_u64 v[128:129], s[48:49], 0, v[128:129]
	v_lshl_add_u64 v[174:175], v[128:129], 0, v[130:131]
	v_lshl_add_u64 v[168:169], v[128:129], 0, v[132:133]
	global_load_dwordx4 v[136:139], v[174:175], off offset:16
	global_load_dwordx4 v[140:143], v[174:175], off
	global_load_dwordx4 v[128:131], v[168:169], off offset:16
	global_load_dwordx4 v[132:135], v[168:169], off
	v_xor_b32_e32 v187, 16, v185
	v_add_u32_e32 v202, 64, v202
	v_cmp_lt_i32_e64 s[0:1], v187, v202
	v_cmp_eq_u32_e32 vcc, 0, v186
	v_xor_b32_e32 v203, 32, v185
	v_cndmask_b32_e64 v186, v185, v187, s[0:1]
	v_lshlrev_b32_e32 v186, 2, v186
	v_cmp_lt_i32_e64 s[0:1], v203, v202
	s_waitcnt vmcnt(0)
	v_pk_add_f32 v[122:123], v[122:123], v[172:173]
	v_pk_add_f32 v[126:127], v[126:127], v[190:191]
	v_pk_add_f32 v[124:125], v[124:125], v[188:189]
	v_pk_add_f32 v[118:119], v[118:119], v[194:195]
	v_pk_add_f32 v[116:117], v[116:117], v[192:193]
	v_pk_add_f32 v[120:121], v[120:121], v[170:171]
	v_pk_add_f32 v[170:171], v[112:113], v[196:197]
	global_store_dwordx4 v[178:179], v[124:127], off nt
	global_store_dwordx4 v[178:179], v[120:123], off offset:16 nt
	v_cvt_pk_bf16_f32 v112, v124, v125
	v_cvt_pk_bf16_f32 v113, v126, v127
	v_mul_f32_e32 v178, v117, v117
	v_mul_f32_e32 v125, v125, v125
	v_mul_f32_e32 v127, v127, v127
	v_mul_f32_e32 v179, v119, v119
	v_pk_add_f32 v[172:173], v[114:115], v[198:199]
	v_cvt_pk_bf16_f32 v114, v120, v121
	v_cvt_pk_bf16_f32 v115, v122, v123
	v_mul_f32_e32 v121, v121, v121
	v_mul_f32_e32 v123, v123, v123
	v_mul_f32_e32 v189, v171, v171
	v_fmac_f32_e32 v125, v124, v124
	v_fmac_f32_e32 v127, v126, v126
	v_fmac_f32_e32 v178, v116, v116
	v_fmac_f32_e32 v179, v118, v118
	v_mul_f32_e32 v190, v173, v173
	v_fmac_f32_e32 v121, v120, v120
	v_fmac_f32_e32 v123, v122, v122
	v_fmac_f32_e32 v189, v170, v170
	v_add_f32_e32 v120, v125, v127
	v_add_f32_e32 v122, v178, v179
	v_fmac_f32_e32 v190, v172, v172
	v_add_f32_e32 v120, v120, v121
	v_add_f32_e32 v121, v122, v189
	v_add_f32_e32 v120, v123, v120
	v_add_f32_e32 v121, v190, v121
	v_add_f32_e32 v120, v120, v121
	v_mov_b32_e32 v121, v120
	s_nop 1
	v_permlane16_swap_b32_e32 v121, v120
	v_cndmask_b32_e64 v187, v185, v203, s[0:1]
	v_lshlrev_b64 v[202:203], 10, v[164:165]
	v_lshl_add_u64 v[204:205], v[202:203], 0, v[162:163]
	v_lshl_add_u64 v[204:205], v[204:205], 1, s[30:31]
	global_store_dwordx4 v[204:205], v[112:115], off
	global_store_dwordx4 v[200:201], v[116:119], off nt
	global_store_dwordx4 v[200:201], v[170:173], off offset:16 nt
	s_waitcnt lgkmcnt(0)
	v_add_f32_e32 v112, v120, v121
	v_lshlrev_b32_e32 v187, 2, v187
	v_mov_b32_e32 v113, v112
	s_nop 1
	v_permlane32_swap_b32_e32 v113, v112
	v_lshl_add_u64 v[202:203], v[202:203], 0, v[160:161]
	v_lshl_add_u64 v[114:115], v[202:203], 1, s[30:31]
	v_cvt_pk_bf16_f32 v188, v116, v117
	v_cvt_pk_bf16_f32 v189, v118, v119
	v_cvt_pk_bf16_f32 v190, v170, v171
	v_cvt_pk_bf16_f32 v191, v172, v173
	global_store_dwordx4 v[114:115], v[188:191], off
	s_and_saveexec_b64 s[0:1], vcc
	s_cbranch_execz .LBB0_1654
	v_lshl_add_u64 v[114:115], v[164:165], 2, s[12:13]
	s_waitcnt lgkmcnt(0)
	v_add_f32_e32 v112, v112, v113
	global_atomic_add_f32 v[114:115], v112, off

; #define EPI_PACK8(v0, v1) (u32x4){pk2((v0)[0], (v0)[1]), pk2((v0)[2], (v0)[3]), pk2((v1)[0], (v1)[1]), pk2((v1)[2], (v1)[3])}
;     __device__ __forceinline__ void operator()(AccRef acc, const Unit& u, int wr, int wc, int fr, int fq) const {
;     ...
;             const f32x4 x0 = xc0 + g0 * (p0 * rp) * pg[bj][0], x1 = xc1 + g1 * (p1 * rp) * pg[bj][1];
;             if (xo) { __builtin_nontemporal_store(x0, (f32x4*)(xo + p)); __builtin_nontemporal_store(x1, (f32x4*)(xo + p + 4)); }
;             *(u32x4*)(xb + p) = EPI_PACK8(x0, x1);
;             q += EPI_SQ8(x0, x1);
;             if (bj == 1) { q += __shfl_xor(q, 16); q += __shfl_xor(q, 32); if (fq == 0) atomicAdd(ssout + row, q); q = 0.f; sc = sn_; qc = qn; }
.LBB0_1753:
	v_mul_f32_e32 v144, v165, v165
	v_mul_f32_e32 v145, v167, v167
	v_fmac_f32_e32 v144, v164, v164
	v_fmac_f32_e32 v145, v166, v166
	v_add_f32_e32 v144, v144, v145
	v_mul_f32_e32 v145, v161, v161
	v_fmac_f32_e32 v145, v160, v160
	v_mul_f32_e32 v146, v129, v129
	v_mul_f32_e32 v147, v131, v131
	v_add_f32_e32 v144, v145, v144
	v_mul_f32_e32 v145, v163, v163
	v_fmac_f32_e32 v146, v128, v128
	v_fmac_f32_e32 v147, v130, v130
	v_fmac_f32_e32 v145, v162, v162
	v_add_f32_e32 v146, v146, v147
	v_mul_f32_e32 v147, v133, v133
	v_add_f32_e32 v144, v145, v144
	v_mul_f32_e32 v145, v135, v135
	v_fmac_f32_e32 v147, v132, v132
	v_fmac_f32_e32 v145, v134, v134
	v_add_f32_e32 v146, v147, v146
	v_add_f32_e32 v145, v145, v146
	v_add_f32_e32 v146, v144, v145
	v_and_b32_e32 v145, 64, v212
	v_xor_b32_e32 v144, 16, v212
	v_add_u32_e32 v147, 64, v145
	v_cmp_lt_i32_e32 vcc, v144, v147
	v_cmp_eq_u32_e64 s[8:9], 0, v213
	v_cvt_pk_bf16_f32 v145, v130, v131
	v_lshl_add_u64 v[130:131], v[194:195], 1, s[24:25]
	v_cndmask_b32_e32 v144, v212, v144, vcc
	v_lshlrev_b32_e32 v166, 2, v144
	v_mov_b32_e32 v148, v146
	s_nop 1
	v_permlane16_swap_b32_e32 v148, v146
	v_cvt_pk_bf16_f32 v144, v128, v129
	v_xor_b32_e32 v129, 32, v212
	v_cmp_lt_i32_e32 vcc, v129, v147
	v_cvt_pk_bf16_f32 v147, v134, v135
	s_waitcnt lgkmcnt(0)
	v_add_f32_e32 v128, v146, v148
	v_cvt_pk_bf16_f32 v146, v132, v133
	s_nop 0
	v_cndmask_b32_e32 v129, v212, v129, vcc
	v_lshlrev_b32_e32 v167, 2, v129
	v_mov_b32_e32 v129, v128
	s_nop 1
	v_permlane32_swap_b32_e32 v129, v128
	s_and_saveexec_b64 s[42:43], s[8:9]
	v_readlane_b32 s72, v254, 6
	v_readlane_b32 s73, v254, 7
	v_readlane_b32 s74, v254, 8
	v_readlane_b32 s75, v254, 9
	s_cbranch_execz .LBB0_1755
	v_lshl_add_u64 v[130:131], v[190:191], 2, s[14:15]
	s_waitcnt lgkmcnt(0)
	v_add_f32_e32 v128, v128, v129
	global_atomic_add_f32 v[130:131], v128, off

; #define EPI_PACK8(v0, v1) (u32x4){pk2((v0)[0], (v0)[1]), pk2((v0)[2], (v0)[3]), pk2((v1)[0], (v1)[1]), pk2((v1)[2], (v1)[3])}
;     __device__ __forceinline__ void operator()(AccRef acc, const Unit& u, int wr, int wc, int fr, int fq) const {
;     ...
;             const f32x4 x0 = xc0 + g0 * (p0 * rp) * pg[bj][0], x1 = xc1 + g1 * (p1 * rp) * pg[bj][1];
;             if (xo) { __builtin_nontemporal_store(x0, (f32x4*)(xo + p)); __builtin_nontemporal_store(x1, (f32x4*)(xo + p + 4)); }
;             *(u32x4*)(xb + p) = EPI_PACK8(x0, x1);
;             q += EPI_SQ8(x0, x1);
;             if (bj == 1) { q += __shfl_xor(q, 16); q += __shfl_xor(q, 32); if (fq == 0) atomicAdd(ssout + row, q); q = 0.f; sc = sn_; qc = qn; }
.LBB0_1759:
	v_mul_f32_e32 v128, v141, v141
	v_mul_f32_e32 v129, v143, v143
	v_fmac_f32_e32 v128, v140, v140
	v_fmac_f32_e32 v129, v142, v142
	v_add_f32_e32 v128, v128, v129
	v_mul_f32_e32 v129, v145, v145
	v_fmac_f32_e32 v129, v144, v144
	v_mul_f32_e32 v130, v113, v113
	v_mul_f32_e32 v131, v115, v115
	v_add_f32_e32 v128, v129, v128
	v_mul_f32_e32 v129, v147, v147
	v_fmac_f32_e32 v130, v112, v112
	v_fmac_f32_e32 v131, v114, v114
	v_fmac_f32_e32 v129, v146, v146
	v_add_f32_e32 v130, v130, v131
	v_mul_f32_e32 v131, v117, v117
	v_add_f32_e32 v128, v129, v128
	v_mul_f32_e32 v129, v119, v119
	v_fmac_f32_e32 v131, v116, v116
	v_fmac_f32_e32 v129, v118, v118
	v_add_f32_e32 v130, v131, v130
	v_add_f32_e32 v129, v129, v130
	v_add_f32_e32 v130, v128, v129
	v_mov_b32_e32 v131, v130
	s_nop 1
	v_permlane16_swap_b32_e32 v131, v130
	v_cvt_pk_bf16_f32 v128, v112, v113
	v_cvt_pk_bf16_f32 v129, v114, v115
	v_lshl_add_u64 v[114:115], v[156:157], 1, s[24:25]
	s_waitcnt lgkmcnt(0)
	v_add_f32_e32 v112, v130, v131
	v_mov_b32_e32 v113, v112
	s_nop 1
	v_permlane32_swap_b32_e32 v113, v112
	v_cvt_pk_bf16_f32 v130, v116, v117
	v_cvt_pk_bf16_f32 v131, v118, v119
	s_nop 0
	s_and_saveexec_b64 s[42:43], s[8:9]
	s_cbranch_execz .LBB0_1761
	v_lshl_add_u64 v[114:115], v[192:193], 2, s[14:15]
	s_waitcnt lgkmcnt(0)
	v_add_f32_e32 v112, v112, v113
	global_atomic_add_f32 v[114:115], v112, off

; #define EPI_PACK8(v0, v1) (u32x4){pk2((v0)[0], (v0)[1]), pk2((v0)[2], (v0)[3]), pk2((v1)[0], (v1)[1]), pk2((v1)[2], (v1)[3])}
;     __device__ __forceinline__ void operator()(AccRef acc, const Unit& u, int wr, int wc, int fr, int fq) const {
;     ...
;             const f32x4 x0 = xc0 + g0 * (p0 * rp) * pg[bj][0], x1 = xc1 + g1 * (p1 * rp) * pg[bj][1];
;             if (xo) { __builtin_nontemporal_store(x0, (f32x4*)(xo + p)); __builtin_nontemporal_store(x1, (f32x4*)(xo + p + 4)); }
;             *(u32x4*)(xb + p) = EPI_PACK8(x0, x1);
;             q += EPI_SQ8(x0, x1);
;             if (bj == 1) { q += __shfl_xor(q, 16); q += __shfl_xor(q, 32); if (fq == 0) atomicAdd(ssout + row, q); q = 0.f; sc = sn_; qc = qn; }
.LBB0_1765:
	v_mul_f32_e32 v112, v125, v125
	v_mul_f32_e32 v113, v127, v127
	v_fmac_f32_e32 v112, v124, v124
	v_fmac_f32_e32 v113, v126, v126
	v_add_f32_e32 v112, v112, v113
	v_mul_f32_e32 v113, v129, v129
	v_fmac_f32_e32 v113, v128, v128
	v_mul_f32_e32 v114, v97, v97
	v_mul_f32_e32 v115, v99, v99
	v_add_f32_e32 v112, v113, v112
	v_mul_f32_e32 v113, v131, v131
	v_fmac_f32_e32 v114, v96, v96
	v_fmac_f32_e32 v115, v98, v98
	v_fmac_f32_e32 v113, v130, v130
	v_add_f32_e32 v114, v114, v115
	v_mul_f32_e32 v115, v101, v101
	v_add_f32_e32 v112, v113, v112
	v_mul_f32_e32 v113, v103, v103
	v_fmac_f32_e32 v115, v100, v100
	v_fmac_f32_e32 v113, v102, v102
	v_add_f32_e32 v114, v115, v114
	v_add_f32_e32 v113, v113, v114
	v_add_f32_e32 v114, v112, v113
	v_mov_b32_e32 v115, v114
	s_nop 1
	v_permlane16_swap_b32_e32 v115, v114
	v_cvt_pk_bf16_f32 v112, v96, v97
	v_cvt_pk_bf16_f32 v113, v98, v99
	v_lshl_add_u64 v[98:99], v[140:141], 1, s[24:25]
	s_waitcnt lgkmcnt(0)
	v_add_f32_e32 v96, v114, v115
	v_mov_b32_e32 v97, v96
	s_nop 1
	v_permlane32_swap_b32_e32 v97, v96
	v_cvt_pk_bf16_f32 v114, v100, v101
	v_cvt_pk_bf16_f32 v115, v102, v103
	s_nop 0
	s_and_saveexec_b64 s[42:43], s[8:9]
	s_cbranch_execz .LBB0_1767
	v_lshl_add_u64 v[98:99], v[152:153], 2, s[14:15]
	s_waitcnt lgkmcnt(0)
	v_add_f32_e32 v96, v96, v97
	global_atomic_add_f32 v[98:99], v96, off

; #define EPI_PACK8(v0, v1) (u32x4){pk2((v0)[0], (v0)[1]), pk2((v0)[2], (v0)[3]), pk2((v1)[0], (v1)[1]), pk2((v1)[2], (v1)[3])}
;     __device__ __forceinline__ void operator()(AccRef acc, const Unit& u, int wr, int wc, int fr, int fq) const {
;     ...
;             const f32x4 x0 = xc0 + g0 * (p0 * rp) * pg[bj][0], x1 = xc1 + g1 * (p1 * rp) * pg[bj][1];
;             if (xo) { __builtin_nontemporal_store(x0, (f32x4*)(xo + p)); __builtin_nontemporal_store(x1, (f32x4*)(xo + p + 4)); }
;             *(u32x4*)(xb + p) = EPI_PACK8(x0, x1);
;             q += EPI_SQ8(x0, x1);
;             if (bj == 1) { q += __shfl_xor(q, 16); q += __shfl_xor(q, 32); if (fq == 0) atomicAdd(ssout + row, q); q = 0.f; sc = sn_; qc = qn; }
.LBB0_1771:
	v_mul_f32_e32 v96, v109, v109
	v_mul_f32_e32 v97, v111, v111
	v_fmac_f32_e32 v96, v108, v108
	v_fmac_f32_e32 v97, v110, v110
	v_add_f32_e32 v96, v96, v97
	v_mul_f32_e32 v97, v113, v113
	v_fmac_f32_e32 v97, v112, v112
	v_mul_f32_e32 v98, v81, v81
	v_mul_f32_e32 v99, v83, v83
	v_add_f32_e32 v96, v97, v96
	v_mul_f32_e32 v97, v115, v115
	v_fmac_f32_e32 v98, v80, v80
	v_fmac_f32_e32 v99, v82, v82
	v_fmac_f32_e32 v97, v114, v114
	v_add_f32_e32 v98, v98, v99
	v_mul_f32_e32 v99, v85, v85
	v_add_f32_e32 v96, v97, v96
	v_mul_f32_e32 v97, v87, v87
	v_fmac_f32_e32 v99, v84, v84
	v_fmac_f32_e32 v97, v86, v86
	v_add_f32_e32 v98, v99, v98
	v_add_f32_e32 v97, v97, v98
	v_add_f32_e32 v98, v96, v97
	v_mov_b32_e32 v99, v98
	s_nop 1
	v_permlane16_swap_b32_e32 v99, v98
	v_cvt_pk_bf16_f32 v96, v80, v81
	v_cvt_pk_bf16_f32 v97, v82, v83
	v_lshl_add_u64 v[82:83], v[124:125], 1, s[24:25]
	s_waitcnt lgkmcnt(0)
	v_add_f32_e32 v80, v98, v99
	v_mov_b32_e32 v81, v80
	s_nop 1
	v_permlane32_swap_b32_e32 v81, v80
	v_cvt_pk_bf16_f32 v98, v84, v85
	v_cvt_pk_bf16_f32 v99, v86, v87
	s_nop 0
	s_and_saveexec_b64 s[42:43], s[8:9]
	s_cbranch_execz .LBB0_1773
	v_lshl_add_u64 v[82:83], v[136:137], 2, s[14:15]
	s_waitcnt lgkmcnt(0)
	v_add_f32_e32 v80, v80, v81
	global_atomic_add_f32 v[82:83], v80, off

; #define EPI_PACK8(v0, v1) (u32x4){pk2((v0)[0], (v0)[1]), pk2((v0)[2], (v0)[3]), pk2((v1)[0], (v1)[1]), pk2((v1)[2], (v1)[3])}
;     __device__ __forceinline__ void operator()(AccRef acc, const Unit& u, int wr, int wc, int fr, int fq) const {
;     ...
;             const f32x4 x0 = xc0 + g0 * (p0 * rp) * pg[bj][0], x1 = xc1 + g1 * (p1 * rp) * pg[bj][1];
;             if (xo) { __builtin_nontemporal_store(x0, (f32x4*)(xo + p)); __builtin_nontemporal_store(x1, (f32x4*)(xo + p + 4)); }
;             *(u32x4*)(xb + p) = EPI_PACK8(x0, x1);
;             q += EPI_SQ8(x0, x1);
;             if (bj == 1) { q += __shfl_xor(q, 16); q += __shfl_xor(q, 32); if (fq == 0) atomicAdd(ssout + row, q); q = 0.f; sc = sn_; qc = qn; }
.LBB0_1777:
	v_mul_f32_e32 v80, v93, v93
	v_mul_f32_e32 v81, v95, v95
	v_fmac_f32_e32 v80, v92, v92
	v_fmac_f32_e32 v81, v94, v94
	v_add_f32_e32 v80, v80, v81
	v_mul_f32_e32 v81, v97, v97
	v_fmac_f32_e32 v81, v96, v96
	v_mul_f32_e32 v82, v65, v65
	v_mul_f32_e32 v83, v67, v67
	v_add_f32_e32 v80, v81, v80
	v_mul_f32_e32 v81, v99, v99
	v_fmac_f32_e32 v82, v64, v64
	v_fmac_f32_e32 v83, v66, v66
	v_fmac_f32_e32 v81, v98, v98
	v_add_f32_e32 v82, v82, v83
	v_mul_f32_e32 v83, v69, v69
	v_add_f32_e32 v80, v81, v80
	v_mul_f32_e32 v81, v71, v71
	v_fmac_f32_e32 v83, v68, v68
	v_fmac_f32_e32 v81, v70, v70
	v_add_f32_e32 v82, v83, v82
	v_add_f32_e32 v81, v81, v82
	v_add_f32_e32 v82, v80, v81
	v_mov_b32_e32 v83, v82
	s_nop 1
	v_permlane16_swap_b32_e32 v83, v82
	v_cvt_pk_bf16_f32 v80, v64, v65
	v_cvt_pk_bf16_f32 v81, v66, v67
	v_lshl_add_u64 v[66:67], v[108:109], 1, s[24:25]
	s_waitcnt lgkmcnt(0)
	v_add_f32_e32 v64, v82, v83
	v_mov_b32_e32 v65, v64
	s_nop 1
	v_permlane32_swap_b32_e32 v65, v64
	v_cvt_pk_bf16_f32 v82, v68, v69
	v_cvt_pk_bf16_f32 v83, v70, v71
	s_nop 0
	s_and_saveexec_b64 s[42:43], s[8:9]
	s_cbranch_execz .LBB0_1779
	v_lshl_add_u64 v[66:67], v[120:121], 2, s[14:15]
	s_waitcnt lgkmcnt(0)
	v_add_f32_e32 v64, v64, v65
	global_atomic_add_f32 v[66:67], v64, off

; #define EPI_PACK8(v0, v1) (u32x4){pk2((v0)[0], (v0)[1]), pk2((v0)[2], (v0)[3]), pk2((v1)[0], (v1)[1]), pk2((v1)[2], (v1)[3])}
;     __device__ __forceinline__ void operator()(AccRef acc, const Unit& u, int wr, int wc, int fr, int fq) const {
;     ...
;             const f32x4 x0 = xc0 + g0 * (p0 * rp) * pg[bj][0], x1 = xc1 + g1 * (p1 * rp) * pg[bj][1];
;             if (xo) { __builtin_nontemporal_store(x0, (f32x4*)(xo + p)); __builtin_nontemporal_store(x1, (f32x4*)(xo + p + 4)); }
;             *(u32x4*)(xb + p) = EPI_PACK8(x0, x1);
;             q += EPI_SQ8(x0, x1);
;             if (bj == 1) { q += __shfl_xor(q, 16); q += __shfl_xor(q, 32); if (fq == 0) atomicAdd(ssout + row, q); q = 0.f; sc = sn_; qc = qn; }
.LBB0_1783:
	v_mul_f32_e32 v64, v77, v77
	v_mul_f32_e32 v65, v79, v79
	v_fmac_f32_e32 v64, v76, v76
	v_fmac_f32_e32 v65, v78, v78
	v_add_f32_e32 v64, v64, v65
	v_mul_f32_e32 v65, v81, v81
	v_fmac_f32_e32 v65, v80, v80
	v_mul_f32_e32 v66, v33, v33
	v_mul_f32_e32 v67, v35, v35
	v_add_f32_e32 v64, v65, v64
	v_mul_f32_e32 v65, v83, v83
	v_fmac_f32_e32 v66, v32, v32
	v_fmac_f32_e32 v67, v34, v34
	v_fmac_f32_e32 v65, v82, v82
	v_add_f32_e32 v66, v66, v67
	v_mul_f32_e32 v67, v37, v37
	v_add_f32_e32 v64, v65, v64
	v_mul_f32_e32 v65, v39, v39
	v_fmac_f32_e32 v67, v36, v36
	v_fmac_f32_e32 v65, v38, v38
	v_add_f32_e32 v66, v67, v66
	v_add_f32_e32 v65, v65, v66
	v_add_f32_e32 v66, v64, v65
	v_mov_b32_e32 v67, v66
	s_nop 1
	v_permlane16_swap_b32_e32 v67, v66
	v_cvt_pk_bf16_f32 v64, v32, v33
	v_cvt_pk_bf16_f32 v65, v34, v35
	v_lshl_add_u64 v[34:35], v[92:93], 1, s[24:25]
	s_waitcnt lgkmcnt(0)
	v_add_f32_e32 v32, v66, v67
	v_mov_b32_e32 v33, v32
	s_nop 1
	v_permlane32_swap_b32_e32 v33, v32
	v_cvt_pk_bf16_f32 v66, v36, v37
	v_cvt_pk_bf16_f32 v67, v38, v39
	s_nop 0
	s_and_saveexec_b64 s[42:43], s[8:9]
	s_cbranch_execz .LBB0_1785
	v_lshl_add_u64 v[34:35], v[104:105], 2, s[14:15]
	s_waitcnt lgkmcnt(0)
	v_add_f32_e32 v32, v32, v33
	global_atomic_add_f32 v[34:35], v32, off

; #define EPI_PACK8(v0, v1) (u32x4){pk2((v0)[0], (v0)[1]), pk2((v0)[2], (v0)[3]), pk2((v1)[0], (v1)[1]), pk2((v1)[2], (v1)[3])}
;     __device__ __forceinline__ void operator()(AccRef acc, const Unit& u, int wr, int wc, int fr, int fq) const {
;     ...
;             const f32x4 x0 = xc0 + g0 * (p0 * rp) * pg[bj][0], x1 = xc1 + g1 * (p1 * rp) * pg[bj][1];
;             if (xo) { __builtin_nontemporal_store(x0, (f32x4*)(xo + p)); __builtin_nontemporal_store(x1, (f32x4*)(xo + p + 4)); }
;             *(u32x4*)(xb + p) = EPI_PACK8(x0, x1);
;             q += EPI_SQ8(x0, x1);
;             if (bj == 1) { q += __shfl_xor(q, 16); q += __shfl_xor(q, 32); if (fq == 0) atomicAdd(ssout + row, q); q = 0.f; sc = sn_; qc = qn; }
.LBB0_1789:
	v_mul_f32_e32 v32, v53, v53
	v_mul_f32_e32 v33, v55, v55
	v_fmac_f32_e32 v32, v52, v52
	v_fmac_f32_e32 v33, v54, v54
	v_add_f32_e32 v32, v32, v33
	v_mul_f32_e32 v33, v65, v65
	v_fmac_f32_e32 v33, v64, v64
	v_mul_f32_e32 v34, v17, v17
	v_mul_f32_e32 v35, v19, v19
	v_add_f32_e32 v32, v33, v32
	v_mul_f32_e32 v33, v67, v67
	v_fmac_f32_e32 v34, v16, v16
	v_fmac_f32_e32 v35, v18, v18
	v_fmac_f32_e32 v33, v66, v66
	v_add_f32_e32 v34, v34, v35
	v_mul_f32_e32 v35, v21, v21
	v_add_f32_e32 v32, v33, v32
	v_mul_f32_e32 v33, v23, v23
	v_fmac_f32_e32 v35, v20, v20
	v_fmac_f32_e32 v33, v22, v22
	v_add_f32_e32 v34, v35, v34
	v_add_f32_e32 v33, v33, v34
	v_add_f32_e32 v34, v32, v33
	v_mov_b32_e32 v35, v34
	s_nop 1
	v_permlane16_swap_b32_e32 v35, v34
	v_cvt_pk_bf16_f32 v32, v16, v17
	v_cvt_pk_bf16_f32 v33, v18, v19
	v_lshl_add_u64 v[18:19], v[76:77], 1, s[24:25]
	s_waitcnt lgkmcnt(0)
	v_add_f32_e32 v16, v34, v35
	v_mov_b32_e32 v17, v16
	s_nop 1
	v_permlane32_swap_b32_e32 v17, v16
	v_cvt_pk_bf16_f32 v34, v20, v21
	v_cvt_pk_bf16_f32 v35, v22, v23
	s_nop 0
	s_and_saveexec_b64 s[42:43], s[8:9]
	s_cbranch_execz .LBB0_1791
	v_lshl_add_u64 v[18:19], v[88:89], 2, s[14:15]
	s_waitcnt lgkmcnt(0)
	v_add_f32_e32 v16, v16, v17
	global_atomic_add_f32 v[18:19], v16, off

; #define EPI_PACK8(v0, v1) (u32x4){pk2((v0)[0], (v0)[1]), pk2((v0)[2], (v0)[3]), pk2((v1)[0], (v1)[1]), pk2((v1)[2], (v1)[3])}
;     __device__ __forceinline__ void operator()(AccRef acc, const Unit& u, int wr, int wc, int fr, int fq) const {
;     ...
;             const f32x4 x0 = xc0 + g0 * (p0 * rp) * pg[bj][0], x1 = xc1 + g1 * (p1 * rp) * pg[bj][1];
;             if (xo) { __builtin_nontemporal_store(x0, (f32x4*)(xo + p)); __builtin_nontemporal_store(x1, (f32x4*)(xo + p + 4)); }
;             *(u32x4*)(xb + p) = EPI_PACK8(x0, x1);
;             q += EPI_SQ8(x0, x1);
;             if (bj == 1) { q += __shfl_xor(q, 16); q += __shfl_xor(q, 32); if (fq == 0) atomicAdd(ssout + row, q); q = 0.f; sc = sn_; qc = qn; }
.LBB0_1795:
	v_mul_f32_e32 v9, v9, v9
	v_fmac_f32_e32 v9, v8, v8
	v_mul_f32_e32 v8, v11, v11
	v_fmac_f32_e32 v8, v10, v10
	v_add_f32_e32 v8, v9, v8
	v_mul_f32_e32 v9, v13, v13
	v_fmac_f32_e32 v9, v12, v12
	v_mul_f32_e32 v10, v1, v1
	v_mul_f32_e32 v11, v3, v3
	v_add_f32_e32 v8, v9, v8
	v_mul_f32_e32 v9, v15, v15
	v_fmac_f32_e32 v10, v0, v0
	v_fmac_f32_e32 v11, v2, v2
	v_fmac_f32_e32 v9, v14, v14
	v_add_f32_e32 v10, v10, v11
	v_mul_f32_e32 v11, v5, v5
	v_add_f32_e32 v8, v9, v8
	v_mul_f32_e32 v9, v7, v7
	v_fmac_f32_e32 v11, v4, v4
	v_fmac_f32_e32 v9, v6, v6
	v_add_f32_e32 v10, v11, v10
	v_add_f32_e32 v9, v9, v10
	v_add_f32_e32 v10, v8, v9
	v_mov_b32_e32 v11, v10
	s_nop 1
	v_permlane16_swap_b32_e32 v11, v10
	v_cvt_pk_bf16_f32 v8, v0, v1
	v_cvt_pk_bf16_f32 v9, v2, v3
	v_lshl_add_u64 v[2:3], v[36:37], 1, s[24:25]
	s_waitcnt lgkmcnt(0)
	v_add_f32_e32 v0, v10, v11
	v_mov_b32_e32 v1, v0
	s_nop 1
	v_permlane32_swap_b32_e32 v1, v0
	v_cvt_pk_bf16_f32 v10, v4, v5
	v_cvt_pk_bf16_f32 v11, v6, v7
	s_nop 0
	s_and_saveexec_b64 s[6:7], s[8:9]
	s_cbranch_execz .LBB0_1797
	v_lshl_add_u64 v[2:3], v[72:73], 2, s[14:15]
	s_waitcnt lgkmcnt(0)
	v_add_f32_e32 v0, v0, v1
	global_atomic_add_f32 v[2:3], v0, off
